# GEMM K-loops: the 48 compiler-emitted lgkmcnt(0) waits that directly duplicate the preceding asm lgkmcnt(0) deleted (on top of no-setprio v12)
# speedup vs baseline: 1.0032x; 1.0032x over previous
; #define PG8_STAGE(bufoff, gbase, voff) do { _Pragma("unroll") for (int _i = 0; _i < 2; ++_i) \
;     __builtin_amdgcn_global_load_lds((const unsigned*)((const char*)(gbase) + (voff)[_i]), (LAS unsigned*)(lds + (bufoff) + ldsw + _i * 8192), 16, 0, 0); } while (0)
; #define PG8_LDA(dst, b, h) do { _Pragma("unroll") for (int m = 0; m < 4; ++m) _Pragma("unroll") for (int k = 0; k < 2; ++k) dst[m][k] = *(const LAS bf16x8*)(lds + PG8_SA(b, h) + aoff + m * 2048 + k * 1024); } while (0)
; #define PG8_LDB(dst, b, h) do { _Pragma("unroll") for (int n = 0; n < 2; ++n) _Pragma("unroll") for (int k = 0; k < 2; ++k) dst[n][k] = *(const LAS bf16x8*)(lds + PG8_SB(b, h) + boff + n * 2048 + k * 1024); } while (0)
; #define PG8_MMA(ai, bj, At, Bt) do { __builtin_amdgcn_s_setprio(1); _Pragma("unroll") for (int m = 0; m < 4; ++m) _Pragma("unroll") for (int n = 0; n < 2; ++n) _Pragma("unroll") for (int k = 0; k < 2; ++k) \
;     acc[ai][bj][m][n] = __builtin_amdgcn_mfma_f32_16x16x32_bf16(Bt[n][k], At[m][k], acc[ai][bj][m][n], 0, 0, 0); __builtin_amdgcn_s_setprio(0); } while (0)
; #define PG8_WAIT_L(n) asm volatile("s_waitcnt lgkmcnt(" #n ")" ::: "memory")
; #define PG8_BAR __builtin_amdgcn_s_barrier()
; #define PG8_SCHED __builtin_amdgcn_sched_barrier(0)
; template <class Epi>
; DI void gemm_phase(LAS unsigned char* lds, const Gemm g, const StaticOrder& S, const Epi& E) {
;     ...
;     for (int t = 0; t < nt; t += 2) {
;       const bool last = (t == nt - 2);
;       const char* a1 = cA + PG8_AK(t + 1);
;       const char* a2 = last ? nA : cA + PG8_AK(t + 2); const char* b2 = last ? nB : cB + (size_t)(t + 2) * kstep;
;       const char* a3 = a2 + kstep; const char* b3 = b2 + kstep;
;       PG8_LDB(B0, 0, 0); PG8_SCHED; PG8_LDA(At, 0, 0); PG8_STAGE(PG8_SA(1, 1), a1 + hstepA, voffA);
;       PG8_WAIT_L(8); PG8_BAR; PG8_WAIT_L(0); PG8_MMA(0, 0, At, B0); PG8_BAR; PG8_SCHED;
;       PG8_LDB(B1, 0, 1); PG8_STAGE(PG8_SB(0, 0), b2, voffB);
;       PG8_BAR; PG8_WAIT_L(0); PG8_MMA(0, 1, At, B1); PG8_BAR;
;       PG8_LDA(At, 0, 1); PG8_STAGE(PG8_SA(0, 0), a2, voffA);
;       PG8_BAR; PG8_WAIT_L(0); PG8_MMA(1, 0, At, B0); PG8_BAR; PG8_SCHED;
.LBB0_184:
	ds_read_b128 v[150:153], v166
	ds_read_b128 v[154:157], v166 offset:1024
	ds_read_b128 v[158:161], v166 offset:2048
	ds_read_b128 v[170:173], v166 offset:3072
	s_add_u32 s30, s6, 0xfff80080
	s_addc_u32 s31, s7, -1
	s_cmp_eq_u32 s39, 28
	s_cselect_b32 s35, s5, s31
	s_cselect_b32 s34, s8, s30
	s_cselect_b32 s31, s23, s38
	s_cselect_b32 s30, s25, s37
	v_lshl_add_u64 v[162:163], s[6:7], 0, v[142:143]
	s_add_i32 m0, s45, 0xc000
	ds_read_b128 v[174:177], v167
	ds_read_b128 v[178:181], v167 offset:1024
	ds_read_b128 v[182:185], v167 offset:2048
	ds_read_b128 v[186:189], v167 offset:3072
	ds_read_b128 v[190:193], v167 offset:4096
	ds_read_b128 v[194:197], v167 offset:5120
	ds_read_b128 v[198:201], v167 offset:6144
	ds_read_b128 v[202:205], v167 offset:7168
	global_load_lds_dwordx4 v[162:163], off
	v_lshl_add_u64 v[162:163], s[6:7], 0, v[144:145]
	s_add_i32 m0, s45, 0xe000
	s_nop 0
	global_load_lds_dwordx4 v[162:163], off
	s_waitcnt lgkmcnt(8)
	s_barrier
	s_waitcnt lgkmcnt(0)
	v_mfma_f32_16x16x32_bf16 v[126:129], v[150:153], v[174:177], v[126:129]
	v_mfma_f32_16x16x32_bf16 v[122:125], v[158:161], v[174:177], v[122:125]
	v_mfma_f32_16x16x32_bf16 v[110:113], v[150:153], v[182:185], v[110:113]
	v_mfma_f32_16x16x32_bf16 v[106:109], v[158:161], v[182:185], v[106:109]
	v_mfma_f32_16x16x32_bf16 v[94:97], v[150:153], v[190:193], v[94:97]
	v_mfma_f32_16x16x32_bf16 v[90:93], v[158:161], v[190:193], v[90:93]
	v_mfma_f32_16x16x32_bf16 v[78:81], v[150:153], v[198:201], v[78:81]
	v_mfma_f32_16x16x32_bf16 v[74:77], v[158:161], v[198:201], v[74:77]
	v_mfma_f32_16x16x32_bf16 v[126:129], v[154:157], v[178:181], v[126:129]
	v_mfma_f32_16x16x32_bf16 v[122:125], v[170:173], v[178:181], v[122:125]
	v_mfma_f32_16x16x32_bf16 v[110:113], v[154:157], v[186:189], v[110:113]
	v_mfma_f32_16x16x32_bf16 v[106:109], v[170:173], v[186:189], v[106:109]
	v_mfma_f32_16x16x32_bf16 v[94:97], v[154:157], v[194:197], v[94:97]
	v_mfma_f32_16x16x32_bf16 v[90:93], v[170:173], v[194:197], v[90:93]
	v_mfma_f32_16x16x32_bf16 v[78:81], v[154:157], v[202:205], v[78:81]
	v_mfma_f32_16x16x32_bf16 v[74:77], v[170:173], v[202:205], v[74:77]
	s_barrier
	s_add_i32 s40, s55, s44
	v_lshl_add_u64 v[162:163], s[30:31], 0, v[132:133]
	s_mov_b32 m0, s40
	ds_read_b128 v[206:209], v168
	ds_read_b128 v[210:213], v168 offset:1024
	ds_read_b128 v[214:217], v168 offset:2048
	ds_read_b128 v[218:221], v168 offset:3072
	global_load_lds_dwordx4 v[162:163], off
	v_lshl_add_u64 v[222:223], s[30:31], 0, v[136:137]
	s_add_i32 m0, s40, 0x2000
	s_nop 0
	global_load_lds_dwordx4 v[222:223], off
	s_barrier
	s_waitcnt lgkmcnt(0)
	v_mfma_f32_16x16x32_bf16 v[118:121], v[206:209], v[174:177], v[118:121]
	v_mfma_f32_16x16x32_bf16 v[114:117], v[214:217], v[174:177], v[114:117]
	v_mfma_f32_16x16x32_bf16 v[102:105], v[206:209], v[182:185], v[102:105]
	v_mfma_f32_16x16x32_bf16 v[98:101], v[214:217], v[182:185], v[98:101]
	v_mfma_f32_16x16x32_bf16 v[86:89], v[206:209], v[190:193], v[86:89]
	v_mfma_f32_16x16x32_bf16 v[82:85], v[214:217], v[190:193], v[82:85]
	v_mfma_f32_16x16x32_bf16 v[70:73], v[206:209], v[198:201], v[70:73]
	v_mfma_f32_16x16x32_bf16 v[66:69], v[214:217], v[198:201], v[66:69]
	v_mfma_f32_16x16x32_bf16 v[118:121], v[210:213], v[178:181], v[118:121]
	v_mfma_f32_16x16x32_bf16 v[114:117], v[218:221], v[178:181], v[114:117]
	v_mfma_f32_16x16x32_bf16 v[102:105], v[210:213], v[186:189], v[102:105]
	v_mfma_f32_16x16x32_bf16 v[98:101], v[218:221], v[186:189], v[98:101]
	v_mfma_f32_16x16x32_bf16 v[86:89], v[210:213], v[194:197], v[86:89]
	v_mfma_f32_16x16x32_bf16 v[82:85], v[218:221], v[194:197], v[82:85]
	v_mfma_f32_16x16x32_bf16 v[70:73], v[210:213], v[202:205], v[70:73]
	v_mfma_f32_16x16x32_bf16 v[66:69], v[218:221], v[202:205], v[66:69]
	s_mov_b32 m0, s45
	v_lshl_add_u64 v[224:225], s[34:35], 0, v[130:131]
	s_barrier
	ds_read_b128 v[174:177], v167 offset:16384
	ds_read_b128 v[178:181], v167 offset:17408
	ds_read_b128 v[182:185], v167 offset:18432
	ds_read_b128 v[186:189], v167 offset:19456
	ds_read_b128 v[190:193], v167 offset:20480
	ds_read_b128 v[194:197], v167 offset:21504
	ds_read_b128 v[198:201], v167 offset:22528
	ds_read_b128 v[202:205], v167 offset:23552
	global_load_lds_dwordx4 v[224:225], off
	v_lshl_add_u64 v[226:227], s[34:35], 0, v[134:135]
	s_mov_b32 m0, s46
	s_nop 0
	global_load_lds_dwordx4 v[226:227], off
	s_barrier
	s_waitcnt lgkmcnt(0)
	v_mfma_f32_16x16x32_bf16 v[62:65], v[150:153], v[174:177], v[62:65]
	v_mfma_f32_16x16x32_bf16 v[58:61], v[158:161], v[174:177], v[58:61]
	v_mfma_f32_16x16x32_bf16 v[46:49], v[150:153], v[182:185], v[46:49]
	v_mfma_f32_16x16x32_bf16 v[42:45], v[158:161], v[182:185], v[42:45]
	v_mfma_f32_16x16x32_bf16 v[30:33], v[150:153], v[190:193], v[30:33]
	v_mfma_f32_16x16x32_bf16 v[26:29], v[158:161], v[190:193], v[26:29]
	v_mfma_f32_16x16x32_bf16 v[14:17], v[150:153], v[198:201], v[14:17]
	v_mfma_f32_16x16x32_bf16 v[10:13], v[158:161], v[198:201], v[10:13]
	v_mfma_f32_16x16x32_bf16 v[62:65], v[154:157], v[178:181], v[62:65]
	v_mfma_f32_16x16x32_bf16 v[58:61], v[170:173], v[178:181], v[58:61]
	v_mfma_f32_16x16x32_bf16 v[46:49], v[154:157], v[186:189], v[46:49]
	v_mfma_f32_16x16x32_bf16 v[42:45], v[170:173], v[186:189], v[42:45]
	v_mfma_f32_16x16x32_bf16 v[30:33], v[154:157], v[194:197], v[30:33]
	v_mfma_f32_16x16x32_bf16 v[26:29], v[170:173], v[194:197], v[26:29]
	v_mfma_f32_16x16x32_bf16 v[14:17], v[154:157], v[202:205], v[14:17]
	v_mfma_f32_16x16x32_bf16 v[10:13], v[170:173], v[202:205], v[10:13]
	s_barrier
; #define PG8_STAGE(bufoff, gbase, voff) do { _Pragma("unroll") for (int _i = 0; _i < 2; ++_i) \
;     __builtin_amdgcn_global_load_lds((const unsigned*)((const char*)(gbase) + (voff)[_i]), (LAS unsigned*)(lds + (bufoff) + ldsw + _i * 8192), 16, 0, 0); } while (0)
; #define PG8_LDA(dst, b, h) do { _Pragma("unroll") for (int m = 0; m < 4; ++m) _Pragma("unroll") for (int k = 0; k < 2; ++k) dst[m][k] = *(const LAS bf16x8*)(lds + PG8_SA(b, h) + aoff + m * 2048 + k * 1024); } while (0)
; #define PG8_LDB(dst, b, h) do { _Pragma("unroll") for (int n = 0; n < 2; ++n) _Pragma("unroll") for (int k = 0; k < 2; ++k) dst[n][k] = *(const LAS bf16x8*)(lds + PG8_SB(b, h) + boff + n * 2048 + k * 1024); } while (0)
; #define PG8_MMA(ai, bj, At, Bt) do { __builtin_amdgcn_s_setprio(1); _Pragma("unroll") for (int m = 0; m < 4; ++m) _Pragma("unroll") for (int n = 0; n < 2; ++n) _Pragma("unroll") for (int k = 0; k < 2; ++k) \
;     acc[ai][bj][m][n] = __builtin_amdgcn_mfma_f32_16x16x32_bf16(Bt[n][k], At[m][k], acc[ai][bj][m][n], 0, 0, 0); __builtin_amdgcn_s_setprio(0); } while (0)
; #define PG8_WAIT_V(n) asm volatile("s_waitcnt vmcnt(" #n ")" ::: "memory")
; #define PG8_WAIT_L(n) asm volatile("s_waitcnt lgkmcnt(" #n ")" ::: "memory")
; #define PG8_BAR __builtin_amdgcn_s_barrier()
; #define PG8_SCHED __builtin_amdgcn_sched_barrier(0)
; template <class Epi>
; DI void gemm_phase(LAS unsigned char* lds, const Gemm g, const StaticOrder& S, const Epi& E) {
;     ...
;       PG8_STAGE(PG8_SB(0, 1), b2 + hstepB, voffB);
;       PG8_WAIT_V(6); PG8_BAR; PG8_MMA(1, 1, At, B1); PG8_BAR;
;       PG8_LDB(B0, 1, 0); PG8_SCHED; PG8_LDA(At, 1, 0); PG8_STAGE(PG8_SA(0, 1), a2 + hstepA, voffA);
;       PG8_WAIT_L(8); PG8_BAR; PG8_WAIT_L(0); PG8_MMA(0, 0, At, B0); PG8_BAR; PG8_SCHED;
;       PG8_LDB(B1, 1, 1); PG8_STAGE(PG8_SB(1, 0), b3, voffB);
	s_add_u32 s40, s30, 0x80000
	s_addc_u32 s41, s31, 0
	s_add_i32 s59, s56, s44
	v_lshl_add_u64 v[150:151], s[40:41], 0, v[132:133]
	s_mov_b32 m0, s59
	s_nop 0
	global_load_lds_dwordx4 v[150:151], off
	v_lshl_add_u64 v[150:151], s[40:41], 0, v[136:137]
	s_add_i32 m0, s59, 0x2000
	s_nop 0
	global_load_lds_dwordx4 v[150:151], off
	s_waitcnt vmcnt(6)
	s_barrier
	v_mfma_f32_16x16x32_bf16 v[54:57], v[206:209], v[174:177], v[54:57]
	v_mfma_f32_16x16x32_bf16 v[50:53], v[214:217], v[174:177], v[50:53]
	v_mfma_f32_16x16x32_bf16 v[38:41], v[206:209], v[182:185], v[38:41]
	v_mfma_f32_16x16x32_bf16 v[34:37], v[214:217], v[182:185], v[34:37]
	v_mfma_f32_16x16x32_bf16 v[22:25], v[206:209], v[190:193], v[22:25]
	v_mfma_f32_16x16x32_bf16 v[18:21], v[214:217], v[190:193], v[18:21]
	v_mfma_f32_16x16x32_bf16 v[6:9], v[206:209], v[198:201], v[6:9]
	v_mfma_f32_16x16x32_bf16 v[2:5], v[214:217], v[198:201], v[2:5]
	v_mfma_f32_16x16x32_bf16 v[54:57], v[210:213], v[178:181], v[54:57]
	v_mfma_f32_16x16x32_bf16 v[50:53], v[218:221], v[178:181], v[50:53]
	v_mfma_f32_16x16x32_bf16 v[38:41], v[210:213], v[186:189], v[38:41]
	v_mfma_f32_16x16x32_bf16 v[34:37], v[218:221], v[186:189], v[34:37]
	v_mfma_f32_16x16x32_bf16 v[22:25], v[210:213], v[194:197], v[22:25]
	v_mfma_f32_16x16x32_bf16 v[18:21], v[218:221], v[194:197], v[18:21]
	v_mfma_f32_16x16x32_bf16 v[6:9], v[210:213], v[202:205], v[6:9]
	v_mfma_f32_16x16x32_bf16 v[2:5], v[218:221], v[202:205], v[2:5]
	s_add_i32 s40, 0, 0x18000
	v_add_u32_e32 v138, s40, v165
	s_barrier
	ds_read_b128 v[150:153], v138
	ds_read_b128 v[154:157], v138 offset:1024
	ds_read_b128 v[158:161], v138 offset:2048
	ds_read_b128 v[170:173], v138 offset:3072
	s_add_u32 s34, s34, 0x80000
	s_addc_u32 s35, s35, 0
	s_mov_b32 m0, s47
	v_lshl_add_u64 v[206:207], s[34:35], 0, v[130:131]
	ds_read_b128 v[174:177], v167 offset:32768
	ds_read_b128 v[178:181], v167 offset:33792
	ds_read_b128 v[182:185], v167 offset:34816
	ds_read_b128 v[186:189], v167 offset:35840
	ds_read_b128 v[190:193], v167 offset:36864
	ds_read_b128 v[194:197], v167 offset:37888
	ds_read_b128 v[198:201], v167 offset:38912
	ds_read_b128 v[202:205], v167 offset:39936
	global_load_lds_dwordx4 v[206:207], off
	v_lshl_add_u64 v[206:207], s[34:35], 0, v[134:135]
	s_mov_b32 m0, s48
	s_nop 0
	global_load_lds_dwordx4 v[206:207], off
	s_waitcnt lgkmcnt(8)
	s_barrier
	s_waitcnt lgkmcnt(0)
	v_mfma_f32_16x16x32_bf16 v[126:129], v[150:153], v[174:177], v[126:129]
	v_mfma_f32_16x16x32_bf16 v[122:125], v[158:161], v[174:177], v[122:125]
	v_mfma_f32_16x16x32_bf16 v[110:113], v[150:153], v[182:185], v[110:113]
	v_mfma_f32_16x16x32_bf16 v[106:109], v[158:161], v[182:185], v[106:109]
	v_mfma_f32_16x16x32_bf16 v[94:97], v[150:153], v[190:193], v[94:97]
	v_mfma_f32_16x16x32_bf16 v[90:93], v[158:161], v[190:193], v[90:93]
	v_mfma_f32_16x16x32_bf16 v[78:81], v[150:153], v[198:201], v[78:81]
	v_mfma_f32_16x16x32_bf16 v[74:77], v[158:161], v[198:201], v[74:77]
	v_mfma_f32_16x16x32_bf16 v[126:129], v[154:157], v[178:181], v[126:129]
	v_mfma_f32_16x16x32_bf16 v[122:125], v[170:173], v[178:181], v[122:125]
	v_mfma_f32_16x16x32_bf16 v[110:113], v[154:157], v[186:189], v[110:113]
	v_mfma_f32_16x16x32_bf16 v[106:109], v[170:173], v[186:189], v[106:109]
	v_mfma_f32_16x16x32_bf16 v[94:97], v[154:157], v[194:197], v[94:97]
	v_mfma_f32_16x16x32_bf16 v[90:93], v[170:173], v[194:197], v[90:93]
	v_mfma_f32_16x16x32_bf16 v[78:81], v[154:157], v[202:205], v[78:81]
	v_mfma_f32_16x16x32_bf16 v[74:77], v[170:173], v[202:205], v[74:77]
	s_barrier
	s_add_i32 s34, 0, 0x1c000
	s_add_i32 s35, s40, s44
	v_add_u32_e32 v138, s34, v165
	v_lshl_add_u64 v[162:163], v[162:163], 0, s[10:11]
	s_mov_b32 m0, s35
	ds_read_b128 v[206:209], v138
	ds_read_b128 v[210:213], v138 offset:1024
	ds_read_b128 v[214:217], v138 offset:2048
	ds_read_b128 v[218:221], v138 offset:3072
	global_load_lds_dwordx4 v[162:163], off
	v_lshl_add_u64 v[162:163], v[222:223], 0, s[10:11]
	s_add_i32 m0, s35, 0x2000
	s_nop 0
	global_load_lds_dwordx4 v[162:163], off
	s_barrier
; #define PG8_WAIT_V(n) asm volatile("s_waitcnt vmcnt(" #n ")" ::: "memory")
; #define PG8_WAIT_L(n) asm volatile("s_waitcnt lgkmcnt(" #n ")" ::: "memory")
; template <class Epi>
; DI void gemm_phase(LAS unsigned char* lds, const Gemm g, const StaticOrder& S, const Epi& E) {
;     ...
;       PG8_BAR; PG8_WAIT_L(0); PG8_MMA(0, 1, At, B1); PG8_BAR;
;       PG8_LDA(At, 1, 1); PG8_STAGE(PG8_SA(1, 0), a3, voffA);
;       PG8_BAR; PG8_WAIT_L(0); PG8_MMA(1, 0, At, B0); PG8_BAR; PG8_SCHED;
;       PG8_STAGE(PG8_SB(1, 1), b3 + hstepB, voffB);
;       PG8_WAIT_V(6); PG8_BAR; PG8_MMA(1, 1, At, B1); PG8_BAR;
;     }
;     E(acc, cur, wr, wc, fr, fq);
;   DI void operator()(const f32x4 (&acc)[2][2][4][2], const pg8::Unit& u, int wr, int wc, int fr, int fq) const {
;     ...
;         const int row = u.pm * 256 + ai * 128 + wr * 64 + m * 16 + fr;
;         const int grow = rowbase + row;
;         float rs = 1.f;
;         if (MODE == EP_IN) rs = ((const float*)(ws + OFF_RS0))[grow];
;         if (MODE == EP_UP) rs = ((const float*)(ws + OFF_RS2))[grow];
;         if (MODE == EP_Q || MODE == EP_KV) {
;           const f32x4* sp = (const f32x4*)(ws + OFF_SSQA) + (size_t)grow * 4 + (MODE == EP_KV ? 2 : 0);
;           const f32x4 s0 = sp[0], s1 = sp[1];
;           const float ss = (s0[0] + s0[1]) + (s0[2] + s0[3]) + (s1[0] + s1[1]) + (s1[2] + s1[3]);
;           rs = __builtin_amdgcn_rsqf(ss * (1.0f / 512) + EPS);
;           if (MODE == EP_Q) rs *= QSCALE;
;         }
;         float ssq = 0.f;
; #pragma unroll
;         for (int bj = 0; bj < 2; ++bj) {
;           f32x4 v0 = acc[ai][bj][m][0] * rs, v1 = acc[ai][bj][m][1] * rs;
;           if (MODE == EP_IN || MODE == EP_MIX || MODE == EP_DOWN) {
; #pragma unroll
;             for (int j = 0; j < 4; ++j) ssq += v0[j] * v0[j] + v1[j] * v1[j];
;           }
;           if (MODE == EP_UP) {
; #pragma unroll
;             for (int j = 0; j < 4; ++j) { float a = fmaxf(v0[j], 0.f), b = fmaxf(v1[j], 0.f); v0[j] = a * a; v1[j] = b * b; }
;           }
;           bf16_t* dst;
;           const int ct = bj * 128 + cl;
;           if (MODE == EP_IN) {
;             if (pn < 4) dst = (bf16_t*)(ws + OFF_PROJA) + (size_t)grow * 1024 + pn * 256 + ct;
;             else if (pn < 16) dst = (bf16_t*)(ws + OFF_PROJG) + (size_t)grow * 3072 + (pn - 4) * 256 + ct;
;             else dst = (bf16_t*)(ws + OFF_PROJS) + (size_t)grow * 256 + ct;
	s_waitcnt lgkmcnt(0)
	v_mfma_f32_16x16x32_bf16 v[118:121], v[206:209], v[174:177], v[118:121]
	v_mfma_f32_16x16x32_bf16 v[114:117], v[214:217], v[174:177], v[114:117]
	v_mfma_f32_16x16x32_bf16 v[102:105], v[206:209], v[182:185], v[102:105]
	v_mfma_f32_16x16x32_bf16 v[98:101], v[214:217], v[182:185], v[98:101]
	v_mfma_f32_16x16x32_bf16 v[86:89], v[206:209], v[190:193], v[86:89]
	v_mfma_f32_16x16x32_bf16 v[82:85], v[214:217], v[190:193], v[82:85]
	v_mfma_f32_16x16x32_bf16 v[70:73], v[206:209], v[198:201], v[70:73]
	v_mfma_f32_16x16x32_bf16 v[66:69], v[214:217], v[198:201], v[66:69]
	v_mfma_f32_16x16x32_bf16 v[118:121], v[210:213], v[178:181], v[118:121]
	v_mfma_f32_16x16x32_bf16 v[114:117], v[218:221], v[178:181], v[114:117]
	v_mfma_f32_16x16x32_bf16 v[102:105], v[210:213], v[186:189], v[102:105]
	v_mfma_f32_16x16x32_bf16 v[98:101], v[218:221], v[186:189], v[98:101]
	v_mfma_f32_16x16x32_bf16 v[86:89], v[210:213], v[194:197], v[86:89]
	v_mfma_f32_16x16x32_bf16 v[82:85], v[218:221], v[194:197], v[82:85]
	v_mfma_f32_16x16x32_bf16 v[70:73], v[210:213], v[202:205], v[70:73]
	v_mfma_f32_16x16x32_bf16 v[66:69], v[218:221], v[202:205], v[66:69]
	s_mov_b32 m0, s50
	v_lshl_add_u64 v[162:163], v[224:225], 0, s[10:11]
	s_barrier
	ds_read_b128 v[174:177], v167 offset:49152
	ds_read_b128 v[178:181], v167 offset:50176
	ds_read_b128 v[182:185], v167 offset:51200
	ds_read_b128 v[186:189], v167 offset:52224
	ds_read_b128 v[190:193], v167 offset:53248
	ds_read_b128 v[194:197], v167 offset:54272
	ds_read_b128 v[198:201], v167 offset:55296
	ds_read_b128 v[202:205], v167 offset:56320
	global_load_lds_dwordx4 v[162:163], off
	v_lshl_add_u64 v[162:163], v[226:227], 0, s[10:11]
	s_mov_b32 m0, s51
	s_nop 0
	global_load_lds_dwordx4 v[162:163], off
	s_barrier
	s_waitcnt lgkmcnt(0)
	v_mfma_f32_16x16x32_bf16 v[62:65], v[150:153], v[174:177], v[62:65]
	v_mfma_f32_16x16x32_bf16 v[58:61], v[158:161], v[174:177], v[58:61]
	v_mfma_f32_16x16x32_bf16 v[46:49], v[150:153], v[182:185], v[46:49]
	v_mfma_f32_16x16x32_bf16 v[42:45], v[158:161], v[182:185], v[42:45]
	v_mfma_f32_16x16x32_bf16 v[30:33], v[150:153], v[190:193], v[30:33]
	v_mfma_f32_16x16x32_bf16 v[26:29], v[158:161], v[190:193], v[26:29]
	v_mfma_f32_16x16x32_bf16 v[14:17], v[150:153], v[198:201], v[14:17]
	v_mfma_f32_16x16x32_bf16 v[10:13], v[158:161], v[198:201], v[10:13]
	v_mfma_f32_16x16x32_bf16 v[62:65], v[154:157], v[178:181], v[62:65]
	v_mfma_f32_16x16x32_bf16 v[58:61], v[170:173], v[178:181], v[58:61]
	v_mfma_f32_16x16x32_bf16 v[46:49], v[154:157], v[186:189], v[46:49]
	v_mfma_f32_16x16x32_bf16 v[42:45], v[170:173], v[186:189], v[42:45]
	v_mfma_f32_16x16x32_bf16 v[30:33], v[154:157], v[194:197], v[30:33]
	v_mfma_f32_16x16x32_bf16 v[26:29], v[170:173], v[194:197], v[26:29]
	v_mfma_f32_16x16x32_bf16 v[14:17], v[154:157], v[202:205], v[14:17]
	v_mfma_f32_16x16x32_bf16 v[10:13], v[170:173], v[202:205], v[10:13]
	s_barrier
	s_add_u32 s30, s30, 0x80080
	s_addc_u32 s31, s31, 0
	s_add_i32 s34, s34, s44
	v_lshl_add_u64 v[150:151], s[30:31], 0, v[132:133]
	s_mov_b32 m0, s34
	s_nop 0
	global_load_lds_dwordx4 v[150:151], off
	v_lshl_add_u64 v[150:151], s[30:31], 0, v[136:137]
	s_add_i32 m0, s34, 0x2000
	s_nop 0
	global_load_lds_dwordx4 v[150:151], off
	s_waitcnt vmcnt(6)
	s_barrier
	v_mfma_f32_16x16x32_bf16 v[54:57], v[206:209], v[174:177], v[54:57]
	v_mfma_f32_16x16x32_bf16 v[50:53], v[214:217], v[174:177], v[50:53]
	v_mfma_f32_16x16x32_bf16 v[38:41], v[206:209], v[182:185], v[38:41]
	v_mfma_f32_16x16x32_bf16 v[34:37], v[214:217], v[182:185], v[34:37]
	v_mfma_f32_16x16x32_bf16 v[22:25], v[206:209], v[190:193], v[22:25]
	v_mfma_f32_16x16x32_bf16 v[18:21], v[214:217], v[190:193], v[18:21]
	v_mfma_f32_16x16x32_bf16 v[6:9], v[206:209], v[198:201], v[6:9]
	v_mfma_f32_16x16x32_bf16 v[2:5], v[214:217], v[198:201], v[2:5]
	v_mfma_f32_16x16x32_bf16 v[54:57], v[210:213], v[178:181], v[54:57]
	v_mfma_f32_16x16x32_bf16 v[50:53], v[218:221], v[178:181], v[50:53]
	v_mfma_f32_16x16x32_bf16 v[38:41], v[210:213], v[186:189], v[38:41]
	v_mfma_f32_16x16x32_bf16 v[34:37], v[218:221], v[186:189], v[34:37]
	v_mfma_f32_16x16x32_bf16 v[22:25], v[210:213], v[194:197], v[22:25]
	v_mfma_f32_16x16x32_bf16 v[18:21], v[218:221], v[194:197], v[18:21]
	v_mfma_f32_16x16x32_bf16 v[6:9], v[210:213], v[202:205], v[6:9]
	v_mfma_f32_16x16x32_bf16 v[2:5], v[218:221], v[202:205], v[2:5]
	s_add_i32 s39, s39, 2
	s_add_u32 s6, s6, 0x100
	s_addc_u32 s7, s7, 0
	s_add_u32 s37, s37, 0x100
	s_addc_u32 s38, s38, 0
	s_cmp_gt_u32 s39, 29
	s_barrier
	s_cbranch_scc0 .LBB0_184
	v_lshl_add_u32 v150, s4, 8, v164
	v_ashrrev_i32_e32 v151, 31, v150
	v_lshl_add_u64 v[152:153], v[150:151], 2, s[12:13]
	s_nop 0
	s_cmp_lt_i32 s36, 4
	s_cselect_b64 s[34:35], -1, 0
	s_cmp_gt_i32 s36, 3
	s_cselect_b64 s[4:5], -1, 0
	s_cmp_gt_u32 s36, 15
	s_cselect_b64 s[38:39], -1, 0
	s_lshl_b32 s30, s36, 8
	v_mad_i64_i32 v[154:155], s[6:7], v150, s57, 0
	s_mov_b32 s8, s30
	v_lshlrev_b64 v[156:157], 9, v[150:151]
	s_mov_b64 s[6:7], -1
	s_and_b64 vcc, exec, s[4:5]
	s_cbranch_vccz .LBB0_191
	s_and_b64 vcc, exec, s[38:39]
	s_cbranch_vccz .LBB0_188
	v_lshl_add_u64 v[162:163], s[14:15], 0, v[156:157]
	s_mov_b64 s[6:7], 0

; #define PG8_STAGE(bufoff, gbase, voff) do { _Pragma("unroll") for (int _i = 0; _i < 2; ++_i) \
;     __builtin_amdgcn_global_load_lds((const unsigned*)((const char*)(gbase) + (voff)[_i]), (LAS unsigned*)(lds + (bufoff) + ldsw + _i * 8192), 16, 0, 0); } while (0)
; #define PG8_LDA(dst, b, h) do { _Pragma("unroll") for (int m = 0; m < 4; ++m) _Pragma("unroll") for (int k = 0; k < 2; ++k) dst[m][k] = *(const LAS bf16x8*)(lds + PG8_SA(b, h) + aoff + m * 2048 + k * 1024); } while (0)
; #define PG8_LDB(dst, b, h) do { _Pragma("unroll") for (int n = 0; n < 2; ++n) _Pragma("unroll") for (int k = 0; k < 2; ++k) dst[n][k] = *(const LAS bf16x8*)(lds + PG8_SB(b, h) + boff + n * 2048 + k * 1024); } while (0)
; #define PG8_MMA(ai, bj, At, Bt) do { __builtin_amdgcn_s_setprio(1); _Pragma("unroll") for (int m = 0; m < 4; ++m) _Pragma("unroll") for (int n = 0; n < 2; ++n) _Pragma("unroll") for (int k = 0; k < 2; ++k) \
;     acc[ai][bj][m][n] = __builtin_amdgcn_mfma_f32_16x16x32_bf16(Bt[n][k], At[m][k], acc[ai][bj][m][n], 0, 0, 0); __builtin_amdgcn_s_setprio(0); } while (0)
; #define PG8_WAIT_L(n) asm volatile("s_waitcnt lgkmcnt(" #n ")" ::: "memory")
; #define PG8_BAR __builtin_amdgcn_s_barrier()
; #define PG8_SCHED __builtin_amdgcn_sched_barrier(0)
; template <class Epi>
; DI void gemm_phase(LAS unsigned char* lds, const Gemm g, const StaticOrder& S, const Epi& E) {
;     ...
;     for (int t = 0; t < nt; t += 2) {
;       const bool last = (t == nt - 2);
;       const char* a1 = cA + PG8_AK(t + 1);
;       const char* a2 = last ? nA : cA + PG8_AK(t + 2); const char* b2 = last ? nB : cB + (size_t)(t + 2) * kstep;
;       const char* a3 = a2 + kstep; const char* b3 = b2 + kstep;
;       PG8_LDB(B0, 0, 0); PG8_SCHED; PG8_LDA(At, 0, 0); PG8_STAGE(PG8_SA(1, 1), a1 + hstepA, voffA);
;       PG8_WAIT_L(8); PG8_BAR; PG8_WAIT_L(0); PG8_MMA(0, 0, At, B0); PG8_BAR; PG8_SCHED;
;       PG8_LDB(B1, 0, 1); PG8_STAGE(PG8_SB(0, 0), b2, voffB);
;       PG8_BAR; PG8_WAIT_L(0); PG8_MMA(0, 1, At, B1); PG8_BAR;
;       PG8_LDA(At, 0, 1); PG8_STAGE(PG8_SA(0, 0), a2, voffA);
;       PG8_BAR; PG8_WAIT_L(0); PG8_MMA(1, 0, At, B0); PG8_BAR; PG8_SCHED;
.LBB0_484:
	ds_read_b128 v[154:157], v174
	ds_read_b128 v[158:161], v174 offset:1024
	ds_read_b128 v[162:165], v174 offset:2048
	ds_read_b128 v[178:181], v174 offset:3072
	s_add_u32 s28, s26, 0xfffc0080
	s_addc_u32 s29, s27, -1
	s_cmp_eq_u32 s53, 4
	s_cselect_b32 s31, s3, s29
	s_cselect_b32 s30, s5, s28
	s_cselect_b32 s29, s6, s33
	s_cselect_b32 s28, s19, s21
	v_lshl_add_u64 v[214:215], s[26:27], 0, v[146:147]
	s_add_i32 m0, s40, 0xc000
	ds_read_b128 v[182:185], v175
	ds_read_b128 v[186:189], v175 offset:1024
	ds_read_b128 v[190:193], v175 offset:2048
	ds_read_b128 v[194:197], v175 offset:3072
	ds_read_b128 v[198:201], v175 offset:4096
	ds_read_b128 v[202:205], v175 offset:5120
	ds_read_b128 v[206:209], v175 offset:6144
	ds_read_b128 v[210:213], v175 offset:7168
	global_load_lds_dwordx4 v[214:215], off
	v_lshl_add_u64 v[214:215], s[26:27], 0, v[148:149]
	s_add_i32 m0, s40, 0xe000
	s_nop 0
	global_load_lds_dwordx4 v[214:215], off
	s_waitcnt lgkmcnt(8)
	s_barrier
	s_waitcnt lgkmcnt(0)
	v_mfma_f32_16x16x32_bf16 v[126:129], v[154:157], v[182:185], v[126:129]
	v_mfma_f32_16x16x32_bf16 v[122:125], v[162:165], v[182:185], v[122:125]
	v_mfma_f32_16x16x32_bf16 v[110:113], v[154:157], v[190:193], v[110:113]
	v_mfma_f32_16x16x32_bf16 v[106:109], v[162:165], v[190:193], v[106:109]
	v_mfma_f32_16x16x32_bf16 v[94:97], v[154:157], v[198:201], v[94:97]
	v_mfma_f32_16x16x32_bf16 v[90:93], v[162:165], v[198:201], v[90:93]
	v_mfma_f32_16x16x32_bf16 v[78:81], v[154:157], v[206:209], v[78:81]
	v_mfma_f32_16x16x32_bf16 v[74:77], v[162:165], v[206:209], v[74:77]
	v_mfma_f32_16x16x32_bf16 v[126:129], v[158:161], v[186:189], v[126:129]
	v_mfma_f32_16x16x32_bf16 v[122:125], v[178:181], v[186:189], v[122:125]
	v_mfma_f32_16x16x32_bf16 v[110:113], v[158:161], v[194:197], v[110:113]
	v_mfma_f32_16x16x32_bf16 v[106:109], v[178:181], v[194:197], v[106:109]
	v_mfma_f32_16x16x32_bf16 v[94:97], v[158:161], v[202:205], v[94:97]
	v_mfma_f32_16x16x32_bf16 v[90:93], v[178:181], v[202:205], v[90:93]
	v_mfma_f32_16x16x32_bf16 v[78:81], v[158:161], v[210:213], v[78:81]
	v_mfma_f32_16x16x32_bf16 v[74:77], v[178:181], v[210:213], v[74:77]
	s_barrier
	s_add_i32 s59, s51, s39
	v_lshl_add_u64 v[230:231], s[28:29], 0, v[132:133]
	s_mov_b32 m0, s59
	ds_read_b128 v[214:217], v176
	ds_read_b128 v[218:221], v176 offset:1024
	ds_read_b128 v[222:225], v176 offset:2048
	ds_read_b128 v[226:229], v176 offset:3072
	global_load_lds_dwordx4 v[230:231], off
	v_lshl_add_u64 v[232:233], s[28:29], 0, v[136:137]
	s_add_i32 m0, s59, 0x2000
	s_nop 0
	global_load_lds_dwordx4 v[232:233], off
	s_barrier
	s_waitcnt lgkmcnt(0)
	v_mfma_f32_16x16x32_bf16 v[118:121], v[214:217], v[182:185], v[118:121]
	v_mfma_f32_16x16x32_bf16 v[114:117], v[222:225], v[182:185], v[114:117]
	v_mfma_f32_16x16x32_bf16 v[102:105], v[214:217], v[190:193], v[102:105]
	v_mfma_f32_16x16x32_bf16 v[98:101], v[222:225], v[190:193], v[98:101]
	v_mfma_f32_16x16x32_bf16 v[86:89], v[214:217], v[198:201], v[86:89]
	v_mfma_f32_16x16x32_bf16 v[82:85], v[222:225], v[198:201], v[82:85]
	v_mfma_f32_16x16x32_bf16 v[70:73], v[214:217], v[206:209], v[70:73]
	v_mfma_f32_16x16x32_bf16 v[66:69], v[222:225], v[206:209], v[66:69]
	v_mfma_f32_16x16x32_bf16 v[118:121], v[218:221], v[186:189], v[118:121]
	v_mfma_f32_16x16x32_bf16 v[114:117], v[226:229], v[186:189], v[114:117]
	v_mfma_f32_16x16x32_bf16 v[102:105], v[218:221], v[194:197], v[102:105]
	v_mfma_f32_16x16x32_bf16 v[98:101], v[226:229], v[194:197], v[98:101]
	v_mfma_f32_16x16x32_bf16 v[86:89], v[218:221], v[202:205], v[86:89]
	v_mfma_f32_16x16x32_bf16 v[82:85], v[226:229], v[202:205], v[82:85]
	v_mfma_f32_16x16x32_bf16 v[70:73], v[218:221], v[210:213], v[70:73]
	v_mfma_f32_16x16x32_bf16 v[66:69], v[226:229], v[210:213], v[66:69]
	s_mov_b32 m0, s40
	v_lshl_add_u64 v[234:235], s[30:31], 0, v[130:131]
	s_barrier
	ds_read_b128 v[182:185], v175 offset:16384
	ds_read_b128 v[186:189], v175 offset:17408
	ds_read_b128 v[190:193], v175 offset:18432
	ds_read_b128 v[194:197], v175 offset:19456
	ds_read_b128 v[198:201], v175 offset:20480
	ds_read_b128 v[202:205], v175 offset:21504
	ds_read_b128 v[206:209], v175 offset:22528
	ds_read_b128 v[210:213], v175 offset:23552
	global_load_lds_dwordx4 v[234:235], off
	v_lshl_add_u64 v[236:237], s[30:31], 0, v[134:135]
	s_mov_b32 m0, s41
	s_nop 0
	global_load_lds_dwordx4 v[236:237], off
	s_barrier
	s_waitcnt lgkmcnt(0)
	v_mfma_f32_16x16x32_bf16 v[62:65], v[154:157], v[182:185], v[62:65]
	v_mfma_f32_16x16x32_bf16 v[58:61], v[162:165], v[182:185], v[58:61]
	v_mfma_f32_16x16x32_bf16 v[46:49], v[154:157], v[190:193], v[46:49]
	v_mfma_f32_16x16x32_bf16 v[42:45], v[162:165], v[190:193], v[42:45]
	v_mfma_f32_16x16x32_bf16 v[30:33], v[154:157], v[198:201], v[30:33]
	v_mfma_f32_16x16x32_bf16 v[26:29], v[162:165], v[198:201], v[26:29]
	v_mfma_f32_16x16x32_bf16 v[14:17], v[154:157], v[206:209], v[14:17]
	v_mfma_f32_16x16x32_bf16 v[10:13], v[162:165], v[206:209], v[10:13]
	v_mfma_f32_16x16x32_bf16 v[62:65], v[158:161], v[186:189], v[62:65]
	v_mfma_f32_16x16x32_bf16 v[58:61], v[178:181], v[186:189], v[58:61]
	v_mfma_f32_16x16x32_bf16 v[46:49], v[158:161], v[194:197], v[46:49]
	v_mfma_f32_16x16x32_bf16 v[42:45], v[178:181], v[194:197], v[42:45]
	v_mfma_f32_16x16x32_bf16 v[30:33], v[158:161], v[202:205], v[30:33]
	v_mfma_f32_16x16x32_bf16 v[26:29], v[178:181], v[202:205], v[26:29]
	v_mfma_f32_16x16x32_bf16 v[14:17], v[158:161], v[210:213], v[14:17]
	v_mfma_f32_16x16x32_bf16 v[10:13], v[178:181], v[210:213], v[10:13]
	s_barrier
; #define PG8_STAGE(bufoff, gbase, voff) do { _Pragma("unroll") for (int _i = 0; _i < 2; ++_i) \
;     __builtin_amdgcn_global_load_lds((const unsigned*)((const char*)(gbase) + (voff)[_i]), (LAS unsigned*)(lds + (bufoff) + ldsw + _i * 8192), 16, 0, 0); } while (0)
; #define PG8_LDA(dst, b, h) do { _Pragma("unroll") for (int m = 0; m < 4; ++m) _Pragma("unroll") for (int k = 0; k < 2; ++k) dst[m][k] = *(const LAS bf16x8*)(lds + PG8_SA(b, h) + aoff + m * 2048 + k * 1024); } while (0)
; #define PG8_LDB(dst, b, h) do { _Pragma("unroll") for (int n = 0; n < 2; ++n) _Pragma("unroll") for (int k = 0; k < 2; ++k) dst[n][k] = *(const LAS bf16x8*)(lds + PG8_SB(b, h) + boff + n * 2048 + k * 1024); } while (0)
; #define PG8_MMA(ai, bj, At, Bt) do { __builtin_amdgcn_s_setprio(1); _Pragma("unroll") for (int m = 0; m < 4; ++m) _Pragma("unroll") for (int n = 0; n < 2; ++n) _Pragma("unroll") for (int k = 0; k < 2; ++k) \
;     acc[ai][bj][m][n] = __builtin_amdgcn_mfma_f32_16x16x32_bf16(Bt[n][k], At[m][k], acc[ai][bj][m][n], 0, 0, 0); __builtin_amdgcn_s_setprio(0); } while (0)
; #define PG8_WAIT_V(n) asm volatile("s_waitcnt vmcnt(" #n ")" ::: "memory")
; #define PG8_WAIT_L(n) asm volatile("s_waitcnt lgkmcnt(" #n ")" ::: "memory")
; #define PG8_BAR __builtin_amdgcn_s_barrier()
; #define PG8_SCHED __builtin_amdgcn_sched_barrier(0)
; template <class Epi>
; DI void gemm_phase(LAS unsigned char* lds, const Gemm g, const StaticOrder& S, const Epi& E) {
;     ...
;       PG8_STAGE(PG8_SB(0, 1), b2 + hstepB, voffB);
;       PG8_WAIT_V(6); PG8_BAR; PG8_MMA(1, 1, At, B1); PG8_BAR;
;       PG8_LDB(B0, 1, 0); PG8_SCHED; PG8_LDA(At, 1, 0); PG8_STAGE(PG8_SA(0, 1), a2 + hstepA, voffA);
;       PG8_WAIT_L(8); PG8_BAR; PG8_WAIT_L(0); PG8_MMA(0, 0, At, B0); PG8_BAR; PG8_SCHED;
;       PG8_LDB(B1, 1, 1); PG8_STAGE(PG8_SB(1, 0), b3, voffB);
;       PG8_BAR; PG8_WAIT_L(0); PG8_MMA(0, 1, At, B1); PG8_BAR;
;       PG8_LDA(At, 1, 1); PG8_STAGE(PG8_SA(1, 0), a3, voffA);
;       PG8_BAR; PG8_WAIT_L(0); PG8_MMA(1, 0, At, B0); PG8_BAR; PG8_SCHED;
	s_add_u32 s60, s28, 0x20000
	s_addc_u32 s61, s29, 0
	s_add_i32 s59, s52, s39
	v_lshl_add_u64 v[154:155], s[60:61], 0, v[132:133]
	s_mov_b32 m0, s59
	s_nop 0
	global_load_lds_dwordx4 v[154:155], off
	v_lshl_add_u64 v[154:155], s[60:61], 0, v[136:137]
	s_add_i32 m0, s59, 0x2000
	s_nop 0
	global_load_lds_dwordx4 v[154:155], off
	s_waitcnt vmcnt(6)
	s_barrier
	v_mfma_f32_16x16x32_bf16 v[54:57], v[214:217], v[182:185], v[54:57]
	v_mfma_f32_16x16x32_bf16 v[50:53], v[222:225], v[182:185], v[50:53]
	v_mfma_f32_16x16x32_bf16 v[38:41], v[214:217], v[190:193], v[38:41]
	v_mfma_f32_16x16x32_bf16 v[34:37], v[222:225], v[190:193], v[34:37]
	v_mfma_f32_16x16x32_bf16 v[22:25], v[214:217], v[198:201], v[22:25]
	v_mfma_f32_16x16x32_bf16 v[18:21], v[222:225], v[198:201], v[18:21]
	v_mfma_f32_16x16x32_bf16 v[6:9], v[214:217], v[206:209], v[6:9]
	v_mfma_f32_16x16x32_bf16 v[2:5], v[222:225], v[206:209], v[2:5]
	v_mfma_f32_16x16x32_bf16 v[54:57], v[218:221], v[186:189], v[54:57]
	v_mfma_f32_16x16x32_bf16 v[50:53], v[226:229], v[186:189], v[50:53]
	v_mfma_f32_16x16x32_bf16 v[38:41], v[218:221], v[194:197], v[38:41]
	v_mfma_f32_16x16x32_bf16 v[34:37], v[226:229], v[194:197], v[34:37]
	v_mfma_f32_16x16x32_bf16 v[22:25], v[218:221], v[202:205], v[22:25]
	v_mfma_f32_16x16x32_bf16 v[18:21], v[226:229], v[202:205], v[18:21]
	v_mfma_f32_16x16x32_bf16 v[6:9], v[218:221], v[210:213], v[6:9]
	v_mfma_f32_16x16x32_bf16 v[2:5], v[226:229], v[210:213], v[2:5]
	s_add_i32 s59, 0, 0x18000
	v_add_u32_e32 v138, s59, v173
	s_barrier
	ds_read_b128 v[154:157], v138
	ds_read_b128 v[158:161], v138 offset:1024
	ds_read_b128 v[162:165], v138 offset:2048
	ds_read_b128 v[178:181], v138 offset:3072
	s_add_u32 s30, s30, 0x40000
	s_addc_u32 s31, s31, 0
	s_mov_b32 m0, s42
	v_lshl_add_u64 v[214:215], s[30:31], 0, v[130:131]
	ds_read_b128 v[182:185], v175 offset:32768
	ds_read_b128 v[186:189], v175 offset:33792
	ds_read_b128 v[190:193], v175 offset:34816
	ds_read_b128 v[194:197], v175 offset:35840
	ds_read_b128 v[198:201], v175 offset:36864
	ds_read_b128 v[202:205], v175 offset:37888
	ds_read_b128 v[206:209], v175 offset:38912
	ds_read_b128 v[210:213], v175 offset:39936
	global_load_lds_dwordx4 v[214:215], off
	v_lshl_add_u64 v[214:215], s[30:31], 0, v[134:135]
	s_mov_b32 m0, s43
	s_nop 0
	global_load_lds_dwordx4 v[214:215], off
	s_waitcnt lgkmcnt(8)
	s_barrier
	s_waitcnt lgkmcnt(0)
	v_mfma_f32_16x16x32_bf16 v[126:129], v[154:157], v[182:185], v[126:129]
	v_mfma_f32_16x16x32_bf16 v[122:125], v[162:165], v[182:185], v[122:125]
	v_mfma_f32_16x16x32_bf16 v[110:113], v[154:157], v[190:193], v[110:113]
	v_mfma_f32_16x16x32_bf16 v[106:109], v[162:165], v[190:193], v[106:109]
	v_mfma_f32_16x16x32_bf16 v[94:97], v[154:157], v[198:201], v[94:97]
	v_mfma_f32_16x16x32_bf16 v[90:93], v[162:165], v[198:201], v[90:93]
	v_mfma_f32_16x16x32_bf16 v[78:81], v[154:157], v[206:209], v[78:81]
	v_mfma_f32_16x16x32_bf16 v[74:77], v[162:165], v[206:209], v[74:77]
	v_mfma_f32_16x16x32_bf16 v[126:129], v[158:161], v[186:189], v[126:129]
	v_mfma_f32_16x16x32_bf16 v[122:125], v[178:181], v[186:189], v[122:125]
	v_mfma_f32_16x16x32_bf16 v[110:113], v[158:161], v[194:197], v[110:113]
	v_mfma_f32_16x16x32_bf16 v[106:109], v[178:181], v[194:197], v[106:109]
	v_mfma_f32_16x16x32_bf16 v[94:97], v[158:161], v[202:205], v[94:97]
	v_mfma_f32_16x16x32_bf16 v[90:93], v[178:181], v[202:205], v[90:93]
	v_mfma_f32_16x16x32_bf16 v[78:81], v[158:161], v[210:213], v[78:81]
	v_mfma_f32_16x16x32_bf16 v[74:77], v[178:181], v[210:213], v[74:77]
	s_barrier
	s_add_i32 s30, 0, 0x1c000
	s_add_i32 s31, s59, s39
	v_add_u32_e32 v138, s30, v173
	v_lshl_add_u64 v[230:231], v[230:231], 0, s[8:9]
	s_mov_b32 m0, s31
	ds_read_b128 v[214:217], v138
	ds_read_b128 v[218:221], v138 offset:1024
	ds_read_b128 v[222:225], v138 offset:2048
	ds_read_b128 v[226:229], v138 offset:3072
	global_load_lds_dwordx4 v[230:231], off
	v_lshl_add_u64 v[230:231], v[232:233], 0, s[8:9]
	s_add_i32 m0, s31, 0x2000
	s_nop 0
	global_load_lds_dwordx4 v[230:231], off
	s_barrier
	s_waitcnt lgkmcnt(0)
	v_mfma_f32_16x16x32_bf16 v[118:121], v[214:217], v[182:185], v[118:121]
	v_mfma_f32_16x16x32_bf16 v[114:117], v[222:225], v[182:185], v[114:117]
	v_mfma_f32_16x16x32_bf16 v[102:105], v[214:217], v[190:193], v[102:105]
	v_mfma_f32_16x16x32_bf16 v[98:101], v[222:225], v[190:193], v[98:101]
	v_mfma_f32_16x16x32_bf16 v[86:89], v[214:217], v[198:201], v[86:89]
	v_mfma_f32_16x16x32_bf16 v[82:85], v[222:225], v[198:201], v[82:85]
	v_mfma_f32_16x16x32_bf16 v[70:73], v[214:217], v[206:209], v[70:73]
	v_mfma_f32_16x16x32_bf16 v[66:69], v[222:225], v[206:209], v[66:69]
	v_mfma_f32_16x16x32_bf16 v[118:121], v[218:221], v[186:189], v[118:121]
	v_mfma_f32_16x16x32_bf16 v[114:117], v[226:229], v[186:189], v[114:117]
	v_mfma_f32_16x16x32_bf16 v[102:105], v[218:221], v[194:197], v[102:105]
	v_mfma_f32_16x16x32_bf16 v[98:101], v[226:229], v[194:197], v[98:101]
	v_mfma_f32_16x16x32_bf16 v[86:89], v[218:221], v[202:205], v[86:89]
	v_mfma_f32_16x16x32_bf16 v[82:85], v[226:229], v[202:205], v[82:85]
	v_mfma_f32_16x16x32_bf16 v[70:73], v[218:221], v[210:213], v[70:73]
	v_mfma_f32_16x16x32_bf16 v[66:69], v[226:229], v[210:213], v[66:69]
	s_mov_b32 m0, s45
	v_lshl_add_u64 v[230:231], v[234:235], 0, s[8:9]
	s_barrier
	ds_read_b128 v[182:185], v175 offset:49152
	ds_read_b128 v[186:189], v175 offset:50176
	ds_read_b128 v[190:193], v175 offset:51200
	ds_read_b128 v[194:197], v175 offset:52224
	ds_read_b128 v[198:201], v175 offset:53248
	ds_read_b128 v[202:205], v175 offset:54272
	ds_read_b128 v[206:209], v175 offset:55296
	ds_read_b128 v[210:213], v175 offset:56320
	global_load_lds_dwordx4 v[230:231], off
	v_lshl_add_u64 v[230:231], v[236:237], 0, s[8:9]
	s_mov_b32 m0, s46
	s_nop 0
	global_load_lds_dwordx4 v[230:231], off
	s_barrier
; template <class Epi>
; DI void gemm_phase(LAS unsigned char* lds, const Gemm g, const StaticOrder& S, const Epi& E) {
;     ...
;       PG8_BAR; PG8_WAIT_L(0); PG8_MMA(1, 0, At, B0); PG8_BAR; PG8_SCHED;
;       PG8_STAGE(PG8_SB(1, 1), b3 + hstepB, voffB);
;       PG8_WAIT_V(6); PG8_BAR; PG8_MMA(1, 1, At, B1); PG8_BAR;
;     }
;     E(acc, cur, wr, wc, fr, fq);
;   DI void operator()(const f32x4 (&acc)[2][2][4][2], const pg8::Unit& u, int wr, int wc, int fr, int fq) const {
;     ...
;         if (MODE == EP_IN) rs = ((const float*)(ws + OFF_RS0))[grow];
;         if (MODE == EP_UP) rs = ((const float*)(ws + OFF_RS2))[grow];
;         if (MODE == EP_Q || MODE == EP_KV) {
;           const f32x4* sp = (const f32x4*)(ws + OFF_SSQA) + (size_t)grow * 4 + (MODE == EP_KV ? 2 : 0);
;           const f32x4 s0 = sp[0], s1 = sp[1];
;           const float ss = (s0[0] + s0[1]) + (s0[2] + s0[3]) + (s1[0] + s1[1]) + (s1[2] + s1[3]);
;           rs = __builtin_amdgcn_rsqf(ss * (1.0f / 512) + EPS);
;           if (MODE == EP_Q) rs *= QSCALE;
;         }
;         float ssq = 0.f;
; #pragma unroll
;         for (int bj = 0; bj < 2; ++bj) {
;           f32x4 v0 = acc[ai][bj][m][0] * rs, v1 = acc[ai][bj][m][1] * rs;
;           if (MODE == EP_IN || MODE == EP_MIX || MODE == EP_DOWN) {
; #pragma unroll
;             for (int j = 0; j < 4; ++j) ssq += v0[j] * v0[j] + v1[j] * v1[j];
;           }
;           if (MODE == EP_UP) {
; #pragma unroll
;             for (int j = 0; j < 4; ++j) { float a = fmaxf(v0[j], 0.f), b = fmaxf(v1[j], 0.f); v0[j] = a * a; v1[j] = b * b; }
;           }
;           bf16_t* dst;
;           const int ct = bj * 128 + cl;
;           if (MODE == EP_IN) {
;             if (pn < 4) dst = (bf16_t*)(ws + OFF_PROJA) + (size_t)grow * 1024 + pn * 256 + ct;
;             else if (pn < 16) dst = (bf16_t*)(ws + OFF_PROJG) + (size_t)grow * 3072 + (pn - 4) * 256 + ct;
;             else dst = (bf16_t*)(ws + OFF_PROJS) + (size_t)grow * 256 + ct;
;           } else if (MODE == EP_Q) {
;             if (pn < 4) dst = (bf16_t*)(dout + DO_Q) + (size_t)grow * 1536 + (pn * 2 + bj) * 192 + cl;
;             else {
;               const int mm = (pn - 4) * 256 + ct, h = mm >> 6, r = mm & 63;
;               dst = (bf16_t*)(dout + DO_Q) + (size_t)grow * 1536 + h * 192 + 128 + r;
;               const int pos = grow < TP ? (grow & 4095) : grow - TP;
	s_waitcnt lgkmcnt(0)
	v_mfma_f32_16x16x32_bf16 v[62:65], v[154:157], v[182:185], v[62:65]
	v_mfma_f32_16x16x32_bf16 v[58:61], v[162:165], v[182:185], v[58:61]
	v_mfma_f32_16x16x32_bf16 v[46:49], v[154:157], v[190:193], v[46:49]
	v_mfma_f32_16x16x32_bf16 v[42:45], v[162:165], v[190:193], v[42:45]
	v_mfma_f32_16x16x32_bf16 v[30:33], v[154:157], v[198:201], v[30:33]
	v_mfma_f32_16x16x32_bf16 v[26:29], v[162:165], v[198:201], v[26:29]
	v_mfma_f32_16x16x32_bf16 v[14:17], v[154:157], v[206:209], v[14:17]
	v_mfma_f32_16x16x32_bf16 v[10:13], v[162:165], v[206:209], v[10:13]
	v_mfma_f32_16x16x32_bf16 v[62:65], v[158:161], v[186:189], v[62:65]
	v_mfma_f32_16x16x32_bf16 v[58:61], v[178:181], v[186:189], v[58:61]
	v_mfma_f32_16x16x32_bf16 v[46:49], v[158:161], v[194:197], v[46:49]
	v_mfma_f32_16x16x32_bf16 v[42:45], v[178:181], v[194:197], v[42:45]
	v_mfma_f32_16x16x32_bf16 v[30:33], v[158:161], v[202:205], v[30:33]
	v_mfma_f32_16x16x32_bf16 v[26:29], v[178:181], v[202:205], v[26:29]
	v_mfma_f32_16x16x32_bf16 v[14:17], v[158:161], v[210:213], v[14:17]
	v_mfma_f32_16x16x32_bf16 v[10:13], v[178:181], v[210:213], v[10:13]
	s_barrier
	s_add_u32 s28, s28, 0x20080
	s_addc_u32 s29, s29, 0
	s_add_i32 s30, s30, s39
	v_lshl_add_u64 v[154:155], s[28:29], 0, v[132:133]
	s_mov_b32 m0, s30
	s_nop 0
	global_load_lds_dwordx4 v[154:155], off
	v_lshl_add_u64 v[154:155], s[28:29], 0, v[136:137]
	s_add_i32 m0, s30, 0x2000
	s_nop 0
	global_load_lds_dwordx4 v[154:155], off
	s_waitcnt vmcnt(6)
	s_barrier
	v_mfma_f32_16x16x32_bf16 v[54:57], v[214:217], v[182:185], v[54:57]
	v_mfma_f32_16x16x32_bf16 v[50:53], v[222:225], v[182:185], v[50:53]
	v_mfma_f32_16x16x32_bf16 v[38:41], v[214:217], v[190:193], v[38:41]
	v_mfma_f32_16x16x32_bf16 v[34:37], v[222:225], v[190:193], v[34:37]
	v_mfma_f32_16x16x32_bf16 v[22:25], v[214:217], v[198:201], v[22:25]
	v_mfma_f32_16x16x32_bf16 v[18:21], v[222:225], v[198:201], v[18:21]
	v_mfma_f32_16x16x32_bf16 v[6:9], v[214:217], v[206:209], v[6:9]
	v_mfma_f32_16x16x32_bf16 v[2:5], v[222:225], v[206:209], v[2:5]
	v_mfma_f32_16x16x32_bf16 v[54:57], v[218:221], v[186:189], v[54:57]
	v_mfma_f32_16x16x32_bf16 v[50:53], v[226:229], v[186:189], v[50:53]
	v_mfma_f32_16x16x32_bf16 v[38:41], v[218:221], v[194:197], v[38:41]
	v_mfma_f32_16x16x32_bf16 v[34:37], v[226:229], v[194:197], v[34:37]
	v_mfma_f32_16x16x32_bf16 v[22:25], v[218:221], v[202:205], v[22:25]
	v_mfma_f32_16x16x32_bf16 v[18:21], v[226:229], v[202:205], v[18:21]
	v_mfma_f32_16x16x32_bf16 v[6:9], v[218:221], v[210:213], v[6:9]
	v_mfma_f32_16x16x32_bf16 v[2:5], v[226:229], v[210:213], v[2:5]
	s_add_i32 s53, s53, 2
	s_add_u32 s26, s26, 0x100
	s_addc_u32 s27, s27, 0
	s_add_u32 s21, s21, 0x100
	s_addc_u32 s33, s33, 0
	s_cmp_gt_u32 s53, 5
	s_barrier
	s_cbranch_scc0 .LBB0_484
	v_lshl_add_u32 v156, s4, 8, v172
	v_ashrrev_i32_e32 v157, 31, v156
	v_lshlrev_b64 v[154:155], 6, v[156:157]
	v_lshl_add_u64 v[154:155], s[10:11], 0, v[154:155]
	global_load_dwordx4 v[160:163], v[154:155], off
	global_load_dwordx4 v[178:181], v[154:155], off offset:16
	v_and_b32_e32 v138, 0xfcf, v156
	v_add_u32_e32 v155, 0xffffc000, v156
	v_cmp_gt_i32_e32 vcc, s44, v156
	s_cmp_gt_i32 s2, 3
	v_readlane_b32 s60, v238, 32
	v_cndmask_b32_e32 v138, v155, v138, vcc
	s_cselect_b64 s[4:5], -1, 0
	s_lshl_b32 s19, s2, 8
	v_mad_i64_i32 v[158:159], s[28:29], v156, s54, 0
	v_readlane_b32 s66, v238, 38
	v_readlane_b32 s67, v238, 39
	s_mov_b64 s[26:27], -1
	v_lshlrev_b32_e32 v154, 1, v142
	s_add_i32 s19, s19, s47
	s_and_b64 vcc, exec, s[4:5]
	v_lshl_add_u64 v[158:159], s[66:67], 0, v[158:159]
	v_readlane_b32 s61, v238, 33
	v_readlane_b32 s62, v238, 34
	v_readlane_b32 s63, v238, 35
	v_readlane_b32 s64, v238, 36
	v_readlane_b32 s65, v238, 37
	s_waitcnt vmcnt(0)
	v_mov_b32_e32 v182, v161
	v_mov_b32_e32 v183, v162
	v_mov_b32_e32 v161, v163
	v_mov_b32_e32 v162, v180
	v_mov_b32_e32 v163, v178
	v_mov_b32_e32 v178, v181
	v_pk_add_f32 v[160:161], v[182:183], v[160:161]
	v_pk_add_f32 v[162:163], v[162:163], v[178:179]
	v_add_f32_e32 v155, v160, v161
	v_add_f32_e32 v155, v155, v163
	v_add_f32_e32 v155, v162, v155
	v_fmamk_f32 v155, v155, 0x3b000000, v177
	v_rsq_f32_e32 v155, v155
	v_lshlrev_b32_e32 v160, 5, v138
	v_ashrrev_i32_e32 v161, 31, v160
	v_lshl_add_u64 v[160:161], v[160:161], 3, v[144:145]
	v_mul_f32_e32 v162, 0x3dd53b94, v155
	v_pk_mul_f32 v[128:129], v[128:129], v[162:163] op_sel_hi:[1,0]
	v_pk_mul_f32 v[126:127], v[126:127], v[162:163] op_sel_hi:[1,0]
	v_pk_mul_f32 v[124:125], v[124:125], v[162:163] op_sel_hi:[1,0]
	v_pk_mul_f32 v[122:123], v[122:123], v[162:163] op_sel_hi:[1,0]
	s_cbranch_vccz .LBB0_487
	global_load_dwordx4 v[178:181], v[160:161], off
	global_load_dwordx4 v[182:185], v[160:161], off offset:16
	s_lshr_b32 s3, s19, 6
	s_mul_i32 s6, s3, 0xc0
	v_mov_b32_e32 v155, v139
	v_lshl_add_u64 v[164:165], s[6:7], 1, v[158:159]
	v_lshl_add_u64 v[164:165], v[164:165], 0, v[154:155]
	s_mov_b64 s[26:27], 0
	v_lshl_add_u64 v[164:165], v[164:165], 0, s[12:13]
	s_waitcnt vmcnt(0)
	v_pk_mul_f32 v[188:189], v[126:127], v[178:179] op_sel:[1,1] op_sel_hi:[0,1]
	v_mul_f32_e32 v138, v129, v181
	v_mul_f32_e32 v190, v128, v181
	v_pk_mul_f32 v[194:195], v[122:123], v[182:183] op_sel:[1,1] op_sel_hi:[0,1]
	v_mul_f32_e32 v196, v125, v185
	v_mul_f32_e32 v198, v124, v185
	v_pk_mul_f32 v[186:187], v[126:127], v[178:179]
	v_pk_mul_f32 v[192:193], v[122:123], v[182:183]
	v_pk_fma_f32 v[126:127], v[126:127], v[178:179], v[188:189] op_sel_hi:[1,0,1]
	v_pk_fma_f32 v[178:179], v[128:129], v[180:181], v[138:139] op_sel_hi:[1,1,0] neg_lo:[0,0,1] neg_hi:[0,0,1]
	v_pk_fma_f32 v[128:129], v[128:129], v[180:181], v[190:191] op_sel:[1,0,0] op_sel_hi:[0,1,0]
	v_pk_fma_f32 v[122:123], v[122:123], v[182:183], v[194:195] op_sel_hi:[1,0,1]
	v_pk_fma_f32 v[180:181], v[124:125], v[184:185], v[196:197] op_sel_hi:[1,1,0] neg_lo:[0,0,1] neg_hi:[0,0,1]
	v_pk_fma_f32 v[124:125], v[124:125], v[184:185], v[198:199] op_sel:[1,0,0] op_sel_hi:[0,1,0]
	v_sub_f32_e32 v122, v192, v194
	v_sub_f32_e32 v126, v186, v188
	v_mov_b32_e32 v129, v128
	v_mov_b32_e32 v128, v178
	v_mov_b32_e32 v125, v124
	v_mov_b32_e32 v124, v180

; #define PG8_STAGE(bufoff, gbase, voff) do { _Pragma("unroll") for (int _i = 0; _i < 2; ++_i) \
;     __builtin_amdgcn_global_load_lds((const unsigned*)((const char*)(gbase) + (voff)[_i]), (LAS unsigned*)(lds + (bufoff) + ldsw + _i * 8192), 16, 0, 0); } while (0)
; #define PG8_LDA(dst, b, h) do { _Pragma("unroll") for (int m = 0; m < 4; ++m) _Pragma("unroll") for (int k = 0; k < 2; ++k) dst[m][k] = *(const LAS bf16x8*)(lds + PG8_SA(b, h) + aoff + m * 2048 + k * 1024); } while (0)
; #define PG8_LDB(dst, b, h) do { _Pragma("unroll") for (int n = 0; n < 2; ++n) _Pragma("unroll") for (int k = 0; k < 2; ++k) dst[n][k] = *(const LAS bf16x8*)(lds + PG8_SB(b, h) + boff + n * 2048 + k * 1024); } while (0)
; #define PG8_MMA(ai, bj, At, Bt) do { __builtin_amdgcn_s_setprio(1); _Pragma("unroll") for (int m = 0; m < 4; ++m) _Pragma("unroll") for (int n = 0; n < 2; ++n) _Pragma("unroll") for (int k = 0; k < 2; ++k) \
;     acc[ai][bj][m][n] = __builtin_amdgcn_mfma_f32_16x16x32_bf16(Bt[n][k], At[m][k], acc[ai][bj][m][n], 0, 0, 0); __builtin_amdgcn_s_setprio(0); } while (0)
; #define PG8_WAIT_L(n) asm volatile("s_waitcnt lgkmcnt(" #n ")" ::: "memory")
; #define PG8_BAR __builtin_amdgcn_s_barrier()
; #define PG8_SCHED __builtin_amdgcn_sched_barrier(0)
; template <class Epi>
; DI void gemm_phase(LAS unsigned char* lds, const Gemm g, const StaticOrder& S, const Epi& E) {
;     ...
;     for (int t = 0; t < nt; t += 2) {
;       const bool last = (t == nt - 2);
;       const char* a1 = cA + PG8_AK(t + 1);
;       const char* a2 = last ? nA : cA + PG8_AK(t + 2); const char* b2 = last ? nB : cB + (size_t)(t + 2) * kstep;
;       const char* a3 = a2 + kstep; const char* b3 = b2 + kstep;
;       PG8_LDB(B0, 0, 0); PG8_SCHED; PG8_LDA(At, 0, 0); PG8_STAGE(PG8_SA(1, 1), a1 + hstepA, voffA);
;       PG8_WAIT_L(8); PG8_BAR; PG8_WAIT_L(0); PG8_MMA(0, 0, At, B0); PG8_BAR; PG8_SCHED;
;       PG8_LDB(B1, 0, 1); PG8_STAGE(PG8_SB(0, 0), b2, voffB);
;       PG8_BAR; PG8_WAIT_L(0); PG8_MMA(0, 1, At, B1); PG8_BAR;
;       PG8_LDA(At, 0, 1); PG8_STAGE(PG8_SA(0, 0), a2, voffA);
;       PG8_BAR; PG8_WAIT_L(0); PG8_MMA(1, 0, At, B0); PG8_BAR; PG8_SCHED;
.LBB0_567:
	ds_read_b128 v[156:159], v1
	ds_read_b128 v[160:163], v1 offset:1024
	ds_read_b128 v[164:167], v1 offset:2048
	ds_read_b128 v[168:171], v1 offset:3072
	s_add_u32 s20, s18, 0xfffc0080
	s_addc_u32 s21, s19, -1
	s_cmp_eq_u32 s47, 4
	s_cselect_b32 s23, s11, s21
	s_cselect_b32 s22, s43, s20
	s_cselect_b32 s21, s9, s46
	s_cselect_b32 s20, s44, s45
	v_lshl_add_u64 v[148:149], s[18:19], 0, v[140:141]
	s_add_i32 m0, s17, 0xc000
	ds_read_b128 v[172:175], v152
	ds_read_b128 v[176:179], v152 offset:1024
	ds_read_b128 v[180:183], v152 offset:2048
	ds_read_b128 v[184:187], v152 offset:3072
	ds_read_b128 v[188:191], v152 offset:4096
	ds_read_b128 v[192:195], v152 offset:5120
	ds_read_b128 v[196:199], v152 offset:6144
	ds_read_b128 v[200:203], v152 offset:7168
	global_load_lds_dwordx4 v[148:149], off
	v_lshl_add_u64 v[148:149], s[18:19], 0, v[142:143]
	s_add_i32 m0, s17, 0xe000
	s_nop 0
	global_load_lds_dwordx4 v[148:149], off
	s_waitcnt lgkmcnt(8)
	s_barrier
	s_waitcnt lgkmcnt(0)
	v_mfma_f32_16x16x32_bf16 v[126:129], v[156:159], v[172:175], v[126:129]
	v_mfma_f32_16x16x32_bf16 v[122:125], v[164:167], v[172:175], v[122:125]
	v_mfma_f32_16x16x32_bf16 v[110:113], v[156:159], v[180:183], v[110:113]
	v_mfma_f32_16x16x32_bf16 v[106:109], v[164:167], v[180:183], v[106:109]
	v_mfma_f32_16x16x32_bf16 v[94:97], v[156:159], v[188:191], v[94:97]
	v_mfma_f32_16x16x32_bf16 v[90:93], v[164:167], v[188:191], v[90:93]
	v_mfma_f32_16x16x32_bf16 v[78:81], v[156:159], v[196:199], v[78:81]
	v_mfma_f32_16x16x32_bf16 v[74:77], v[164:167], v[196:199], v[74:77]
	v_mfma_f32_16x16x32_bf16 v[126:129], v[160:163], v[176:179], v[126:129]
	v_mfma_f32_16x16x32_bf16 v[122:125], v[168:171], v[176:179], v[122:125]
	v_mfma_f32_16x16x32_bf16 v[110:113], v[160:163], v[184:187], v[110:113]
	v_mfma_f32_16x16x32_bf16 v[106:109], v[168:171], v[184:187], v[106:109]
	v_mfma_f32_16x16x32_bf16 v[94:97], v[160:163], v[192:195], v[94:97]
	v_mfma_f32_16x16x32_bf16 v[90:93], v[168:171], v[192:195], v[90:93]
	v_mfma_f32_16x16x32_bf16 v[78:81], v[160:163], v[200:203], v[78:81]
	v_mfma_f32_16x16x32_bf16 v[74:77], v[168:171], v[200:203], v[74:77]
	s_barrier
	s_add_i32 s48, s39, s30
	v_lshl_add_u64 v[148:149], s[20:21], 0, v[132:133]
	s_mov_b32 m0, s48
	ds_read_b128 v[204:207], v153
	ds_read_b128 v[208:211], v153 offset:1024
	ds_read_b128 v[212:215], v153 offset:2048
	ds_read_b128 v[216:219], v153 offset:3072
	global_load_lds_dwordx4 v[148:149], off
	v_lshl_add_u64 v[220:221], s[20:21], 0, v[136:137]
	s_add_i32 m0, s48, 0x2000
	s_nop 0
	global_load_lds_dwordx4 v[220:221], off
	s_barrier
	s_waitcnt lgkmcnt(0)
	v_mfma_f32_16x16x32_bf16 v[118:121], v[204:207], v[172:175], v[118:121]
	v_mfma_f32_16x16x32_bf16 v[114:117], v[212:215], v[172:175], v[114:117]
	v_mfma_f32_16x16x32_bf16 v[102:105], v[204:207], v[180:183], v[102:105]
	v_mfma_f32_16x16x32_bf16 v[98:101], v[212:215], v[180:183], v[98:101]
	v_mfma_f32_16x16x32_bf16 v[86:89], v[204:207], v[188:191], v[86:89]
	v_mfma_f32_16x16x32_bf16 v[82:85], v[212:215], v[188:191], v[82:85]
	v_mfma_f32_16x16x32_bf16 v[70:73], v[204:207], v[196:199], v[70:73]
	v_mfma_f32_16x16x32_bf16 v[66:69], v[212:215], v[196:199], v[66:69]
	v_mfma_f32_16x16x32_bf16 v[118:121], v[208:211], v[176:179], v[118:121]
	v_mfma_f32_16x16x32_bf16 v[114:117], v[216:219], v[176:179], v[114:117]
	v_mfma_f32_16x16x32_bf16 v[102:105], v[208:211], v[184:187], v[102:105]
	v_mfma_f32_16x16x32_bf16 v[98:101], v[216:219], v[184:187], v[98:101]
	v_mfma_f32_16x16x32_bf16 v[86:89], v[208:211], v[192:195], v[86:89]
	v_mfma_f32_16x16x32_bf16 v[82:85], v[216:219], v[192:195], v[82:85]
	v_mfma_f32_16x16x32_bf16 v[70:73], v[208:211], v[200:203], v[70:73]
	v_mfma_f32_16x16x32_bf16 v[66:69], v[216:219], v[200:203], v[66:69]
	s_mov_b32 m0, s17
	v_lshl_add_u64 v[222:223], s[22:23], 0, v[130:131]
	s_barrier
	ds_read_b128 v[172:175], v152 offset:16384
	ds_read_b128 v[176:179], v152 offset:17408
	ds_read_b128 v[180:183], v152 offset:18432
	ds_read_b128 v[184:187], v152 offset:19456
	ds_read_b128 v[188:191], v152 offset:20480
	ds_read_b128 v[192:195], v152 offset:21504
	ds_read_b128 v[196:199], v152 offset:22528
	ds_read_b128 v[200:203], v152 offset:23552
	global_load_lds_dwordx4 v[222:223], off
	v_lshl_add_u64 v[224:225], s[22:23], 0, v[134:135]
	s_mov_b32 m0, s31
	s_nop 0
	global_load_lds_dwordx4 v[224:225], off
	s_barrier
	s_waitcnt lgkmcnt(0)
	v_mfma_f32_16x16x32_bf16 v[62:65], v[156:159], v[172:175], v[62:65]
	v_mfma_f32_16x16x32_bf16 v[58:61], v[164:167], v[172:175], v[58:61]
	v_mfma_f32_16x16x32_bf16 v[46:49], v[156:159], v[180:183], v[46:49]
	v_mfma_f32_16x16x32_bf16 v[42:45], v[164:167], v[180:183], v[42:45]
	v_mfma_f32_16x16x32_bf16 v[30:33], v[156:159], v[188:191], v[30:33]
	v_mfma_f32_16x16x32_bf16 v[26:29], v[164:167], v[188:191], v[26:29]
	v_mfma_f32_16x16x32_bf16 v[14:17], v[156:159], v[196:199], v[14:17]
	v_mfma_f32_16x16x32_bf16 v[10:13], v[164:167], v[196:199], v[10:13]
	v_mfma_f32_16x16x32_bf16 v[62:65], v[160:163], v[176:179], v[62:65]
	v_mfma_f32_16x16x32_bf16 v[58:61], v[168:171], v[176:179], v[58:61]
	v_mfma_f32_16x16x32_bf16 v[46:49], v[160:163], v[184:187], v[46:49]
	v_mfma_f32_16x16x32_bf16 v[42:45], v[168:171], v[184:187], v[42:45]
	v_mfma_f32_16x16x32_bf16 v[30:33], v[160:163], v[192:195], v[30:33]
	v_mfma_f32_16x16x32_bf16 v[26:29], v[168:171], v[192:195], v[26:29]
	v_mfma_f32_16x16x32_bf16 v[14:17], v[160:163], v[200:203], v[14:17]
	v_mfma_f32_16x16x32_bf16 v[10:13], v[168:171], v[200:203], v[10:13]
	s_barrier
; #define PG8_STAGE(bufoff, gbase, voff) do { _Pragma("unroll") for (int _i = 0; _i < 2; ++_i) \
;     __builtin_amdgcn_global_load_lds((const unsigned*)((const char*)(gbase) + (voff)[_i]), (LAS unsigned*)(lds + (bufoff) + ldsw + _i * 8192), 16, 0, 0); } while (0)
; #define PG8_LDA(dst, b, h) do { _Pragma("unroll") for (int m = 0; m < 4; ++m) _Pragma("unroll") for (int k = 0; k < 2; ++k) dst[m][k] = *(const LAS bf16x8*)(lds + PG8_SA(b, h) + aoff + m * 2048 + k * 1024); } while (0)
; #define PG8_LDB(dst, b, h) do { _Pragma("unroll") for (int n = 0; n < 2; ++n) _Pragma("unroll") for (int k = 0; k < 2; ++k) dst[n][k] = *(const LAS bf16x8*)(lds + PG8_SB(b, h) + boff + n * 2048 + k * 1024); } while (0)
; #define PG8_MMA(ai, bj, At, Bt) do { __builtin_amdgcn_s_setprio(1); _Pragma("unroll") for (int m = 0; m < 4; ++m) _Pragma("unroll") for (int n = 0; n < 2; ++n) _Pragma("unroll") for (int k = 0; k < 2; ++k) \
;     acc[ai][bj][m][n] = __builtin_amdgcn_mfma_f32_16x16x32_bf16(Bt[n][k], At[m][k], acc[ai][bj][m][n], 0, 0, 0); __builtin_amdgcn_s_setprio(0); } while (0)
; #define PG8_WAIT_V(n) asm volatile("s_waitcnt vmcnt(" #n ")" ::: "memory")
; #define PG8_WAIT_L(n) asm volatile("s_waitcnt lgkmcnt(" #n ")" ::: "memory")
; #define PG8_BAR __builtin_amdgcn_s_barrier()
; #define PG8_SCHED __builtin_amdgcn_sched_barrier(0)
; template <class Epi>
; DI void gemm_phase(LAS unsigned char* lds, const Gemm g, const StaticOrder& S, const Epi& E) {
;     ...
;       PG8_STAGE(PG8_SB(0, 1), b2 + hstepB, voffB);
;       PG8_WAIT_V(6); PG8_BAR; PG8_MMA(1, 1, At, B1); PG8_BAR;
;       PG8_LDB(B0, 1, 0); PG8_SCHED; PG8_LDA(At, 1, 0); PG8_STAGE(PG8_SA(0, 1), a2 + hstepA, voffA);
;       PG8_WAIT_L(8); PG8_BAR; PG8_WAIT_L(0); PG8_MMA(0, 0, At, B0); PG8_BAR; PG8_SCHED;
;       PG8_LDB(B1, 1, 1); PG8_STAGE(PG8_SB(1, 0), b3, voffB);
;       PG8_BAR; PG8_WAIT_L(0); PG8_MMA(0, 1, At, B1); PG8_BAR;
;       PG8_LDA(At, 1, 1); PG8_STAGE(PG8_SA(1, 0), a3, voffA);
;       PG8_BAR; PG8_WAIT_L(0); PG8_MMA(1, 0, At, B0); PG8_BAR; PG8_SCHED;
	s_add_u32 s48, s20, 0x20000
	s_addc_u32 s49, s21, 0
	s_add_i32 s50, s40, s30
	v_lshl_add_u64 v[156:157], s[48:49], 0, v[132:133]
	s_mov_b32 m0, s50
	s_nop 0
	global_load_lds_dwordx4 v[156:157], off
	v_lshl_add_u64 v[156:157], s[48:49], 0, v[136:137]
	s_add_i32 m0, s50, 0x2000
	s_nop 0
	global_load_lds_dwordx4 v[156:157], off
	s_waitcnt vmcnt(6)
	s_barrier
	v_mfma_f32_16x16x32_bf16 v[54:57], v[204:207], v[172:175], v[54:57]
	v_mfma_f32_16x16x32_bf16 v[50:53], v[212:215], v[172:175], v[50:53]
	v_mfma_f32_16x16x32_bf16 v[38:41], v[204:207], v[180:183], v[38:41]
	v_mfma_f32_16x16x32_bf16 v[34:37], v[212:215], v[180:183], v[34:37]
	v_mfma_f32_16x16x32_bf16 v[22:25], v[204:207], v[188:191], v[22:25]
	v_mfma_f32_16x16x32_bf16 v[18:21], v[212:215], v[188:191], v[18:21]
	v_mfma_f32_16x16x32_bf16 v[6:9], v[204:207], v[196:199], v[6:9]
	v_mfma_f32_16x16x32_bf16 v[2:5], v[212:215], v[196:199], v[2:5]
	v_mfma_f32_16x16x32_bf16 v[54:57], v[208:211], v[176:179], v[54:57]
	v_mfma_f32_16x16x32_bf16 v[50:53], v[216:219], v[176:179], v[50:53]
	v_mfma_f32_16x16x32_bf16 v[38:41], v[208:211], v[184:187], v[38:41]
	v_mfma_f32_16x16x32_bf16 v[34:37], v[216:219], v[184:187], v[34:37]
	v_mfma_f32_16x16x32_bf16 v[22:25], v[208:211], v[192:195], v[22:25]
	v_mfma_f32_16x16x32_bf16 v[18:21], v[216:219], v[192:195], v[18:21]
	v_mfma_f32_16x16x32_bf16 v[6:9], v[208:211], v[200:203], v[6:9]
	v_mfma_f32_16x16x32_bf16 v[2:5], v[216:219], v[200:203], v[2:5]
	s_add_i32 s48, 0, 0x18000
	v_add_u32_e32 v155, s48, v151
	s_barrier
	ds_read_b128 v[156:159], v155
	ds_read_b128 v[160:163], v155 offset:1024
	ds_read_b128 v[164:167], v155 offset:2048
	ds_read_b128 v[168:171], v155 offset:3072
	s_add_u32 s22, s22, 0x40000
	s_addc_u32 s23, s23, 0
	s_mov_b32 m0, s33
	v_lshl_add_u64 v[204:205], s[22:23], 0, v[130:131]
	ds_read_b128 v[172:175], v152 offset:32768
	ds_read_b128 v[176:179], v152 offset:33792
	ds_read_b128 v[180:183], v152 offset:34816
	ds_read_b128 v[184:187], v152 offset:35840
	ds_read_b128 v[188:191], v152 offset:36864
	ds_read_b128 v[192:195], v152 offset:37888
	ds_read_b128 v[196:199], v152 offset:38912
	ds_read_b128 v[200:203], v152 offset:39936
	global_load_lds_dwordx4 v[204:205], off
	v_lshl_add_u64 v[204:205], s[22:23], 0, v[134:135]
	s_mov_b32 m0, s34
	s_nop 0
	global_load_lds_dwordx4 v[204:205], off
	s_waitcnt lgkmcnt(8)
	s_barrier
	s_waitcnt lgkmcnt(0)
	v_mfma_f32_16x16x32_bf16 v[126:129], v[156:159], v[172:175], v[126:129]
	v_mfma_f32_16x16x32_bf16 v[122:125], v[164:167], v[172:175], v[122:125]
	v_mfma_f32_16x16x32_bf16 v[110:113], v[156:159], v[180:183], v[110:113]
	v_mfma_f32_16x16x32_bf16 v[106:109], v[164:167], v[180:183], v[106:109]
	v_mfma_f32_16x16x32_bf16 v[94:97], v[156:159], v[188:191], v[94:97]
	v_mfma_f32_16x16x32_bf16 v[90:93], v[164:167], v[188:191], v[90:93]
	v_mfma_f32_16x16x32_bf16 v[78:81], v[156:159], v[196:199], v[78:81]
	v_mfma_f32_16x16x32_bf16 v[74:77], v[164:167], v[196:199], v[74:77]
	v_mfma_f32_16x16x32_bf16 v[126:129], v[160:163], v[176:179], v[126:129]
	v_mfma_f32_16x16x32_bf16 v[122:125], v[168:171], v[176:179], v[122:125]
	v_mfma_f32_16x16x32_bf16 v[110:113], v[160:163], v[184:187], v[110:113]
	v_mfma_f32_16x16x32_bf16 v[106:109], v[168:171], v[184:187], v[106:109]
	v_mfma_f32_16x16x32_bf16 v[94:97], v[160:163], v[192:195], v[94:97]
	v_mfma_f32_16x16x32_bf16 v[90:93], v[168:171], v[192:195], v[90:93]
	v_mfma_f32_16x16x32_bf16 v[78:81], v[160:163], v[200:203], v[78:81]
	v_mfma_f32_16x16x32_bf16 v[74:77], v[168:171], v[200:203], v[74:77]
	s_barrier
	s_add_i32 s22, 0, 0x1c000
	s_add_i32 s23, s48, s30
	v_add_u32_e32 v155, s22, v151
	v_lshl_add_u64 v[148:149], v[148:149], 0, s[2:3]
	s_mov_b32 m0, s23
	ds_read_b128 v[204:207], v155
	ds_read_b128 v[208:211], v155 offset:1024
	ds_read_b128 v[212:215], v155 offset:2048
	ds_read_b128 v[216:219], v155 offset:3072
	global_load_lds_dwordx4 v[148:149], off
	v_lshl_add_u64 v[148:149], v[220:221], 0, s[2:3]
	s_add_i32 m0, s23, 0x2000
	s_nop 0
	global_load_lds_dwordx4 v[148:149], off
	s_barrier
	s_waitcnt lgkmcnt(0)
	v_mfma_f32_16x16x32_bf16 v[118:121], v[204:207], v[172:175], v[118:121]
	v_mfma_f32_16x16x32_bf16 v[114:117], v[212:215], v[172:175], v[114:117]
	v_mfma_f32_16x16x32_bf16 v[102:105], v[204:207], v[180:183], v[102:105]
	v_mfma_f32_16x16x32_bf16 v[98:101], v[212:215], v[180:183], v[98:101]
	v_mfma_f32_16x16x32_bf16 v[86:89], v[204:207], v[188:191], v[86:89]
	v_mfma_f32_16x16x32_bf16 v[82:85], v[212:215], v[188:191], v[82:85]
	v_mfma_f32_16x16x32_bf16 v[70:73], v[204:207], v[196:199], v[70:73]
	v_mfma_f32_16x16x32_bf16 v[66:69], v[212:215], v[196:199], v[66:69]
	v_mfma_f32_16x16x32_bf16 v[118:121], v[208:211], v[176:179], v[118:121]
	v_mfma_f32_16x16x32_bf16 v[114:117], v[216:219], v[176:179], v[114:117]
	v_mfma_f32_16x16x32_bf16 v[102:105], v[208:211], v[184:187], v[102:105]
	v_mfma_f32_16x16x32_bf16 v[98:101], v[216:219], v[184:187], v[98:101]
	v_mfma_f32_16x16x32_bf16 v[86:89], v[208:211], v[192:195], v[86:89]
	v_mfma_f32_16x16x32_bf16 v[82:85], v[216:219], v[192:195], v[82:85]
	v_mfma_f32_16x16x32_bf16 v[70:73], v[208:211], v[200:203], v[70:73]
	v_mfma_f32_16x16x32_bf16 v[66:69], v[216:219], v[200:203], v[66:69]
	s_mov_b32 m0, s36
	v_lshl_add_u64 v[148:149], v[222:223], 0, s[2:3]
	s_barrier
	ds_read_b128 v[172:175], v152 offset:49152
	ds_read_b128 v[176:179], v152 offset:50176
	ds_read_b128 v[180:183], v152 offset:51200
	ds_read_b128 v[184:187], v152 offset:52224
	ds_read_b128 v[188:191], v152 offset:53248
	ds_read_b128 v[192:195], v152 offset:54272
	ds_read_b128 v[196:199], v152 offset:55296
	ds_read_b128 v[200:203], v152 offset:56320
	global_load_lds_dwordx4 v[148:149], off
	v_lshl_add_u64 v[148:149], v[224:225], 0, s[2:3]
	s_mov_b32 m0, s37
	s_nop 0
	global_load_lds_dwordx4 v[148:149], off
	s_barrier
; template <class Epi>
; DI void gemm_phase(LAS unsigned char* lds, const Gemm g, const StaticOrder& S, const Epi& E) {
;     ...
;       PG8_BAR; PG8_WAIT_L(0); PG8_MMA(1, 0, At, B0); PG8_BAR; PG8_SCHED;
;       PG8_STAGE(PG8_SB(1, 1), b3 + hstepB, voffB);
;       PG8_WAIT_V(6); PG8_BAR; PG8_MMA(1, 1, At, B1); PG8_BAR;
;     }
;     E(acc, cur, wr, wc, fr, fq);
;   DI void operator()(const f32x4 (&acc)[2][2][4][2], const pg8::Unit& u, int wr, int wc, int fr, int fq) const {
;     ...
;         if (MODE == EP_IN) rs = ((const float*)(ws + OFF_RS0))[grow];
;         if (MODE == EP_UP) rs = ((const float*)(ws + OFF_RS2))[grow];
;         if (MODE == EP_Q || MODE == EP_KV) {
;           const f32x4* sp = (const f32x4*)(ws + OFF_SSQA) + (size_t)grow * 4 + (MODE == EP_KV ? 2 : 0);
;           const f32x4 s0 = sp[0], s1 = sp[1];
;           const float ss = (s0[0] + s0[1]) + (s0[2] + s0[3]) + (s1[0] + s1[1]) + (s1[2] + s1[3]);
;           rs = __builtin_amdgcn_rsqf(ss * (1.0f / 512) + EPS);
;           if (MODE == EP_Q) rs *= QSCALE;
;         }
;         float ssq = 0.f;
; #pragma unroll
;         for (int bj = 0; bj < 2; ++bj) {
;           f32x4 v0 = acc[ai][bj][m][0] * rs, v1 = acc[ai][bj][m][1] * rs;
;           if (MODE == EP_IN || MODE == EP_MIX || MODE == EP_DOWN) {
; #pragma unroll
;             for (int j = 0; j < 4; ++j) ssq += v0[j] * v0[j] + v1[j] * v1[j];
;           }
;           if (MODE == EP_UP) {
; #pragma unroll
;             for (int j = 0; j < 4; ++j) { float a = fmaxf(v0[j], 0.f), b = fmaxf(v1[j], 0.f); v0[j] = a * a; v1[j] = b * b; }
;           }
;           bf16_t* dst;
;           const int ct = bj * 128 + cl;
;           if (MODE == EP_IN) {
;             if (pn < 4) dst = (bf16_t*)(ws + OFF_PROJA) + (size_t)grow * 1024 + pn * 256 + ct;
;             else if (pn < 16) dst = (bf16_t*)(ws + OFF_PROJG) + (size_t)grow * 3072 + (pn - 4) * 256 + ct;
;             else dst = (bf16_t*)(ws + OFF_PROJS) + (size_t)grow * 256 + ct;
;           } else if (MODE == EP_Q) {
;             if (pn < 4) dst = (bf16_t*)(dout + DO_Q) + (size_t)grow * 1536 + (pn * 2 + bj) * 192 + cl;
;             else {
;               const int mm = (pn - 4) * 256 + ct, h = mm >> 6, r = mm & 63;
;               dst = (bf16_t*)(dout + DO_Q) + (size_t)grow * 1536 + h * 192 + 128 + r;
;               const int pos = grow < TP ? (grow & 4095) : grow - TP;
	s_waitcnt lgkmcnt(0)
	v_mfma_f32_16x16x32_bf16 v[62:65], v[156:159], v[172:175], v[62:65]
	v_mfma_f32_16x16x32_bf16 v[58:61], v[164:167], v[172:175], v[58:61]
	v_mfma_f32_16x16x32_bf16 v[46:49], v[156:159], v[180:183], v[46:49]
	v_mfma_f32_16x16x32_bf16 v[42:45], v[164:167], v[180:183], v[42:45]
	v_mfma_f32_16x16x32_bf16 v[30:33], v[156:159], v[188:191], v[30:33]
	v_mfma_f32_16x16x32_bf16 v[26:29], v[164:167], v[188:191], v[26:29]
	v_mfma_f32_16x16x32_bf16 v[14:17], v[156:159], v[196:199], v[14:17]
	v_mfma_f32_16x16x32_bf16 v[10:13], v[164:167], v[196:199], v[10:13]
	v_mfma_f32_16x16x32_bf16 v[62:65], v[160:163], v[176:179], v[62:65]
	v_mfma_f32_16x16x32_bf16 v[58:61], v[168:171], v[176:179], v[58:61]
	v_mfma_f32_16x16x32_bf16 v[46:49], v[160:163], v[184:187], v[46:49]
	v_mfma_f32_16x16x32_bf16 v[42:45], v[168:171], v[184:187], v[42:45]
	v_mfma_f32_16x16x32_bf16 v[30:33], v[160:163], v[192:195], v[30:33]
	v_mfma_f32_16x16x32_bf16 v[26:29], v[168:171], v[192:195], v[26:29]
	v_mfma_f32_16x16x32_bf16 v[14:17], v[160:163], v[200:203], v[14:17]
	v_mfma_f32_16x16x32_bf16 v[10:13], v[168:171], v[200:203], v[10:13]
	s_barrier
	s_add_u32 s20, s20, 0x20080
	s_addc_u32 s21, s21, 0
	s_add_i32 s22, s22, s30
	v_lshl_add_u64 v[148:149], s[20:21], 0, v[132:133]
	s_mov_b32 m0, s22
	s_nop 0
	global_load_lds_dwordx4 v[148:149], off
	v_lshl_add_u64 v[148:149], s[20:21], 0, v[136:137]
	s_add_i32 m0, s22, 0x2000
	s_nop 0
	global_load_lds_dwordx4 v[148:149], off
	s_waitcnt vmcnt(6)
	s_barrier
	v_mfma_f32_16x16x32_bf16 v[54:57], v[204:207], v[172:175], v[54:57]
	v_mfma_f32_16x16x32_bf16 v[50:53], v[212:215], v[172:175], v[50:53]
	v_mfma_f32_16x16x32_bf16 v[38:41], v[204:207], v[180:183], v[38:41]
	v_mfma_f32_16x16x32_bf16 v[34:37], v[212:215], v[180:183], v[34:37]
	v_mfma_f32_16x16x32_bf16 v[22:25], v[204:207], v[188:191], v[22:25]
	v_mfma_f32_16x16x32_bf16 v[18:21], v[212:215], v[188:191], v[18:21]
	v_mfma_f32_16x16x32_bf16 v[6:9], v[204:207], v[196:199], v[6:9]
	v_mfma_f32_16x16x32_bf16 v[2:5], v[212:215], v[196:199], v[2:5]
	v_mfma_f32_16x16x32_bf16 v[54:57], v[208:211], v[176:179], v[54:57]
	v_mfma_f32_16x16x32_bf16 v[50:53], v[216:219], v[176:179], v[50:53]
	v_mfma_f32_16x16x32_bf16 v[38:41], v[208:211], v[184:187], v[38:41]
	v_mfma_f32_16x16x32_bf16 v[34:37], v[216:219], v[184:187], v[34:37]
	v_mfma_f32_16x16x32_bf16 v[22:25], v[208:211], v[192:195], v[22:25]
	v_mfma_f32_16x16x32_bf16 v[18:21], v[216:219], v[192:195], v[18:21]
	v_mfma_f32_16x16x32_bf16 v[6:9], v[208:211], v[200:203], v[6:9]
	v_mfma_f32_16x16x32_bf16 v[2:5], v[216:219], v[200:203], v[2:5]
	s_add_i32 s47, s47, 2
	s_add_u32 s18, s18, 0x100
	s_addc_u32 s19, s19, 0
	s_add_u32 s45, s45, 0x100
	s_addc_u32 s46, s46, 0
	s_cmp_gt_u32 s47, 5
	s_barrier
	s_cbranch_scc0 .LBB0_567
	v_lshl_add_u32 v148, s16, 8, v150
	v_ashrrev_i32_e32 v149, 31, v148
	v_lshlrev_b64 v[156:157], 6, v[148:149]
	v_lshl_add_u64 v[160:161], s[84:85], 0, v[156:157]
	v_add_co_u32_e32 v156, vcc, 0x5e00000, v160
	v_lshlrev_b64 v[166:167], 12, v[148:149]
	s_nop 0
	v_addc_co_u32_e32 v157, vcc, 0, v161, vcc
	global_load_dwordx4 v[156:159], v[156:157], off offset:32
	v_lshl_add_u64 v[160:161], v[160:161], 0, s[6:7]
	global_load_dwordx4 v[160:163], v[160:161], off offset:16
	s_lshl_b32 s18, s42, 8
	v_or_b32_e32 v164, 16, v148
	s_ashr_i32 s19, s18, 31
	v_ashrrev_i32_e32 v165, 31, v164
	s_lshl_b64 s[18:19], s[18:19], 1
	v_lshl_add_u64 v[166:167], s[4:5], 0, v[166:167]
	v_lshlrev_b64 v[168:169], 6, v[164:165]
	v_lshl_add_u64 v[166:167], v[166:167], 0, s[18:19]
	v_lshl_add_u64 v[168:169], s[84:85], 0, v[168:169]
	v_lshl_add_u64 v[166:167], v[166:167], 0, v[138:139]
	s_mov_b32 s42, s8
	s_mov_b32 s16, s10
	s_mov_b64 s[20:21], s[14:15]
	s_mov_b64 s[22:23], s[12:13]
	s_waitcnt vmcnt(0)
	v_mov_b32_e32 v170, v157
	v_mov_b32_e32 v171, v158
	v_mov_b32_e32 v157, v159
	v_mov_b32_e32 v158, v162
	v_mov_b32_e32 v159, v160
	v_mov_b32_e32 v160, v163
	v_pk_add_f32 v[156:157], v[170:171], v[156:157]
	v_pk_add_f32 v[158:159], v[158:159], v[160:161]
	v_add_f32_e32 v149, v156, v157
	v_add_f32_e32 v149, v149, v159
	v_add_f32_e32 v149, v158, v149
	v_fmamk_f32 v149, v149, 0x3b000000, v154
	v_rsq_f32_e32 v156, v149
	v_add_co_u32_e32 v158, vcc, s41, v168
	v_pk_mul_f32 v[128:129], v[128:129], v[156:157] op_sel_hi:[1,0]
	v_pk_mul_f32 v[126:127], v[126:127], v[156:157] op_sel_hi:[1,0]
	v_pk_mul_f32 v[124:125], v[124:125], v[156:157] op_sel_hi:[1,0]
	v_pk_mul_f32 v[122:123], v[122:123], v[156:157] op_sel_hi:[1,0]
	v_pk_mul_f32 v[120:121], v[120:121], v[156:157] op_sel_hi:[1,0]
	v_pk_mul_f32 v[118:119], v[118:119], v[156:157] op_sel_hi:[1,0]
	v_pk_mul_f32 v[160:161], v[116:117], v[156:157] op_sel_hi:[1,0]
	v_pk_mul_f32 v[156:157], v[114:115], v[156:157] op_sel_hi:[1,0]
	v_cvt_pk_bf16_f32 v114, v126, v127
	v_cvt_pk_bf16_f32 v115, v128, v129
	v_cvt_pk_bf16_f32 v116, v122, v123
	v_cvt_pk_bf16_f32 v117, v124, v125
	v_addc_co_u32_e32 v159, vcc, 0, v169, vcc
	v_cvt_pk_bf16_f32 v118, v118, v119
	v_cvt_pk_bf16_f32 v119, v120, v121
	v_cvt_pk_bf16_f32 v120, v156, v157
	v_cvt_pk_bf16_f32 v121, v160, v161
	global_store_dwordx4 v[166:167], v[114:117], off
	global_store_dwordx4 v[166:167], v[118:121], off offset:256
	global_load_dwordx4 v[114:117], v[158:159], off offset:32
	v_or_b32_e32 v122, 32, v148
	v_lshl_add_u64 v[118:119], v[168:169], 0, s[6:7]
	global_load_dwordx4 v[118:121], v[118:119], off offset:16
	v_ashrrev_i32_e32 v123, 31, v122
	v_lshlrev_b64 v[124:125], 12, v[164:165]
	v_lshlrev_b64 v[126:127], 6, v[122:123]
	v_lshl_add_u64 v[124:125], s[4:5], 0, v[124:125]
	v_lshl_add_u64 v[126:127], s[84:85], 0, v[126:127]
	v_lshl_add_u64 v[124:125], v[124:125], 0, s[18:19]
	s_waitcnt vmcnt(0)
;   DI void operator()(const f32x4 (&acc)[2][2][4][2], const pg8::Unit& u, int wr, int wc, int fr, int fq) const {
;     ...
;         if (MODE == EP_IN) rs = ((const float*)(ws + OFF_RS0))[grow];
;         if (MODE == EP_UP) rs = ((const float*)(ws + OFF_RS2))[grow];
;         if (MODE == EP_Q || MODE == EP_KV) {
;           const f32x4* sp = (const f32x4*)(ws + OFF_SSQA) + (size_t)grow * 4 + (MODE == EP_KV ? 2 : 0);
;           const f32x4 s0 = sp[0], s1 = sp[1];
;           const float ss = (s0[0] + s0[1]) + (s0[2] + s0[3]) + (s1[0] + s1[1]) + (s1[2] + s1[3]);
;           rs = __builtin_amdgcn_rsqf(ss * (1.0f / 512) + EPS);
;           if (MODE == EP_Q) rs *= QSCALE;
;         }
;         float ssq = 0.f;
; #pragma unroll
;         for (int bj = 0; bj < 2; ++bj) {
;           f32x4 v0 = acc[ai][bj][m][0] * rs, v1 = acc[ai][bj][m][1] * rs;
;           if (MODE == EP_IN || MODE == EP_MIX || MODE == EP_DOWN) {
; #pragma unroll
;             for (int j = 0; j < 4; ++j) ssq += v0[j] * v0[j] + v1[j] * v1[j];
;           }
;           if (MODE == EP_UP) {
; #pragma unroll
;             for (int j = 0; j < 4; ++j) { float a = fmaxf(v0[j], 0.f), b = fmaxf(v1[j], 0.f); v0[j] = a * a; v1[j] = b * b; }
;           }
;           bf16_t* dst;
;           const int ct = bj * 128 + cl;
;           if (MODE == EP_IN) {
;             if (pn < 4) dst = (bf16_t*)(ws + OFF_PROJA) + (size_t)grow * 1024 + pn * 256 + ct;
;             else if (pn < 16) dst = (bf16_t*)(ws + OFF_PROJG) + (size_t)grow * 3072 + (pn - 4) * 256 + ct;
;             else dst = (bf16_t*)(ws + OFF_PROJS) + (size_t)grow * 256 + ct;
;           } else if (MODE == EP_Q) {
;             if (pn < 4) dst = (bf16_t*)(dout + DO_Q) + (size_t)grow * 1536 + (pn * 2 + bj) * 192 + cl;
;             else {
;               const int mm = (pn - 4) * 256 + ct, h = mm >> 6, r = mm & 63;
;               dst = (bf16_t*)(dout + DO_Q) + (size_t)grow * 1536 + h * 192 + 128 + r;
;               const int pos = grow < TP ? (grow & 4095) : grow - TP;
;               const f32x4* tb = (const f32x4*)((const f32x2*)(ws + OFF_ROPE) + pos * 32 + (r >> 1));
;               const f32x4 t0 = tb[0], t1 = tb[1];
;               f32x4 o0, o1;
;               o0[0] = v0[0] * t0[0] - v0[1] * t0[1]; o0[1] = v0[1] * t0[0] + v0[0] * t0[1];
;               o0[2] = v0[2] * t0[2] - v0[3] * t0[3]; o0[3] = v0[3] * t0[2] + v0[2] * t0[3];
	v_mov_b32_e32 v128, v115
	v_mov_b32_e32 v129, v116
	v_mov_b32_e32 v115, v117
	v_mov_b32_e32 v116, v120
	v_mov_b32_e32 v117, v118
	v_mov_b32_e32 v118, v121
	v_pk_add_f32 v[114:115], v[128:129], v[114:115]
	v_pk_add_f32 v[116:117], v[116:117], v[118:119]
	v_add_f32_e32 v114, v114, v115
	v_add_f32_e32 v114, v114, v117
	v_add_f32_e32 v114, v116, v114
	v_fmamk_f32 v114, v114, 0x3b000000, v154
	v_rsq_f32_e32 v114, v114
	v_add_co_u32_e32 v116, vcc, s41, v126
	v_lshl_add_u64 v[118:119], v[124:125], 0, v[138:139]
	v_pk_mul_f32 v[112:113], v[112:113], v[114:115] op_sel_hi:[1,0]
	v_pk_mul_f32 v[110:111], v[110:111], v[114:115] op_sel_hi:[1,0]
	v_pk_mul_f32 v[108:109], v[108:109], v[114:115] op_sel_hi:[1,0]
	v_pk_mul_f32 v[106:107], v[106:107], v[114:115] op_sel_hi:[1,0]
	v_pk_mul_f32 v[104:105], v[104:105], v[114:115] op_sel_hi:[1,0]
	v_pk_mul_f32 v[102:103], v[102:103], v[114:115] op_sel_hi:[1,0]
	v_pk_mul_f32 v[120:121], v[100:101], v[114:115] op_sel_hi:[1,0]
	v_pk_mul_f32 v[114:115], v[98:99], v[114:115] op_sel_hi:[1,0]
	v_cvt_pk_bf16_f32 v98, v110, v111
	v_cvt_pk_bf16_f32 v99, v112, v113
	v_cvt_pk_bf16_f32 v100, v106, v107
	v_cvt_pk_bf16_f32 v101, v108, v109
	v_addc_co_u32_e32 v117, vcc, 0, v127, vcc
	v_cvt_pk_bf16_f32 v102, v102, v103
	v_cvt_pk_bf16_f32 v103, v104, v105
	v_cvt_pk_bf16_f32 v104, v114, v115
	v_cvt_pk_bf16_f32 v105, v120, v121
	global_store_dwordx4 v[118:119], v[98:101], off
	global_store_dwordx4 v[118:119], v[102:105], off offset:256
	global_load_dwordx4 v[98:101], v[116:117], off offset:32
	v_or_b32_e32 v106, 48, v148
	v_lshl_add_u64 v[102:103], v[126:127], 0, s[6:7]
	global_load_dwordx4 v[102:105], v[102:103], off offset:16
	v_ashrrev_i32_e32 v107, 31, v106
	v_lshlrev_b64 v[108:109], 12, v[122:123]
	v_lshlrev_b64 v[110:111], 6, v[106:107]
	v_lshl_add_u64 v[108:109], s[4:5], 0, v[108:109]
	v_lshl_add_u64 v[110:111], s[84:85], 0, v[110:111]
	v_lshl_add_u64 v[108:109], v[108:109], 0, s[18:19]
	s_waitcnt vmcnt(0)
	v_mov_b32_e32 v112, v99
	v_mov_b32_e32 v113, v100
	v_mov_b32_e32 v99, v101
	v_mov_b32_e32 v100, v104
	v_mov_b32_e32 v101, v102
	v_mov_b32_e32 v102, v105
	v_pk_add_f32 v[98:99], v[112:113], v[98:99]
	v_pk_add_f32 v[100:101], v[100:101], v[102:103]
	v_add_f32_e32 v98, v98, v99
	v_add_f32_e32 v98, v98, v101
	v_add_f32_e32 v98, v100, v98
	v_fmamk_f32 v98, v98, 0x3b000000, v154
	v_rsq_f32_e32 v98, v98
	v_add_co_u32_e32 v100, vcc, s41, v110
	v_lshl_add_u64 v[102:103], v[108:109], 0, v[138:139]
	v_pk_mul_f32 v[96:97], v[96:97], v[98:99] op_sel_hi:[1,0]
	v_pk_mul_f32 v[94:95], v[94:95], v[98:99] op_sel_hi:[1,0]
	v_pk_mul_f32 v[92:93], v[92:93], v[98:99] op_sel_hi:[1,0]
	v_pk_mul_f32 v[90:91], v[90:91], v[98:99] op_sel_hi:[1,0]
	v_pk_mul_f32 v[88:89], v[88:89], v[98:99] op_sel_hi:[1,0]
	v_pk_mul_f32 v[86:87], v[86:87], v[98:99] op_sel_hi:[1,0]
	v_pk_mul_f32 v[104:105], v[84:85], v[98:99] op_sel_hi:[1,0]
	v_pk_mul_f32 v[98:99], v[82:83], v[98:99] op_sel_hi:[1,0]
	v_cvt_pk_bf16_f32 v82, v94, v95
	v_cvt_pk_bf16_f32 v83, v96, v97
	v_cvt_pk_bf16_f32 v84, v90, v91
	v_cvt_pk_bf16_f32 v85, v92, v93
	v_addc_co_u32_e32 v101, vcc, 0, v111, vcc
	v_cvt_pk_bf16_f32 v86, v86, v87
	v_cvt_pk_bf16_f32 v87, v88, v89
	v_cvt_pk_bf16_f32 v88, v98, v99
	v_cvt_pk_bf16_f32 v89, v104, v105
	global_store_dwordx4 v[102:103], v[82:85], off
	global_store_dwordx4 v[102:103], v[86:89], off offset:256
	global_load_dwordx4 v[82:85], v[100:101], off offset:32
	v_add_u32_e32 v90, 0x80, v148
	v_lshl_add_u64 v[86:87], v[110:111], 0, s[6:7]
	global_load_dwordx4 v[86:89], v[86:87], off offset:16
	v_ashrrev_i32_e32 v91, 31, v90
	v_lshlrev_b64 v[92:93], 12, v[106:107]
	v_lshlrev_b64 v[94:95], 6, v[90:91]
	v_lshl_add_u64 v[92:93], s[4:5], 0, v[92:93]
	v_lshl_add_u64 v[94:95], s[84:85], 0, v[94:95]
	v_lshl_add_u64 v[92:93], v[92:93], 0, s[18:19]
	s_waitcnt vmcnt(0)
	v_mov_b32_e32 v96, v83
	v_mov_b32_e32 v97, v84
	v_mov_b32_e32 v83, v85
	v_mov_b32_e32 v84, v88
	v_mov_b32_e32 v85, v86
	v_mov_b32_e32 v86, v89
	v_pk_add_f32 v[82:83], v[96:97], v[82:83]
	v_pk_add_f32 v[84:85], v[84:85], v[86:87]
	v_add_f32_e32 v82, v82, v83
	v_add_f32_e32 v82, v82, v85
	v_add_f32_e32 v82, v84, v82
	v_fmamk_f32 v82, v82, 0x3b000000, v154
	v_rsq_f32_e32 v82, v82
	v_add_co_u32_e32 v84, vcc, s41, v94
	v_lshl_add_u64 v[86:87], v[92:93], 0, v[138:139]
	v_pk_mul_f32 v[80:81], v[80:81], v[82:83] op_sel_hi:[1,0]
	v_pk_mul_f32 v[78:79], v[78:79], v[82:83] op_sel_hi:[1,0]
	v_pk_mul_f32 v[76:77], v[76:77], v[82:83] op_sel_hi:[1,0]
	v_pk_mul_f32 v[74:75], v[74:75], v[82:83] op_sel_hi:[1,0]
	v_pk_mul_f32 v[72:73], v[72:73], v[82:83] op_sel_hi:[1,0]
	v_pk_mul_f32 v[70:71], v[70:71], v[82:83] op_sel_hi:[1,0]
	v_pk_mul_f32 v[88:89], v[68:69], v[82:83] op_sel_hi:[1,0]
	v_pk_mul_f32 v[82:83], v[66:67], v[82:83] op_sel_hi:[1,0]
	v_cvt_pk_bf16_f32 v66, v78, v79
	v_cvt_pk_bf16_f32 v67, v80, v81
	v_cvt_pk_bf16_f32 v68, v74, v75
	v_cvt_pk_bf16_f32 v69, v76, v77
	v_addc_co_u32_e32 v85, vcc, 0, v95, vcc
	v_cvt_pk_bf16_f32 v70, v70, v71
	v_cvt_pk_bf16_f32 v71, v72, v73
	v_cvt_pk_bf16_f32 v72, v82, v83
	v_cvt_pk_bf16_f32 v73, v88, v89
	global_store_dwordx4 v[86:87], v[66:69], off
	global_store_dwordx4 v[86:87], v[70:73], off offset:256
	global_load_dwordx4 v[66:69], v[84:85], off offset:32
	v_add_u32_e32 v74, 0x90, v148
	v_lshl_add_u64 v[70:71], v[94:95], 0, s[6:7]
	global_load_dwordx4 v[70:73], v[70:71], off offset:16
	v_ashrrev_i32_e32 v75, 31, v74
	v_lshlrev_b64 v[76:77], 12, v[90:91]
	v_lshlrev_b64 v[78:79], 6, v[74:75]
	v_lshl_add_u64 v[76:77], s[4:5], 0, v[76:77]
	v_lshl_add_u64 v[78:79], s[84:85], 0, v[78:79]
	v_lshl_add_u64 v[76:77], v[76:77], 0, s[18:19]
	s_waitcnt vmcnt(0)
;   DI void operator()(const f32x4 (&acc)[2][2][4][2], const pg8::Unit& u, int wr, int wc, int fr, int fq) const {
;     ...
;         if (MODE == EP_IN) rs = ((const float*)(ws + OFF_RS0))[grow];
;         if (MODE == EP_UP) rs = ((const float*)(ws + OFF_RS2))[grow];
;         if (MODE == EP_Q || MODE == EP_KV) {
;           const f32x4* sp = (const f32x4*)(ws + OFF_SSQA) + (size_t)grow * 4 + (MODE == EP_KV ? 2 : 0);
;           const f32x4 s0 = sp[0], s1 = sp[1];
;           const float ss = (s0[0] + s0[1]) + (s0[2] + s0[3]) + (s1[0] + s1[1]) + (s1[2] + s1[3]);
;           rs = __builtin_amdgcn_rsqf(ss * (1.0f / 512) + EPS);
;           if (MODE == EP_Q) rs *= QSCALE;
;         }
;         float ssq = 0.f;
; #pragma unroll
;         for (int bj = 0; bj < 2; ++bj) {
;           f32x4 v0 = acc[ai][bj][m][0] * rs, v1 = acc[ai][bj][m][1] * rs;
;           if (MODE == EP_IN || MODE == EP_MIX || MODE == EP_DOWN) {
; #pragma unroll
;             for (int j = 0; j < 4; ++j) ssq += v0[j] * v0[j] + v1[j] * v1[j];
;           }
;           if (MODE == EP_UP) {
; #pragma unroll
;             for (int j = 0; j < 4; ++j) { float a = fmaxf(v0[j], 0.f), b = fmaxf(v1[j], 0.f); v0[j] = a * a; v1[j] = b * b; }
;           }
;           bf16_t* dst;
;           const int ct = bj * 128 + cl;
;           if (MODE == EP_IN) {
;             if (pn < 4) dst = (bf16_t*)(ws + OFF_PROJA) + (size_t)grow * 1024 + pn * 256 + ct;
;             else if (pn < 16) dst = (bf16_t*)(ws + OFF_PROJG) + (size_t)grow * 3072 + (pn - 4) * 256 + ct;
;             else dst = (bf16_t*)(ws + OFF_PROJS) + (size_t)grow * 256 + ct;
;           } else if (MODE == EP_Q) {
;             if (pn < 4) dst = (bf16_t*)(dout + DO_Q) + (size_t)grow * 1536 + (pn * 2 + bj) * 192 + cl;
;             else {
;               const int mm = (pn - 4) * 256 + ct, h = mm >> 6, r = mm & 63;
;               dst = (bf16_t*)(dout + DO_Q) + (size_t)grow * 1536 + h * 192 + 128 + r;
;               const int pos = grow < TP ? (grow & 4095) : grow - TP;
;               const f32x4* tb = (const f32x4*)((const f32x2*)(ws + OFF_ROPE) + pos * 32 + (r >> 1));
;               const f32x4 t0 = tb[0], t1 = tb[1];
;               f32x4 o0, o1;
;               o0[0] = v0[0] * t0[0] - v0[1] * t0[1]; o0[1] = v0[1] * t0[0] + v0[0] * t0[1];
;               o0[2] = v0[2] * t0[2] - v0[3] * t0[3]; o0[3] = v0[3] * t0[2] + v0[2] * t0[3];
	v_mov_b32_e32 v80, v67
	v_mov_b32_e32 v81, v68
	v_mov_b32_e32 v67, v69
	v_mov_b32_e32 v68, v72
	v_mov_b32_e32 v69, v70
	v_mov_b32_e32 v70, v73
	v_pk_add_f32 v[66:67], v[80:81], v[66:67]
	v_pk_add_f32 v[68:69], v[68:69], v[70:71]
	v_add_f32_e32 v66, v66, v67
	v_add_f32_e32 v66, v66, v69
	v_add_f32_e32 v66, v68, v66
	v_fmamk_f32 v66, v66, 0x3b000000, v154
	v_rsq_f32_e32 v66, v66
	v_add_co_u32_e32 v68, vcc, s41, v78
	v_lshl_add_u64 v[70:71], v[76:77], 0, v[138:139]
	v_pk_mul_f32 v[64:65], v[64:65], v[66:67] op_sel_hi:[1,0]
	v_pk_mul_f32 v[62:63], v[62:63], v[66:67] op_sel_hi:[1,0]
	v_pk_mul_f32 v[60:61], v[60:61], v[66:67] op_sel_hi:[1,0]
	v_pk_mul_f32 v[58:59], v[58:59], v[66:67] op_sel_hi:[1,0]
	v_pk_mul_f32 v[56:57], v[56:57], v[66:67] op_sel_hi:[1,0]
	v_pk_mul_f32 v[54:55], v[54:55], v[66:67] op_sel_hi:[1,0]
	v_pk_mul_f32 v[72:73], v[52:53], v[66:67] op_sel_hi:[1,0]
	v_pk_mul_f32 v[66:67], v[50:51], v[66:67] op_sel_hi:[1,0]
	v_cvt_pk_bf16_f32 v50, v62, v63
	v_cvt_pk_bf16_f32 v51, v64, v65
	v_cvt_pk_bf16_f32 v52, v58, v59
	v_cvt_pk_bf16_f32 v53, v60, v61
	v_addc_co_u32_e32 v69, vcc, 0, v79, vcc
	v_cvt_pk_bf16_f32 v54, v54, v55
	v_cvt_pk_bf16_f32 v55, v56, v57
	v_cvt_pk_bf16_f32 v56, v66, v67
	v_cvt_pk_bf16_f32 v57, v72, v73
	global_store_dwordx4 v[70:71], v[50:53], off
	global_store_dwordx4 v[70:71], v[54:57], off offset:256
	global_load_dwordx4 v[50:53], v[68:69], off offset:32
	v_add_u32_e32 v58, 0xa0, v148
	v_lshl_add_u64 v[54:55], v[78:79], 0, s[6:7]
	global_load_dwordx4 v[54:57], v[54:55], off offset:16
	v_ashrrev_i32_e32 v59, 31, v58
	v_lshlrev_b64 v[60:61], 12, v[74:75]
	v_lshlrev_b64 v[62:63], 6, v[58:59]
	v_lshl_add_u64 v[60:61], s[4:5], 0, v[60:61]
	v_lshl_add_u64 v[62:63], s[84:85], 0, v[62:63]
	v_lshl_add_u64 v[60:61], v[60:61], 0, s[18:19]
	s_waitcnt vmcnt(0)
	v_mov_b32_e32 v64, v51
	v_mov_b32_e32 v65, v52
	v_mov_b32_e32 v51, v53
	v_mov_b32_e32 v52, v56
	v_mov_b32_e32 v53, v54
	v_mov_b32_e32 v54, v57
	v_pk_add_f32 v[50:51], v[64:65], v[50:51]
	v_pk_add_f32 v[52:53], v[52:53], v[54:55]
	v_add_f32_e32 v50, v50, v51
	v_add_f32_e32 v50, v50, v53
	v_add_f32_e32 v50, v52, v50
	v_fmamk_f32 v50, v50, 0x3b000000, v154
	v_rsq_f32_e32 v50, v50
	v_add_co_u32_e32 v52, vcc, s41, v62
	v_lshl_add_u64 v[54:55], v[60:61], 0, v[138:139]
	v_pk_mul_f32 v[48:49], v[48:49], v[50:51] op_sel_hi:[1,0]
	v_pk_mul_f32 v[46:47], v[46:47], v[50:51] op_sel_hi:[1,0]
	v_pk_mul_f32 v[44:45], v[44:45], v[50:51] op_sel_hi:[1,0]
	v_pk_mul_f32 v[42:43], v[42:43], v[50:51] op_sel_hi:[1,0]
	v_pk_mul_f32 v[40:41], v[40:41], v[50:51] op_sel_hi:[1,0]
	v_pk_mul_f32 v[38:39], v[38:39], v[50:51] op_sel_hi:[1,0]
	v_pk_mul_f32 v[56:57], v[36:37], v[50:51] op_sel_hi:[1,0]
	v_pk_mul_f32 v[50:51], v[34:35], v[50:51] op_sel_hi:[1,0]
	v_cvt_pk_bf16_f32 v34, v46, v47
	v_cvt_pk_bf16_f32 v35, v48, v49
	v_cvt_pk_bf16_f32 v36, v42, v43
	v_cvt_pk_bf16_f32 v37, v44, v45
	v_addc_co_u32_e32 v53, vcc, 0, v63, vcc
	v_cvt_pk_bf16_f32 v38, v38, v39
	v_cvt_pk_bf16_f32 v39, v40, v41
	v_cvt_pk_bf16_f32 v40, v50, v51
	v_cvt_pk_bf16_f32 v41, v56, v57
	global_store_dwordx4 v[54:55], v[34:37], off
	global_store_dwordx4 v[54:55], v[38:41], off offset:256
	global_load_dwordx4 v[34:37], v[52:53], off offset:32
	v_add_u32_e32 v42, 0xb0, v148
	v_lshl_add_u64 v[38:39], v[62:63], 0, s[6:7]
	global_load_dwordx4 v[38:41], v[38:39], off offset:16
	v_ashrrev_i32_e32 v43, 31, v42
	v_lshlrev_b64 v[44:45], 12, v[58:59]
	v_lshlrev_b64 v[46:47], 6, v[42:43]
	v_lshl_add_u64 v[44:45], s[4:5], 0, v[44:45]
	v_lshl_add_u64 v[46:47], s[84:85], 0, v[46:47]
	v_lshl_add_u64 v[44:45], v[44:45], 0, s[18:19]
	s_waitcnt vmcnt(0)
	v_mov_b32_e32 v48, v35
	v_mov_b32_e32 v49, v36
	v_mov_b32_e32 v35, v37
	v_mov_b32_e32 v36, v40
	v_mov_b32_e32 v37, v38
	v_mov_b32_e32 v38, v41
	v_pk_add_f32 v[34:35], v[48:49], v[34:35]
	v_pk_add_f32 v[36:37], v[36:37], v[38:39]
	v_add_f32_e32 v34, v34, v35
	v_add_f32_e32 v34, v34, v37
	v_add_f32_e32 v34, v36, v34
	v_fmamk_f32 v34, v34, 0x3b000000, v154
	v_rsq_f32_e32 v34, v34
	v_add_co_u32_e32 v36, vcc, s41, v46
	v_lshl_add_u64 v[38:39], v[44:45], 0, v[138:139]
	v_pk_mul_f32 v[32:33], v[32:33], v[34:35] op_sel_hi:[1,0]
	v_pk_mul_f32 v[30:31], v[30:31], v[34:35] op_sel_hi:[1,0]
	v_pk_mul_f32 v[28:29], v[28:29], v[34:35] op_sel_hi:[1,0]
	v_pk_mul_f32 v[26:27], v[26:27], v[34:35] op_sel_hi:[1,0]
	v_pk_mul_f32 v[24:25], v[24:25], v[34:35] op_sel_hi:[1,0]
	v_pk_mul_f32 v[22:23], v[22:23], v[34:35] op_sel_hi:[1,0]
	v_pk_mul_f32 v[40:41], v[20:21], v[34:35] op_sel_hi:[1,0]
	v_pk_mul_f32 v[34:35], v[18:19], v[34:35] op_sel_hi:[1,0]
	v_cvt_pk_bf16_f32 v18, v30, v31
	v_cvt_pk_bf16_f32 v19, v32, v33
	v_cvt_pk_bf16_f32 v20, v26, v27
	v_cvt_pk_bf16_f32 v21, v28, v29
	v_addc_co_u32_e32 v37, vcc, 0, v47, vcc
	v_cvt_pk_bf16_f32 v22, v22, v23
	v_cvt_pk_bf16_f32 v23, v24, v25
	v_cvt_pk_bf16_f32 v24, v34, v35
	v_cvt_pk_bf16_f32 v25, v40, v41
	global_store_dwordx4 v[38:39], v[18:21], off
	global_store_dwordx4 v[38:39], v[22:25], off offset:256
	global_load_dwordx4 v[18:21], v[36:37], off offset:32
	v_lshlrev_b64 v[26:27], 12, v[42:43]
	v_lshl_add_u64 v[22:23], v[46:47], 0, s[6:7]
	global_load_dwordx4 v[22:25], v[22:23], off offset:16
	s_and_b64 vcc, exec, s[0:1]
	s_waitcnt vmcnt(0)
	v_mov_b32_e32 v28, v19
	v_mov_b32_e32 v29, v20
	v_mov_b32_e32 v19, v21
	v_mov_b32_e32 v20, v24
	v_mov_b32_e32 v21, v22
	v_mov_b32_e32 v22, v25
	v_pk_add_f32 v[18:19], v[28:29], v[18:19]
	v_pk_add_f32 v[20:21], v[20:21], v[22:23]
	v_add_f32_e32 v18, v18, v19
	v_add_f32_e32 v18, v18, v21
	v_add_f32_e32 v18, v20, v18
	v_fmamk_f32 v18, v18, 0x3b000000, v154
	v_rsq_f32_e32 v18, v18
	v_lshl_add_u64 v[20:21], s[4:5], 0, v[26:27]
	v_lshl_add_u64 v[20:21], v[20:21], 0, s[18:19]
	v_lshl_add_u64 v[20:21], v[20:21], 0, v[138:139]
	v_pk_mul_f32 v[16:17], v[16:17], v[18:19] op_sel_hi:[1,0]
	v_pk_mul_f32 v[14:15], v[14:15], v[18:19] op_sel_hi:[1,0]
	v_pk_mul_f32 v[12:13], v[12:13], v[18:19] op_sel_hi:[1,0]
	v_pk_mul_f32 v[10:11], v[10:11], v[18:19] op_sel_hi:[1,0]
	v_pk_mul_f32 v[8:9], v[8:9], v[18:19] op_sel_hi:[1,0]
	v_pk_mul_f32 v[6:7], v[6:7], v[18:19] op_sel_hi:[1,0]
	v_pk_mul_f32 v[22:23], v[4:5], v[18:19] op_sel_hi:[1,0]
	v_pk_mul_f32 v[18:19], v[2:3], v[18:19] op_sel_hi:[1,0]
	v_cvt_pk_bf16_f32 v2, v14, v15
	v_cvt_pk_bf16_f32 v3, v16, v17
	v_cvt_pk_bf16_f32 v4, v10, v11
	v_cvt_pk_bf16_f32 v5, v12, v13
	v_cvt_pk_bf16_f32 v6, v6, v7
	v_cvt_pk_bf16_f32 v7, v8, v9
	v_cvt_pk_bf16_f32 v8, v18, v19
	v_cvt_pk_bf16_f32 v9, v22, v23
	global_store_dwordx4 v[20:21], v[2:5], off
	global_store_dwordx4 v[20:21], v[6:9], off offset:256
	s_cbranch_vccz .LBB0_560
	s_waitcnt vmcnt(0)
	s_cmpk_gt_u32 s24, 0xff
	s_cbranch_scc1 .LBB0_571
	s_barrier

; #define PG8_STAGE(bufoff, gbase, voff) do { _Pragma("unroll") for (int _i = 0; _i < 2; ++_i) \
;     __builtin_amdgcn_global_load_lds((const unsigned*)((const char*)(gbase) + (voff)[_i]), (LAS unsigned*)(lds + (bufoff) + ldsw + _i * 8192), 16, 0, 0); } while (0)
; #define PG8_LDA(dst, b, h) do { _Pragma("unroll") for (int m = 0; m < 4; ++m) _Pragma("unroll") for (int k = 0; k < 2; ++k) dst[m][k] = *(const LAS bf16x8*)(lds + PG8_SA(b, h) + aoff + m * 2048 + k * 1024); } while (0)
; #define PG8_LDB(dst, b, h) do { _Pragma("unroll") for (int n = 0; n < 2; ++n) _Pragma("unroll") for (int k = 0; k < 2; ++k) dst[n][k] = *(const LAS bf16x8*)(lds + PG8_SB(b, h) + boff + n * 2048 + k * 1024); } while (0)
; #define PG8_MMA(ai, bj, At, Bt) do { __builtin_amdgcn_s_setprio(1); _Pragma("unroll") for (int m = 0; m < 4; ++m) _Pragma("unroll") for (int n = 0; n < 2; ++n) _Pragma("unroll") for (int k = 0; k < 2; ++k) \
;     acc[ai][bj][m][n] = __builtin_amdgcn_mfma_f32_16x16x32_bf16(Bt[n][k], At[m][k], acc[ai][bj][m][n], 0, 0, 0); __builtin_amdgcn_s_setprio(0); } while (0)
; #define PG8_WAIT_L(n) asm volatile("s_waitcnt lgkmcnt(" #n ")" ::: "memory")
; #define PG8_BAR __builtin_amdgcn_s_barrier()
; #define PG8_SCHED __builtin_amdgcn_sched_barrier(0)
; template <class Epi>
; DI void gemm_phase(LAS unsigned char* lds, const Gemm g, const StaticOrder& S, const Epi& E) {
;     ...
;     for (int t = 0; t < nt; t += 2) {
;       const bool last = (t == nt - 2);
;       const char* a1 = cA + PG8_AK(t + 1);
;       const char* a2 = last ? nA : cA + PG8_AK(t + 2); const char* b2 = last ? nB : cB + (size_t)(t + 2) * kstep;
;       const char* a3 = a2 + kstep; const char* b3 = b2 + kstep;
;       PG8_LDB(B0, 0, 0); PG8_SCHED; PG8_LDA(At, 0, 0); PG8_STAGE(PG8_SA(1, 1), a1 + hstepA, voffA);
;       PG8_WAIT_L(8); PG8_BAR; PG8_WAIT_L(0); PG8_MMA(0, 0, At, B0); PG8_BAR; PG8_SCHED;
;       PG8_LDB(B1, 0, 1); PG8_STAGE(PG8_SB(0, 0), b2, voffB);
;       PG8_BAR; PG8_WAIT_L(0); PG8_MMA(0, 1, At, B1); PG8_BAR;
;       PG8_LDA(At, 0, 1); PG8_STAGE(PG8_SA(0, 0), a2, voffA);
;       PG8_BAR; PG8_WAIT_L(0); PG8_MMA(1, 0, At, B0); PG8_BAR; PG8_SCHED;
.LBB0_840:
	s_add_i32 s52, s24, 2
	s_cmp_gt_u32 s52, 15
	s_cselect_b32 s54, s39, 0
	s_cselect_b32 s55, s40, 0
	s_cmp_gt_u32 s52, 13
	s_cselect_b32 s26, s39, 0
	ds_read_b128 v[156:159], v151
	ds_read_b128 v[160:163], v151 offset:1024
	ds_read_b128 v[164:167], v151 offset:2048
	ds_read_b128 v[168:171], v151 offset:3072
	s_cselect_b32 s25, s40, 0
	s_add_u32 s26, s22, s26
	s_addc_u32 s25, s23, s25
	s_add_u32 s26, s26, 0xfffc0080
	s_addc_u32 s25, s25, -1
	s_cmp_eq_u32 s24, 28
	s_cselect_b32 s24, s49, s50
	s_cselect_b32 s27, s15, s25
	s_cselect_b32 s26, s21, s26
	s_cselect_b32 s25, s13, s51
	v_lshl_add_u64 v[148:149], s[22:23], 0, v[140:141]
	v_lshl_add_u64 v[148:149], v[148:149], 0, s[54:55]
	s_add_i32 m0, s35, 0xc000
	ds_read_b128 v[172:175], v152
	ds_read_b128 v[176:179], v152 offset:1024
	ds_read_b128 v[180:183], v152 offset:2048
	ds_read_b128 v[184:187], v152 offset:3072
	ds_read_b128 v[188:191], v152 offset:4096
	ds_read_b128 v[192:195], v152 offset:5120
	ds_read_b128 v[196:199], v152 offset:6144
	ds_read_b128 v[200:203], v152 offset:7168
	global_load_lds_dwordx4 v[148:149], off
	v_lshl_add_u64 v[148:149], s[22:23], 0, v[142:143]
	v_lshl_add_u64 v[148:149], v[148:149], 0, s[54:55]
	s_add_i32 m0, s35, 0xe000
	s_nop 0
	global_load_lds_dwordx4 v[148:149], off
	s_waitcnt lgkmcnt(8)
	s_barrier
	s_waitcnt lgkmcnt(0)
	v_mfma_f32_16x16x32_bf16 v[126:129], v[156:159], v[172:175], v[126:129]
	v_mfma_f32_16x16x32_bf16 v[122:125], v[164:167], v[172:175], v[122:125]
	v_mfma_f32_16x16x32_bf16 v[110:113], v[156:159], v[180:183], v[110:113]
	v_mfma_f32_16x16x32_bf16 v[106:109], v[164:167], v[180:183], v[106:109]
	v_mfma_f32_16x16x32_bf16 v[94:97], v[156:159], v[188:191], v[94:97]
	v_mfma_f32_16x16x32_bf16 v[90:93], v[164:167], v[188:191], v[90:93]
	v_mfma_f32_16x16x32_bf16 v[78:81], v[156:159], v[196:199], v[78:81]
	v_mfma_f32_16x16x32_bf16 v[74:77], v[164:167], v[196:199], v[74:77]
	v_mfma_f32_16x16x32_bf16 v[126:129], v[160:163], v[176:179], v[126:129]
	v_mfma_f32_16x16x32_bf16 v[122:125], v[168:171], v[176:179], v[122:125]
	v_mfma_f32_16x16x32_bf16 v[110:113], v[160:163], v[184:187], v[110:113]
	v_mfma_f32_16x16x32_bf16 v[106:109], v[168:171], v[184:187], v[106:109]
	v_mfma_f32_16x16x32_bf16 v[94:97], v[160:163], v[192:195], v[94:97]
	v_mfma_f32_16x16x32_bf16 v[90:93], v[168:171], v[192:195], v[90:93]
	v_mfma_f32_16x16x32_bf16 v[78:81], v[160:163], v[200:203], v[78:81]
	v_mfma_f32_16x16x32_bf16 v[74:77], v[168:171], v[200:203], v[74:77]
	s_barrier
	s_add_i32 s53, s46, s34
	v_lshl_add_u64 v[148:149], s[24:25], 0, v[132:133]
	s_mov_b32 m0, s53
	ds_read_b128 v[204:207], v153
	ds_read_b128 v[208:211], v153 offset:1024
	ds_read_b128 v[212:215], v153 offset:2048
	ds_read_b128 v[216:219], v153 offset:3072
	global_load_lds_dwordx4 v[148:149], off
	v_lshl_add_u64 v[220:221], s[24:25], 0, v[136:137]
	s_add_i32 m0, s53, 0x2000
	s_nop 0
	global_load_lds_dwordx4 v[220:221], off
	s_barrier
	s_waitcnt lgkmcnt(0)
	v_mfma_f32_16x16x32_bf16 v[118:121], v[204:207], v[172:175], v[118:121]
	v_mfma_f32_16x16x32_bf16 v[114:117], v[212:215], v[172:175], v[114:117]
	v_mfma_f32_16x16x32_bf16 v[102:105], v[204:207], v[180:183], v[102:105]
	v_mfma_f32_16x16x32_bf16 v[98:101], v[212:215], v[180:183], v[98:101]
	v_mfma_f32_16x16x32_bf16 v[86:89], v[204:207], v[188:191], v[86:89]
	v_mfma_f32_16x16x32_bf16 v[82:85], v[212:215], v[188:191], v[82:85]
	v_mfma_f32_16x16x32_bf16 v[70:73], v[204:207], v[196:199], v[70:73]
	v_mfma_f32_16x16x32_bf16 v[66:69], v[212:215], v[196:199], v[66:69]
	v_mfma_f32_16x16x32_bf16 v[118:121], v[208:211], v[176:179], v[118:121]
	v_mfma_f32_16x16x32_bf16 v[114:117], v[216:219], v[176:179], v[114:117]
	v_mfma_f32_16x16x32_bf16 v[102:105], v[208:211], v[184:187], v[102:105]
	v_mfma_f32_16x16x32_bf16 v[98:101], v[216:219], v[184:187], v[98:101]
	v_mfma_f32_16x16x32_bf16 v[86:89], v[208:211], v[192:195], v[86:89]
	v_mfma_f32_16x16x32_bf16 v[82:85], v[216:219], v[192:195], v[82:85]
	v_mfma_f32_16x16x32_bf16 v[70:73], v[208:211], v[200:203], v[70:73]
	v_mfma_f32_16x16x32_bf16 v[66:69], v[216:219], v[200:203], v[66:69]
	s_mov_b32 m0, s35
	v_lshl_add_u64 v[222:223], s[26:27], 0, v[130:131]
	s_barrier
	ds_read_b128 v[172:175], v152 offset:16384
	ds_read_b128 v[176:179], v152 offset:17408
	ds_read_b128 v[180:183], v152 offset:18432
	ds_read_b128 v[184:187], v152 offset:19456
	ds_read_b128 v[188:191], v152 offset:20480
	ds_read_b128 v[192:195], v152 offset:21504
	ds_read_b128 v[196:199], v152 offset:22528
	ds_read_b128 v[200:203], v152 offset:23552
	global_load_lds_dwordx4 v[222:223], off
	v_lshl_add_u64 v[224:225], s[26:27], 0, v[134:135]
	s_mov_b32 m0, s36
	s_nop 0
	global_load_lds_dwordx4 v[224:225], off
	s_barrier
	s_waitcnt lgkmcnt(0)
	v_mfma_f32_16x16x32_bf16 v[62:65], v[156:159], v[172:175], v[62:65]
	v_mfma_f32_16x16x32_bf16 v[58:61], v[164:167], v[172:175], v[58:61]
	v_mfma_f32_16x16x32_bf16 v[46:49], v[156:159], v[180:183], v[46:49]
	v_mfma_f32_16x16x32_bf16 v[42:45], v[164:167], v[180:183], v[42:45]
	v_mfma_f32_16x16x32_bf16 v[30:33], v[156:159], v[188:191], v[30:33]
	v_mfma_f32_16x16x32_bf16 v[26:29], v[164:167], v[188:191], v[26:29]
	v_mfma_f32_16x16x32_bf16 v[14:17], v[156:159], v[196:199], v[14:17]
	v_mfma_f32_16x16x32_bf16 v[10:13], v[164:167], v[196:199], v[10:13]
	v_mfma_f32_16x16x32_bf16 v[62:65], v[160:163], v[176:179], v[62:65]
	v_mfma_f32_16x16x32_bf16 v[58:61], v[168:171], v[176:179], v[58:61]
	v_mfma_f32_16x16x32_bf16 v[46:49], v[160:163], v[184:187], v[46:49]
	v_mfma_f32_16x16x32_bf16 v[42:45], v[168:171], v[184:187], v[42:45]
	v_mfma_f32_16x16x32_bf16 v[30:33], v[160:163], v[192:195], v[30:33]
	v_mfma_f32_16x16x32_bf16 v[26:29], v[168:171], v[192:195], v[26:29]
	v_mfma_f32_16x16x32_bf16 v[14:17], v[160:163], v[200:203], v[14:17]
	v_mfma_f32_16x16x32_bf16 v[10:13], v[168:171], v[200:203], v[10:13]
	s_barrier
; #define PG8_STAGE(bufoff, gbase, voff) do { _Pragma("unroll") for (int _i = 0; _i < 2; ++_i) \
;     __builtin_amdgcn_global_load_lds((const unsigned*)((const char*)(gbase) + (voff)[_i]), (LAS unsigned*)(lds + (bufoff) + ldsw + _i * 8192), 16, 0, 0); } while (0)
; #define PG8_LDA(dst, b, h) do { _Pragma("unroll") for (int m = 0; m < 4; ++m) _Pragma("unroll") for (int k = 0; k < 2; ++k) dst[m][k] = *(const LAS bf16x8*)(lds + PG8_SA(b, h) + aoff + m * 2048 + k * 1024); } while (0)
; #define PG8_LDB(dst, b, h) do { _Pragma("unroll") for (int n = 0; n < 2; ++n) _Pragma("unroll") for (int k = 0; k < 2; ++k) dst[n][k] = *(const LAS bf16x8*)(lds + PG8_SB(b, h) + boff + n * 2048 + k * 1024); } while (0)
; #define PG8_MMA(ai, bj, At, Bt) do { __builtin_amdgcn_s_setprio(1); _Pragma("unroll") for (int m = 0; m < 4; ++m) _Pragma("unroll") for (int n = 0; n < 2; ++n) _Pragma("unroll") for (int k = 0; k < 2; ++k) \
;     acc[ai][bj][m][n] = __builtin_amdgcn_mfma_f32_16x16x32_bf16(Bt[n][k], At[m][k], acc[ai][bj][m][n], 0, 0, 0); __builtin_amdgcn_s_setprio(0); } while (0)
; #define PG8_WAIT_V(n) asm volatile("s_waitcnt vmcnt(" #n ")" ::: "memory")
; #define PG8_WAIT_L(n) asm volatile("s_waitcnt lgkmcnt(" #n ")" ::: "memory")
; #define PG8_BAR __builtin_amdgcn_s_barrier()
; #define PG8_SCHED __builtin_amdgcn_sched_barrier(0)
; template <class Epi>
; DI void gemm_phase(LAS unsigned char* lds, const Gemm g, const StaticOrder& S, const Epi& E) {
;     ...
;       PG8_STAGE(PG8_SB(0, 1), b2 + hstepB, voffB);
;       PG8_WAIT_V(6); PG8_BAR; PG8_MMA(1, 1, At, B1); PG8_BAR;
;       PG8_LDB(B0, 1, 0); PG8_SCHED; PG8_LDA(At, 1, 0); PG8_STAGE(PG8_SA(0, 1), a2 + hstepA, voffA);
;       PG8_WAIT_L(8); PG8_BAR; PG8_WAIT_L(0); PG8_MMA(0, 0, At, B0); PG8_BAR; PG8_SCHED;
;       PG8_LDB(B1, 1, 1); PG8_STAGE(PG8_SB(1, 0), b3, voffB);
;       PG8_BAR; PG8_WAIT_L(0); PG8_MMA(0, 1, At, B1); PG8_BAR;
;       PG8_LDA(At, 1, 1); PG8_STAGE(PG8_SA(1, 0), a3, voffA);
;       PG8_BAR; PG8_WAIT_L(0); PG8_MMA(1, 0, At, B0); PG8_BAR; PG8_SCHED;
	s_add_u32 s54, s24, 0x80000
	s_addc_u32 s55, s25, 0
	s_add_i32 s53, s47, s34
	v_lshl_add_u64 v[156:157], s[54:55], 0, v[132:133]
	s_mov_b32 m0, s53
	s_nop 0
	global_load_lds_dwordx4 v[156:157], off
	v_lshl_add_u64 v[156:157], s[54:55], 0, v[136:137]
	s_add_i32 m0, s53, 0x2000
	s_nop 0
	global_load_lds_dwordx4 v[156:157], off
	s_waitcnt vmcnt(6)
	s_barrier
	v_mfma_f32_16x16x32_bf16 v[54:57], v[204:207], v[172:175], v[54:57]
	v_mfma_f32_16x16x32_bf16 v[50:53], v[212:215], v[172:175], v[50:53]
	v_mfma_f32_16x16x32_bf16 v[38:41], v[204:207], v[180:183], v[38:41]
	v_mfma_f32_16x16x32_bf16 v[34:37], v[212:215], v[180:183], v[34:37]
	v_mfma_f32_16x16x32_bf16 v[22:25], v[204:207], v[188:191], v[22:25]
	v_mfma_f32_16x16x32_bf16 v[18:21], v[212:215], v[188:191], v[18:21]
	v_mfma_f32_16x16x32_bf16 v[6:9], v[204:207], v[196:199], v[6:9]
	v_mfma_f32_16x16x32_bf16 v[2:5], v[212:215], v[196:199], v[2:5]
	v_mfma_f32_16x16x32_bf16 v[54:57], v[208:211], v[176:179], v[54:57]
	v_mfma_f32_16x16x32_bf16 v[50:53], v[216:219], v[176:179], v[50:53]
	v_mfma_f32_16x16x32_bf16 v[38:41], v[208:211], v[184:187], v[38:41]
	v_mfma_f32_16x16x32_bf16 v[34:37], v[216:219], v[184:187], v[34:37]
	v_mfma_f32_16x16x32_bf16 v[22:25], v[208:211], v[192:195], v[22:25]
	v_mfma_f32_16x16x32_bf16 v[18:21], v[216:219], v[192:195], v[18:21]
	v_mfma_f32_16x16x32_bf16 v[6:9], v[208:211], v[200:203], v[6:9]
	v_mfma_f32_16x16x32_bf16 v[2:5], v[216:219], v[200:203], v[2:5]
	s_add_i32 s53, 0, 0x18000
	v_add_u32_e32 v155, s53, v150
	s_barrier
	ds_read_b128 v[156:159], v155
	ds_read_b128 v[160:163], v155 offset:1024
	ds_read_b128 v[164:167], v155 offset:2048
	ds_read_b128 v[168:171], v155 offset:3072
	s_add_u32 s26, s26, 0x40000
	s_addc_u32 s27, s27, 0
	s_mov_b32 m0, s37
	v_lshl_add_u64 v[204:205], s[26:27], 0, v[130:131]
	ds_read_b128 v[172:175], v152 offset:32768
	ds_read_b128 v[176:179], v152 offset:33792
	ds_read_b128 v[180:183], v152 offset:34816
	ds_read_b128 v[184:187], v152 offset:35840
	ds_read_b128 v[188:191], v152 offset:36864
	ds_read_b128 v[192:195], v152 offset:37888
	ds_read_b128 v[196:199], v152 offset:38912
	ds_read_b128 v[200:203], v152 offset:39936
	global_load_lds_dwordx4 v[204:205], off
	v_lshl_add_u64 v[204:205], s[26:27], 0, v[134:135]
	s_mov_b32 m0, s38
	s_nop 0
	global_load_lds_dwordx4 v[204:205], off
	s_waitcnt lgkmcnt(8)
	s_barrier
	s_waitcnt lgkmcnt(0)
	v_mfma_f32_16x16x32_bf16 v[126:129], v[156:159], v[172:175], v[126:129]
	v_mfma_f32_16x16x32_bf16 v[122:125], v[164:167], v[172:175], v[122:125]
	v_mfma_f32_16x16x32_bf16 v[110:113], v[156:159], v[180:183], v[110:113]
	v_mfma_f32_16x16x32_bf16 v[106:109], v[164:167], v[180:183], v[106:109]
	v_mfma_f32_16x16x32_bf16 v[94:97], v[156:159], v[188:191], v[94:97]
	v_mfma_f32_16x16x32_bf16 v[90:93], v[164:167], v[188:191], v[90:93]
	v_mfma_f32_16x16x32_bf16 v[78:81], v[156:159], v[196:199], v[78:81]
	v_mfma_f32_16x16x32_bf16 v[74:77], v[164:167], v[196:199], v[74:77]
	v_mfma_f32_16x16x32_bf16 v[126:129], v[160:163], v[176:179], v[126:129]
	v_mfma_f32_16x16x32_bf16 v[122:125], v[168:171], v[176:179], v[122:125]
	v_mfma_f32_16x16x32_bf16 v[110:113], v[160:163], v[184:187], v[110:113]
	v_mfma_f32_16x16x32_bf16 v[106:109], v[168:171], v[184:187], v[106:109]
	v_mfma_f32_16x16x32_bf16 v[94:97], v[160:163], v[192:195], v[94:97]
	v_mfma_f32_16x16x32_bf16 v[90:93], v[168:171], v[192:195], v[90:93]
	v_mfma_f32_16x16x32_bf16 v[78:81], v[160:163], v[200:203], v[78:81]
	v_mfma_f32_16x16x32_bf16 v[74:77], v[168:171], v[200:203], v[74:77]
	s_barrier
	s_add_i32 s26, 0, 0x1c000
	s_add_i32 s27, s53, s34
	v_add_u32_e32 v155, s26, v150
	v_lshl_add_u64 v[148:149], v[148:149], 0, s[6:7]
	s_mov_b32 m0, s27
	ds_read_b128 v[204:207], v155
	ds_read_b128 v[208:211], v155 offset:1024
	ds_read_b128 v[212:215], v155 offset:2048
	ds_read_b128 v[216:219], v155 offset:3072
	global_load_lds_dwordx4 v[148:149], off
	v_lshl_add_u64 v[148:149], v[220:221], 0, s[6:7]
	s_add_i32 m0, s27, 0x2000
	s_nop 0
	global_load_lds_dwordx4 v[148:149], off
	s_barrier
	s_waitcnt lgkmcnt(0)
	v_mfma_f32_16x16x32_bf16 v[118:121], v[204:207], v[172:175], v[118:121]
	v_mfma_f32_16x16x32_bf16 v[114:117], v[212:215], v[172:175], v[114:117]
	v_mfma_f32_16x16x32_bf16 v[102:105], v[204:207], v[180:183], v[102:105]
	v_mfma_f32_16x16x32_bf16 v[98:101], v[212:215], v[180:183], v[98:101]
	v_mfma_f32_16x16x32_bf16 v[86:89], v[204:207], v[188:191], v[86:89]
	v_mfma_f32_16x16x32_bf16 v[82:85], v[212:215], v[188:191], v[82:85]
	v_mfma_f32_16x16x32_bf16 v[70:73], v[204:207], v[196:199], v[70:73]
	v_mfma_f32_16x16x32_bf16 v[66:69], v[212:215], v[196:199], v[66:69]
	v_mfma_f32_16x16x32_bf16 v[118:121], v[208:211], v[176:179], v[118:121]
	v_mfma_f32_16x16x32_bf16 v[114:117], v[216:219], v[176:179], v[114:117]
	v_mfma_f32_16x16x32_bf16 v[102:105], v[208:211], v[184:187], v[102:105]
	v_mfma_f32_16x16x32_bf16 v[98:101], v[216:219], v[184:187], v[98:101]
	v_mfma_f32_16x16x32_bf16 v[86:89], v[208:211], v[192:195], v[86:89]
	v_mfma_f32_16x16x32_bf16 v[82:85], v[216:219], v[192:195], v[82:85]
	v_mfma_f32_16x16x32_bf16 v[70:73], v[208:211], v[200:203], v[70:73]
	v_mfma_f32_16x16x32_bf16 v[66:69], v[216:219], v[200:203], v[66:69]
	s_mov_b32 m0, s42
	v_lshl_add_u64 v[148:149], v[222:223], 0, s[6:7]
	s_barrier
; template <class Epi>
; DI void gemm_phase(LAS unsigned char* lds, const Gemm g, const StaticOrder& S, const Epi& E) {
;     ...
;       PG8_BAR; PG8_WAIT_L(0); PG8_MMA(0, 1, At, B1); PG8_BAR;
;       PG8_LDA(At, 1, 1); PG8_STAGE(PG8_SA(1, 0), a3, voffA);
;       PG8_BAR; PG8_WAIT_L(0); PG8_MMA(1, 0, At, B0); PG8_BAR; PG8_SCHED;
;       PG8_STAGE(PG8_SB(1, 1), b3 + hstepB, voffB);
;       PG8_WAIT_V(6); PG8_BAR; PG8_MMA(1, 1, At, B1); PG8_BAR;
;     }
;     E(acc, cur, wr, wc, fr, fq);
;   DI void operator()(const f32x4 (&acc)[2][2][4][2], const pg8::Unit& u, int wr, int wc, int fr, int fq) const {
;     ...
;         float ssq = 0.f;
; #pragma unroll
;         for (int bj = 0; bj < 2; ++bj) {
;           f32x4 v0 = acc[ai][bj][m][0] * rs, v1 = acc[ai][bj][m][1] * rs;
;           if (MODE == EP_IN || MODE == EP_MIX || MODE == EP_DOWN) {
; #pragma unroll
;             for (int j = 0; j < 4; ++j) ssq += v0[j] * v0[j] + v1[j] * v1[j];
;           }
;           if (MODE == EP_UP) {
; #pragma unroll
;             for (int j = 0; j < 4; ++j) { float a = fmaxf(v0[j], 0.f), b = fmaxf(v1[j], 0.f); v0[j] = a * a; v1[j] = b * b; }
;           }
;           bf16_t* dst;
;           const int ct = bj * 128 + cl;
;           if (MODE == EP_IN) {
;             if (pn < 4) dst = (bf16_t*)(ws + OFF_PROJA) + (size_t)grow * 1024 + pn * 256 + ct;
;             else if (pn < 16) dst = (bf16_t*)(ws + OFF_PROJG) + (size_t)grow * 3072 + (pn - 4) * 256 + ct;
;             else dst = (bf16_t*)(ws + OFF_PROJS) + (size_t)grow * 256 + ct;
;           } else if (MODE == EP_Q) {
;             if (pn < 4) dst = (bf16_t*)(dout + DO_Q) + (size_t)grow * 1536 + (pn * 2 + bj) * 192 + cl;
;             else {
;               const int mm = (pn - 4) * 256 + ct, h = mm >> 6, r = mm & 63;
;               dst = (bf16_t*)(dout + DO_Q) + (size_t)grow * 1536 + h * 192 + 128 + r;
;               const int pos = grow < TP ? (grow & 4095) : grow - TP;
;               const f32x4* tb = (const f32x4*)((const f32x2*)(ws + OFF_ROPE) + pos * 32 + (r >> 1));
;               const f32x4 t0 = tb[0], t1 = tb[1];
;               f32x4 o0, o1;
;               o0[0] = v0[0] * t0[0] - v0[1] * t0[1]; o0[1] = v0[1] * t0[0] + v0[0] * t0[1];
;               o0[2] = v0[2] * t0[2] - v0[3] * t0[3]; o0[3] = v0[3] * t0[2] + v0[2] * t0[3];
;               o1[0] = v1[0] * t1[0] - v1[1] * t1[1]; o1[1] = v1[1] * t1[0] + v1[0] * t1[1];
	ds_read_b128 v[172:175], v152 offset:49152
	ds_read_b128 v[176:179], v152 offset:50176
	ds_read_b128 v[180:183], v152 offset:51200
	ds_read_b128 v[184:187], v152 offset:52224
	ds_read_b128 v[188:191], v152 offset:53248
	ds_read_b128 v[192:195], v152 offset:54272
	ds_read_b128 v[196:199], v152 offset:55296
	ds_read_b128 v[200:203], v152 offset:56320
	global_load_lds_dwordx4 v[148:149], off
	v_lshl_add_u64 v[148:149], v[224:225], 0, s[6:7]
	s_mov_b32 m0, s43
	s_nop 0
	global_load_lds_dwordx4 v[148:149], off
	s_barrier
	s_waitcnt lgkmcnt(0)
	v_mfma_f32_16x16x32_bf16 v[62:65], v[156:159], v[172:175], v[62:65]
	v_mfma_f32_16x16x32_bf16 v[58:61], v[164:167], v[172:175], v[58:61]
	v_mfma_f32_16x16x32_bf16 v[46:49], v[156:159], v[180:183], v[46:49]
	v_mfma_f32_16x16x32_bf16 v[42:45], v[164:167], v[180:183], v[42:45]
	v_mfma_f32_16x16x32_bf16 v[30:33], v[156:159], v[188:191], v[30:33]
	v_mfma_f32_16x16x32_bf16 v[26:29], v[164:167], v[188:191], v[26:29]
	v_mfma_f32_16x16x32_bf16 v[14:17], v[156:159], v[196:199], v[14:17]
	v_mfma_f32_16x16x32_bf16 v[10:13], v[164:167], v[196:199], v[10:13]
	v_mfma_f32_16x16x32_bf16 v[62:65], v[160:163], v[176:179], v[62:65]
	v_mfma_f32_16x16x32_bf16 v[58:61], v[168:171], v[176:179], v[58:61]
	v_mfma_f32_16x16x32_bf16 v[46:49], v[160:163], v[184:187], v[46:49]
	v_mfma_f32_16x16x32_bf16 v[42:45], v[168:171], v[184:187], v[42:45]
	v_mfma_f32_16x16x32_bf16 v[30:33], v[160:163], v[192:195], v[30:33]
	v_mfma_f32_16x16x32_bf16 v[26:29], v[168:171], v[192:195], v[26:29]
	v_mfma_f32_16x16x32_bf16 v[14:17], v[160:163], v[200:203], v[14:17]
	v_mfma_f32_16x16x32_bf16 v[10:13], v[168:171], v[200:203], v[10:13]
	s_barrier
	s_add_u32 s24, s24, 0x80080
	s_addc_u32 s25, s25, 0
	s_add_i32 s26, s26, s34
	v_lshl_add_u64 v[148:149], s[24:25], 0, v[132:133]
	s_mov_b32 m0, s26
	s_nop 0
	global_load_lds_dwordx4 v[148:149], off
	v_lshl_add_u64 v[148:149], s[24:25], 0, v[136:137]
	s_add_i32 m0, s26, 0x2000
	s_nop 0
	global_load_lds_dwordx4 v[148:149], off
	s_waitcnt vmcnt(6)
	s_barrier
	v_mfma_f32_16x16x32_bf16 v[54:57], v[204:207], v[172:175], v[54:57]
	v_mfma_f32_16x16x32_bf16 v[50:53], v[212:215], v[172:175], v[50:53]
	v_mfma_f32_16x16x32_bf16 v[38:41], v[204:207], v[180:183], v[38:41]
	v_mfma_f32_16x16x32_bf16 v[34:37], v[212:215], v[180:183], v[34:37]
	v_mfma_f32_16x16x32_bf16 v[22:25], v[204:207], v[188:191], v[22:25]
	v_mfma_f32_16x16x32_bf16 v[18:21], v[212:215], v[188:191], v[18:21]
	v_mfma_f32_16x16x32_bf16 v[6:9], v[204:207], v[196:199], v[6:9]
	v_mfma_f32_16x16x32_bf16 v[2:5], v[212:215], v[196:199], v[2:5]
	v_mfma_f32_16x16x32_bf16 v[54:57], v[208:211], v[176:179], v[54:57]
	v_mfma_f32_16x16x32_bf16 v[50:53], v[216:219], v[176:179], v[50:53]
	v_mfma_f32_16x16x32_bf16 v[38:41], v[208:211], v[184:187], v[38:41]
	v_mfma_f32_16x16x32_bf16 v[34:37], v[216:219], v[184:187], v[34:37]
	v_mfma_f32_16x16x32_bf16 v[22:25], v[208:211], v[192:195], v[22:25]
	v_mfma_f32_16x16x32_bf16 v[18:21], v[216:219], v[192:195], v[18:21]
	v_mfma_f32_16x16x32_bf16 v[6:9], v[208:211], v[200:203], v[6:9]
	v_mfma_f32_16x16x32_bf16 v[2:5], v[216:219], v[200:203], v[2:5]
	s_add_u32 s22, s22, 0x100
	s_addc_u32 s23, s23, 0
	s_add_u32 s50, s50, 0x100
	s_addc_u32 s51, s51, 0
	s_cmp_gt_u32 s52, 29
	s_mov_b32 s24, s52
	s_barrier
	s_cbranch_scc0 .LBB0_840
	v_mul_f32_e32 v157, v122, v122
	v_mul_f32_e32 v160, v123, v123
	v_fmac_f32_e32 v157, v126, v126
	v_fmac_f32_e32 v160, v127, v127
	v_add_f32_e32 v157, v157, v160
	v_mul_f32_e32 v160, v124, v124
	v_fmac_f32_e32 v160, v128, v128
	v_add_f32_e32 v157, v160, v157
	v_mul_f32_e32 v160, v125, v125
	v_fmac_f32_e32 v160, v129, v129
	v_cvt_pk_bf16_f32 v126, v126, v127
	v_cvt_pk_bf16_f32 v127, v128, v129
	v_mul_f32_e32 v128, v114, v114
	v_add_f32_e32 v157, v160, v157
	v_fmac_f32_e32 v128, v118, v118
	v_mul_f32_e32 v129, v115, v115
	v_add_f32_e32 v128, v157, v128
	v_fmac_f32_e32 v129, v119, v119
	v_and_b32_e32 v155, 64, v154
	v_add_f32_e32 v128, v129, v128
	v_mul_f32_e32 v129, v116, v116
	v_xor_b32_e32 v149, 16, v154
	v_add_u32_e32 v155, 64, v155
	v_fmac_f32_e32 v129, v120, v120
	v_cmp_lt_i32_e32 vcc, v149, v155
	v_add_f32_e32 v128, v129, v128
	v_mul_f32_e32 v129, v117, v117
	v_cndmask_b32_e32 v149, v154, v149, vcc
	v_fmac_f32_e32 v129, v121, v121
	v_lshlrev_b32_e32 v156, 2, v149
	v_add_f32_e32 v157, v129, v128
	ds_bpermute_b32 v160, v156, v157
	v_xor_b32_e32 v149, 32, v154
	v_cmp_lt_i32_e32 vcc, v149, v155
	v_lshl_add_u32 v148, s20, 8, v1
	v_cvt_pk_bf16_f32 v128, v122, v123
	v_cndmask_b32_e32 v149, v154, v149, vcc
	v_lshlrev_b32_e32 v155, 2, v149
	v_cvt_pk_bf16_f32 v122, v118, v119
	s_waitcnt lgkmcnt(0)
	v_add_f32_e32 v118, v157, v160
	v_ashrrev_i32_e32 v149, 31, v148
	ds_bpermute_b32 v119, v155, v118
	s_lshl_b32 s22, s4, 8
	v_lshlrev_b64 v[158:159], 12, v[148:149]
	s_ashr_i32 s23, s22, 31
	v_lshl_add_u64 v[158:159], s[8:9], 0, v[158:159]
	s_lshl_b32 s20, s4, 2
	v_lshl_add_u64 v[158:159], s[22:23], 1, v[158:159]
	s_ashr_i32 s21, s20, 31
	v_lshl_add_u64 v[158:159], v[158:159], 0, v[138:139]
	v_cvt_pk_bf16_f32 v129, v124, v125
	v_cvt_pk_bf16_f32 v123, v120, v121
	v_cvt_pk_bf16_f32 v124, v114, v115
	v_cvt_pk_bf16_f32 v125, v116, v117
	global_store_dwordx4 v[158:159], v[126:129], off
	global_store_dwordx4 v[158:159], v[122:125], off offset:256
	s_and_saveexec_b64 s[24:25], s[0:1]
	s_cbranch_execz .LBB0_843
	v_lshlrev_b64 v[114:115], 7, v[148:149]
	v_lshl_add_u64 v[114:115], s[10:11], 0, v[114:115]
	v_lshl_add_u64 v[114:115], s[20:21], 2, v[114:115]
	s_lshl_b32 s4, s41, 2
	v_lshl_add_u64 v[114:115], v[114:115], 0, s[4:5]
	s_waitcnt lgkmcnt(0)
	v_add_f32_e32 v116, v118, v119
	global_store_dword v[114:115], v116, off

; #define PG8_STAGE(bufoff, gbase, voff) do { _Pragma("unroll") for (int _i = 0; _i < 2; ++_i) \
;     __builtin_amdgcn_global_load_lds((const unsigned*)((const char*)(gbase) + (voff)[_i]), (LAS unsigned*)(lds + (bufoff) + ldsw + _i * 8192), 16, 0, 0); } while (0)
; #define PG8_LDA(dst, b, h) do { _Pragma("unroll") for (int m = 0; m < 4; ++m) _Pragma("unroll") for (int k = 0; k < 2; ++k) dst[m][k] = *(const LAS bf16x8*)(lds + PG8_SA(b, h) + aoff + m * 2048 + k * 1024); } while (0)
; #define PG8_LDB(dst, b, h) do { _Pragma("unroll") for (int n = 0; n < 2; ++n) _Pragma("unroll") for (int k = 0; k < 2; ++k) dst[n][k] = *(const LAS bf16x8*)(lds + PG8_SB(b, h) + boff + n * 2048 + k * 1024); } while (0)
; #define PG8_MMA(ai, bj, At, Bt) do { __builtin_amdgcn_s_setprio(1); _Pragma("unroll") for (int m = 0; m < 4; ++m) _Pragma("unroll") for (int n = 0; n < 2; ++n) _Pragma("unroll") for (int k = 0; k < 2; ++k) \
;     acc[ai][bj][m][n] = __builtin_amdgcn_mfma_f32_16x16x32_bf16(Bt[n][k], At[m][k], acc[ai][bj][m][n], 0, 0, 0); __builtin_amdgcn_s_setprio(0); } while (0)
; #define PG8_WAIT_L(n) asm volatile("s_waitcnt lgkmcnt(" #n ")" ::: "memory")
; #define PG8_BAR __builtin_amdgcn_s_barrier()
; #define PG8_SCHED __builtin_amdgcn_sched_barrier(0)
; template <class Epi>
; DI void gemm_phase(LAS unsigned char* lds, const Gemm g, const StaticOrder& S, const Epi& E) {
;     ...
;     for (int t = 0; t < nt; t += 2) {
;       const bool last = (t == nt - 2);
;       const char* a1 = cA + PG8_AK(t + 1);
;       const char* a2 = last ? nA : cA + PG8_AK(t + 2); const char* b2 = last ? nB : cB + (size_t)(t + 2) * kstep;
;       const char* a3 = a2 + kstep; const char* b3 = b2 + kstep;
;       PG8_LDB(B0, 0, 0); PG8_SCHED; PG8_LDA(At, 0, 0); PG8_STAGE(PG8_SA(1, 1), a1 + hstepA, voffA);
;       PG8_WAIT_L(8); PG8_BAR; PG8_WAIT_L(0); PG8_MMA(0, 0, At, B0); PG8_BAR; PG8_SCHED;
;       PG8_LDB(B1, 0, 1); PG8_STAGE(PG8_SB(0, 0), b2, voffB);
;       PG8_BAR; PG8_WAIT_L(0); PG8_MMA(0, 1, At, B1); PG8_BAR;
;       PG8_LDA(At, 0, 1); PG8_STAGE(PG8_SA(0, 0), a2, voffA);
;       PG8_BAR; PG8_WAIT_L(0); PG8_MMA(1, 0, At, B0); PG8_BAR; PG8_SCHED;
.LBB0_921:
	ds_read_b128 v[154:157], v151
	ds_read_b128 v[158:161], v151 offset:1024
	ds_read_b128 v[162:165], v151 offset:2048
	ds_read_b128 v[166:169], v151 offset:3072
	s_add_u32 s20, s18, 0xfff80080
	s_addc_u32 s21, s19, -1
	s_cmp_eq_u32 s46, 28
	s_cselect_b32 s23, s11, s21
	s_cselect_b32 s22, s42, s20
	s_cselect_b32 s21, s9, s45
	s_cselect_b32 s20, s43, s44
	v_lshl_add_u64 v[148:149], s[18:19], 0, v[140:141]
	s_add_i32 m0, s17, 0xc000
	ds_read_b128 v[170:173], v152
	ds_read_b128 v[174:177], v152 offset:1024
	ds_read_b128 v[178:181], v152 offset:2048
	ds_read_b128 v[182:185], v152 offset:3072
	ds_read_b128 v[186:189], v152 offset:4096
	ds_read_b128 v[190:193], v152 offset:5120
	ds_read_b128 v[194:197], v152 offset:6144
	ds_read_b128 v[198:201], v152 offset:7168
	global_load_lds_dwordx4 v[148:149], off
	v_lshl_add_u64 v[148:149], s[18:19], 0, v[142:143]
	s_add_i32 m0, s17, 0xe000
	s_nop 0
	global_load_lds_dwordx4 v[148:149], off
	s_waitcnt lgkmcnt(8)
	s_barrier
	s_waitcnt lgkmcnt(0)
	v_mfma_f32_16x16x32_bf16 v[126:129], v[154:157], v[170:173], v[126:129]
	v_mfma_f32_16x16x32_bf16 v[122:125], v[162:165], v[170:173], v[122:125]
	v_mfma_f32_16x16x32_bf16 v[110:113], v[154:157], v[178:181], v[110:113]
	v_mfma_f32_16x16x32_bf16 v[106:109], v[162:165], v[178:181], v[106:109]
	v_mfma_f32_16x16x32_bf16 v[94:97], v[154:157], v[186:189], v[94:97]
	v_mfma_f32_16x16x32_bf16 v[90:93], v[162:165], v[186:189], v[90:93]
	v_mfma_f32_16x16x32_bf16 v[78:81], v[154:157], v[194:197], v[78:81]
	v_mfma_f32_16x16x32_bf16 v[74:77], v[162:165], v[194:197], v[74:77]
	v_mfma_f32_16x16x32_bf16 v[126:129], v[158:161], v[174:177], v[126:129]
	v_mfma_f32_16x16x32_bf16 v[122:125], v[166:169], v[174:177], v[122:125]
	v_mfma_f32_16x16x32_bf16 v[110:113], v[158:161], v[182:185], v[110:113]
	v_mfma_f32_16x16x32_bf16 v[106:109], v[166:169], v[182:185], v[106:109]
	v_mfma_f32_16x16x32_bf16 v[94:97], v[158:161], v[190:193], v[94:97]
	v_mfma_f32_16x16x32_bf16 v[90:93], v[166:169], v[190:193], v[90:93]
	v_mfma_f32_16x16x32_bf16 v[78:81], v[158:161], v[198:201], v[78:81]
	v_mfma_f32_16x16x32_bf16 v[74:77], v[166:169], v[198:201], v[74:77]
	s_barrier
	s_add_i32 s47, s39, s30
	v_lshl_add_u64 v[148:149], s[20:21], 0, v[132:133]
	s_mov_b32 m0, s47
	ds_read_b128 v[202:205], v153
	ds_read_b128 v[206:209], v153 offset:1024
	ds_read_b128 v[210:213], v153 offset:2048
	ds_read_b128 v[214:217], v153 offset:3072
	global_load_lds_dwordx4 v[148:149], off
	v_lshl_add_u64 v[218:219], s[20:21], 0, v[136:137]
	s_add_i32 m0, s47, 0x2000
	s_nop 0
	global_load_lds_dwordx4 v[218:219], off
	s_barrier
	s_waitcnt lgkmcnt(0)
	v_mfma_f32_16x16x32_bf16 v[118:121], v[202:205], v[170:173], v[118:121]
	v_mfma_f32_16x16x32_bf16 v[114:117], v[210:213], v[170:173], v[114:117]
	v_mfma_f32_16x16x32_bf16 v[102:105], v[202:205], v[178:181], v[102:105]
	v_mfma_f32_16x16x32_bf16 v[98:101], v[210:213], v[178:181], v[98:101]
	v_mfma_f32_16x16x32_bf16 v[86:89], v[202:205], v[186:189], v[86:89]
	v_mfma_f32_16x16x32_bf16 v[82:85], v[210:213], v[186:189], v[82:85]
	v_mfma_f32_16x16x32_bf16 v[70:73], v[202:205], v[194:197], v[70:73]
	v_mfma_f32_16x16x32_bf16 v[66:69], v[210:213], v[194:197], v[66:69]
	v_mfma_f32_16x16x32_bf16 v[118:121], v[206:209], v[174:177], v[118:121]
	v_mfma_f32_16x16x32_bf16 v[114:117], v[214:217], v[174:177], v[114:117]
	v_mfma_f32_16x16x32_bf16 v[102:105], v[206:209], v[182:185], v[102:105]
	v_mfma_f32_16x16x32_bf16 v[98:101], v[214:217], v[182:185], v[98:101]
	v_mfma_f32_16x16x32_bf16 v[86:89], v[206:209], v[190:193], v[86:89]
	v_mfma_f32_16x16x32_bf16 v[82:85], v[214:217], v[190:193], v[82:85]
	v_mfma_f32_16x16x32_bf16 v[70:73], v[206:209], v[198:201], v[70:73]
	v_mfma_f32_16x16x32_bf16 v[66:69], v[214:217], v[198:201], v[66:69]
	s_mov_b32 m0, s17
	v_lshl_add_u64 v[220:221], s[22:23], 0, v[130:131]
	s_barrier
	ds_read_b128 v[170:173], v152 offset:16384
	ds_read_b128 v[174:177], v152 offset:17408
	ds_read_b128 v[178:181], v152 offset:18432
	ds_read_b128 v[182:185], v152 offset:19456
	ds_read_b128 v[186:189], v152 offset:20480
	ds_read_b128 v[190:193], v152 offset:21504
	ds_read_b128 v[194:197], v152 offset:22528
	ds_read_b128 v[198:201], v152 offset:23552
	global_load_lds_dwordx4 v[220:221], off
	v_lshl_add_u64 v[222:223], s[22:23], 0, v[134:135]
	s_mov_b32 m0, s31
	s_nop 0
	global_load_lds_dwordx4 v[222:223], off
	s_barrier
	s_waitcnt lgkmcnt(0)
	v_mfma_f32_16x16x32_bf16 v[62:65], v[154:157], v[170:173], v[62:65]
	v_mfma_f32_16x16x32_bf16 v[58:61], v[162:165], v[170:173], v[58:61]
	v_mfma_f32_16x16x32_bf16 v[46:49], v[154:157], v[178:181], v[46:49]
	v_mfma_f32_16x16x32_bf16 v[42:45], v[162:165], v[178:181], v[42:45]
	v_mfma_f32_16x16x32_bf16 v[30:33], v[154:157], v[186:189], v[30:33]
	v_mfma_f32_16x16x32_bf16 v[26:29], v[162:165], v[186:189], v[26:29]
	v_mfma_f32_16x16x32_bf16 v[14:17], v[154:157], v[194:197], v[14:17]
	v_mfma_f32_16x16x32_bf16 v[10:13], v[162:165], v[194:197], v[10:13]
	v_mfma_f32_16x16x32_bf16 v[62:65], v[158:161], v[174:177], v[62:65]
	v_mfma_f32_16x16x32_bf16 v[58:61], v[166:169], v[174:177], v[58:61]
	v_mfma_f32_16x16x32_bf16 v[46:49], v[158:161], v[182:185], v[46:49]
	v_mfma_f32_16x16x32_bf16 v[42:45], v[166:169], v[182:185], v[42:45]
	v_mfma_f32_16x16x32_bf16 v[30:33], v[158:161], v[190:193], v[30:33]
	v_mfma_f32_16x16x32_bf16 v[26:29], v[166:169], v[190:193], v[26:29]
	v_mfma_f32_16x16x32_bf16 v[14:17], v[158:161], v[198:201], v[14:17]
	v_mfma_f32_16x16x32_bf16 v[10:13], v[166:169], v[198:201], v[10:13]
	s_barrier
; #define PG8_STAGE(bufoff, gbase, voff) do { _Pragma("unroll") for (int _i = 0; _i < 2; ++_i) \
;     __builtin_amdgcn_global_load_lds((const unsigned*)((const char*)(gbase) + (voff)[_i]), (LAS unsigned*)(lds + (bufoff) + ldsw + _i * 8192), 16, 0, 0); } while (0)
; #define PG8_LDA(dst, b, h) do { _Pragma("unroll") for (int m = 0; m < 4; ++m) _Pragma("unroll") for (int k = 0; k < 2; ++k) dst[m][k] = *(const LAS bf16x8*)(lds + PG8_SA(b, h) + aoff + m * 2048 + k * 1024); } while (0)
; #define PG8_LDB(dst, b, h) do { _Pragma("unroll") for (int n = 0; n < 2; ++n) _Pragma("unroll") for (int k = 0; k < 2; ++k) dst[n][k] = *(const LAS bf16x8*)(lds + PG8_SB(b, h) + boff + n * 2048 + k * 1024); } while (0)
; #define PG8_MMA(ai, bj, At, Bt) do { __builtin_amdgcn_s_setprio(1); _Pragma("unroll") for (int m = 0; m < 4; ++m) _Pragma("unroll") for (int n = 0; n < 2; ++n) _Pragma("unroll") for (int k = 0; k < 2; ++k) \
;     acc[ai][bj][m][n] = __builtin_amdgcn_mfma_f32_16x16x32_bf16(Bt[n][k], At[m][k], acc[ai][bj][m][n], 0, 0, 0); __builtin_amdgcn_s_setprio(0); } while (0)
; #define PG8_WAIT_V(n) asm volatile("s_waitcnt vmcnt(" #n ")" ::: "memory")
; #define PG8_WAIT_L(n) asm volatile("s_waitcnt lgkmcnt(" #n ")" ::: "memory")
; #define PG8_BAR __builtin_amdgcn_s_barrier()
; #define PG8_SCHED __builtin_amdgcn_sched_barrier(0)
; template <class Epi>
; DI void gemm_phase(LAS unsigned char* lds, const Gemm g, const StaticOrder& S, const Epi& E) {
;     ...
;       PG8_STAGE(PG8_SB(0, 1), b2 + hstepB, voffB);
;       PG8_WAIT_V(6); PG8_BAR; PG8_MMA(1, 1, At, B1); PG8_BAR;
;       PG8_LDB(B0, 1, 0); PG8_SCHED; PG8_LDA(At, 1, 0); PG8_STAGE(PG8_SA(0, 1), a2 + hstepA, voffA);
;       PG8_WAIT_L(8); PG8_BAR; PG8_WAIT_L(0); PG8_MMA(0, 0, At, B0); PG8_BAR; PG8_SCHED;
;       PG8_LDB(B1, 1, 1); PG8_STAGE(PG8_SB(1, 0), b3, voffB);
;       PG8_BAR; PG8_WAIT_L(0); PG8_MMA(0, 1, At, B1); PG8_BAR;
;       PG8_LDA(At, 1, 1); PG8_STAGE(PG8_SA(1, 0), a3, voffA);
;       PG8_BAR; PG8_WAIT_L(0); PG8_MMA(1, 0, At, B0); PG8_BAR; PG8_SCHED;
	s_add_u32 s48, s20, 0x80000
	s_addc_u32 s49, s21, 0
	s_add_i32 s47, s40, s30
	v_lshl_add_u64 v[154:155], s[48:49], 0, v[132:133]
	s_mov_b32 m0, s47
	s_nop 0
	global_load_lds_dwordx4 v[154:155], off
	v_lshl_add_u64 v[154:155], s[48:49], 0, v[136:137]
	s_add_i32 m0, s47, 0x2000
	s_nop 0
	global_load_lds_dwordx4 v[154:155], off
	s_waitcnt vmcnt(6)
	s_barrier
	v_mfma_f32_16x16x32_bf16 v[54:57], v[202:205], v[170:173], v[54:57]
	v_mfma_f32_16x16x32_bf16 v[50:53], v[210:213], v[170:173], v[50:53]
	v_mfma_f32_16x16x32_bf16 v[38:41], v[202:205], v[178:181], v[38:41]
	v_mfma_f32_16x16x32_bf16 v[34:37], v[210:213], v[178:181], v[34:37]
	v_mfma_f32_16x16x32_bf16 v[22:25], v[202:205], v[186:189], v[22:25]
	v_mfma_f32_16x16x32_bf16 v[18:21], v[210:213], v[186:189], v[18:21]
	v_mfma_f32_16x16x32_bf16 v[6:9], v[202:205], v[194:197], v[6:9]
	v_mfma_f32_16x16x32_bf16 v[2:5], v[210:213], v[194:197], v[2:5]
	v_mfma_f32_16x16x32_bf16 v[54:57], v[206:209], v[174:177], v[54:57]
	v_mfma_f32_16x16x32_bf16 v[50:53], v[214:217], v[174:177], v[50:53]
	v_mfma_f32_16x16x32_bf16 v[38:41], v[206:209], v[182:185], v[38:41]
	v_mfma_f32_16x16x32_bf16 v[34:37], v[214:217], v[182:185], v[34:37]
	v_mfma_f32_16x16x32_bf16 v[22:25], v[206:209], v[190:193], v[22:25]
	v_mfma_f32_16x16x32_bf16 v[18:21], v[214:217], v[190:193], v[18:21]
	v_mfma_f32_16x16x32_bf16 v[6:9], v[206:209], v[198:201], v[6:9]
	v_mfma_f32_16x16x32_bf16 v[2:5], v[214:217], v[198:201], v[2:5]
	s_add_i32 s47, 0, 0x18000
	v_add_u32_e32 v166, s47, v150
	s_barrier
	ds_read_b128 v[154:157], v166
	ds_read_b128 v[158:161], v166 offset:1024
	ds_read_b128 v[162:165], v166 offset:2048
	ds_read_b128 v[166:169], v166 offset:3072
	s_add_u32 s22, s22, 0x80000
	s_addc_u32 s23, s23, 0
	s_mov_b32 m0, s33
	v_lshl_add_u64 v[202:203], s[22:23], 0, v[130:131]
	ds_read_b128 v[170:173], v152 offset:32768
	ds_read_b128 v[174:177], v152 offset:33792
	ds_read_b128 v[178:181], v152 offset:34816
	ds_read_b128 v[182:185], v152 offset:35840
	ds_read_b128 v[186:189], v152 offset:36864
	ds_read_b128 v[190:193], v152 offset:37888
	ds_read_b128 v[194:197], v152 offset:38912
	ds_read_b128 v[198:201], v152 offset:39936
	global_load_lds_dwordx4 v[202:203], off
	v_lshl_add_u64 v[202:203], s[22:23], 0, v[134:135]
	s_mov_b32 m0, s34
	s_nop 0
	global_load_lds_dwordx4 v[202:203], off
	s_waitcnt lgkmcnt(8)
	s_barrier
	s_waitcnt lgkmcnt(0)
	v_mfma_f32_16x16x32_bf16 v[126:129], v[154:157], v[170:173], v[126:129]
	v_mfma_f32_16x16x32_bf16 v[122:125], v[162:165], v[170:173], v[122:125]
	v_mfma_f32_16x16x32_bf16 v[110:113], v[154:157], v[178:181], v[110:113]
	v_mfma_f32_16x16x32_bf16 v[106:109], v[162:165], v[178:181], v[106:109]
	v_mfma_f32_16x16x32_bf16 v[94:97], v[154:157], v[186:189], v[94:97]
	v_mfma_f32_16x16x32_bf16 v[90:93], v[162:165], v[186:189], v[90:93]
	v_mfma_f32_16x16x32_bf16 v[78:81], v[154:157], v[194:197], v[78:81]
	v_mfma_f32_16x16x32_bf16 v[74:77], v[162:165], v[194:197], v[74:77]
	v_mfma_f32_16x16x32_bf16 v[126:129], v[158:161], v[174:177], v[126:129]
	v_mfma_f32_16x16x32_bf16 v[122:125], v[166:169], v[174:177], v[122:125]
	v_mfma_f32_16x16x32_bf16 v[110:113], v[158:161], v[182:185], v[110:113]
	v_mfma_f32_16x16x32_bf16 v[106:109], v[166:169], v[182:185], v[106:109]
	v_mfma_f32_16x16x32_bf16 v[94:97], v[158:161], v[190:193], v[94:97]
	v_mfma_f32_16x16x32_bf16 v[90:93], v[166:169], v[190:193], v[90:93]
	v_mfma_f32_16x16x32_bf16 v[78:81], v[158:161], v[198:201], v[78:81]
	v_mfma_f32_16x16x32_bf16 v[74:77], v[166:169], v[198:201], v[74:77]
	s_barrier
	s_add_i32 s22, 0, 0x1c000
	s_add_i32 s23, s47, s30
	v_add_u32_e32 v214, s22, v150
	v_lshl_add_u64 v[148:149], v[148:149], 0, s[2:3]
	s_mov_b32 m0, s23
	ds_read_b128 v[202:205], v214
	ds_read_b128 v[206:209], v214 offset:1024
	ds_read_b128 v[210:213], v214 offset:2048
	ds_read_b128 v[214:217], v214 offset:3072
	global_load_lds_dwordx4 v[148:149], off
	v_lshl_add_u64 v[148:149], v[218:219], 0, s[2:3]
	s_add_i32 m0, s23, 0x2000
	s_nop 0
	global_load_lds_dwordx4 v[148:149], off
	s_barrier
	s_waitcnt lgkmcnt(0)
	v_mfma_f32_16x16x32_bf16 v[118:121], v[202:205], v[170:173], v[118:121]
	v_mfma_f32_16x16x32_bf16 v[114:117], v[210:213], v[170:173], v[114:117]
	v_mfma_f32_16x16x32_bf16 v[102:105], v[202:205], v[178:181], v[102:105]
	v_mfma_f32_16x16x32_bf16 v[98:101], v[210:213], v[178:181], v[98:101]
	v_mfma_f32_16x16x32_bf16 v[86:89], v[202:205], v[186:189], v[86:89]
	v_mfma_f32_16x16x32_bf16 v[82:85], v[210:213], v[186:189], v[82:85]
	v_mfma_f32_16x16x32_bf16 v[70:73], v[202:205], v[194:197], v[70:73]
	v_mfma_f32_16x16x32_bf16 v[66:69], v[210:213], v[194:197], v[66:69]
	v_mfma_f32_16x16x32_bf16 v[118:121], v[206:209], v[174:177], v[118:121]
	v_mfma_f32_16x16x32_bf16 v[114:117], v[214:217], v[174:177], v[114:117]
	v_mfma_f32_16x16x32_bf16 v[102:105], v[206:209], v[182:185], v[102:105]
	v_mfma_f32_16x16x32_bf16 v[98:101], v[214:217], v[182:185], v[98:101]
	v_mfma_f32_16x16x32_bf16 v[86:89], v[206:209], v[190:193], v[86:89]
	v_mfma_f32_16x16x32_bf16 v[82:85], v[214:217], v[190:193], v[82:85]
	v_mfma_f32_16x16x32_bf16 v[70:73], v[206:209], v[198:201], v[70:73]
	v_mfma_f32_16x16x32_bf16 v[66:69], v[214:217], v[198:201], v[66:69]
	s_mov_b32 m0, s36
	v_lshl_add_u64 v[148:149], v[220:221], 0, s[2:3]
	s_barrier
	ds_read_b128 v[170:173], v152 offset:49152
	ds_read_b128 v[174:177], v152 offset:50176
	ds_read_b128 v[178:181], v152 offset:51200
	ds_read_b128 v[182:185], v152 offset:52224
	ds_read_b128 v[186:189], v152 offset:53248
	ds_read_b128 v[190:193], v152 offset:54272
	ds_read_b128 v[194:197], v152 offset:55296
	ds_read_b128 v[198:201], v152 offset:56320
	global_load_lds_dwordx4 v[148:149], off
	v_lshl_add_u64 v[148:149], v[222:223], 0, s[2:3]
	s_mov_b32 m0, s37
	s_nop 0
	global_load_lds_dwordx4 v[148:149], off
	s_barrier
; DI unsigned pk2(float a, float b) { f32x2 v = {a, b}; bfv2 r = __builtin_convertvector(v, bfv2); return __builtin_bit_cast(unsigned, r); }
; #define PG8_STAGE(bufoff, gbase, voff) do { _Pragma("unroll") for (int _i = 0; _i < 2; ++_i) \
;     __builtin_amdgcn_global_load_lds((const unsigned*)((const char*)(gbase) + (voff)[_i]), (LAS unsigned*)(lds + (bufoff) + ldsw + _i * 8192), 16, 0, 0); } while (0)
; #define PG8_MMA(ai, bj, At, Bt) do { __builtin_amdgcn_s_setprio(1); _Pragma("unroll") for (int m = 0; m < 4; ++m) _Pragma("unroll") for (int n = 0; n < 2; ++n) _Pragma("unroll") for (int k = 0; k < 2; ++k) \
;     acc[ai][bj][m][n] = __builtin_amdgcn_mfma_f32_16x16x32_bf16(Bt[n][k], At[m][k], acc[ai][bj][m][n], 0, 0, 0); __builtin_amdgcn_s_setprio(0); } while (0)
; #define PG8_WAIT_V(n) asm volatile("s_waitcnt vmcnt(" #n ")" ::: "memory")
; #define PG8_WAIT_L(n) asm volatile("s_waitcnt lgkmcnt(" #n ")" ::: "memory")
; #define PG8_BAR __builtin_amdgcn_s_barrier()
; #define PG8_SCHED __builtin_amdgcn_sched_barrier(0)
; template <class Epi>
; DI void gemm_phase(LAS unsigned char* lds, const Gemm g, const StaticOrder& S, const Epi& E) {
;     ...
;       PG8_BAR; PG8_WAIT_L(0); PG8_MMA(1, 0, At, B0); PG8_BAR; PG8_SCHED;
;       PG8_STAGE(PG8_SB(1, 1), b3 + hstepB, voffB);
;       PG8_WAIT_V(6); PG8_BAR; PG8_MMA(1, 1, At, B1); PG8_BAR;
;     }
;     E(acc, cur, wr, wc, fr, fq);
;   DI void operator()(const f32x4 (&acc)[2][2][4][2], const pg8::Unit& u, int wr, int wc, int fr, int fq) const {
;     ...
;         if (MODE == EP_UP) rs = ((const float*)(ws + OFF_RS2))[grow];
;     ...
;           f32x4 v0 = acc[ai][bj][m][0] * rs, v1 = acc[ai][bj][m][1] * rs;
;     ...
;           if (MODE == EP_UP) {
; #pragma unroll
;             for (int j = 0; j < 4; ++j) { float a = fmaxf(v0[j], 0.f), b = fmaxf(v1[j], 0.f); v0[j] = a * a; v1[j] = b * b; }
;           }
;     ...
;             dst = (bf16_t*)(ws + OFF_U) + (size_t)row * 8192 + pn * 256 + ct;
;           } else {
;             dst = (bf16_t*)dout + (size_t)grow * 4096 + pn * 256 + ct;
;           }
;           u32x4 w = {pk2(v0[0], v0[1]), pk2(v0[2], v0[3]), pk2(v1[0], v1[1]), pk2(v1[2], v1[3])};
;           *(u32x4*)dst = w;
	s_waitcnt lgkmcnt(0)
	v_mfma_f32_16x16x32_bf16 v[62:65], v[154:157], v[170:173], v[62:65]
	v_mfma_f32_16x16x32_bf16 v[58:61], v[162:165], v[170:173], v[58:61]
	v_mfma_f32_16x16x32_bf16 v[46:49], v[154:157], v[178:181], v[46:49]
	v_mfma_f32_16x16x32_bf16 v[42:45], v[162:165], v[178:181], v[42:45]
	v_mfma_f32_16x16x32_bf16 v[30:33], v[154:157], v[186:189], v[30:33]
	v_mfma_f32_16x16x32_bf16 v[26:29], v[162:165], v[186:189], v[26:29]
	v_mfma_f32_16x16x32_bf16 v[14:17], v[154:157], v[194:197], v[14:17]
	v_mfma_f32_16x16x32_bf16 v[10:13], v[162:165], v[194:197], v[10:13]
	v_mfma_f32_16x16x32_bf16 v[62:65], v[158:161], v[174:177], v[62:65]
	v_mfma_f32_16x16x32_bf16 v[58:61], v[166:169], v[174:177], v[58:61]
	v_mfma_f32_16x16x32_bf16 v[46:49], v[158:161], v[182:185], v[46:49]
	v_mfma_f32_16x16x32_bf16 v[42:45], v[166:169], v[182:185], v[42:45]
	v_mfma_f32_16x16x32_bf16 v[30:33], v[158:161], v[190:193], v[30:33]
	v_mfma_f32_16x16x32_bf16 v[26:29], v[166:169], v[190:193], v[26:29]
	v_mfma_f32_16x16x32_bf16 v[14:17], v[158:161], v[198:201], v[14:17]
	v_mfma_f32_16x16x32_bf16 v[10:13], v[166:169], v[198:201], v[10:13]
	s_barrier
	s_add_u32 s20, s20, 0x80080
	s_addc_u32 s21, s21, 0
	s_add_i32 s22, s22, s30
	v_lshl_add_u64 v[148:149], s[20:21], 0, v[132:133]
	s_mov_b32 m0, s22
	s_nop 0
	global_load_lds_dwordx4 v[148:149], off
	v_lshl_add_u64 v[148:149], s[20:21], 0, v[136:137]
	s_add_i32 m0, s22, 0x2000
	s_nop 0
	global_load_lds_dwordx4 v[148:149], off
	s_waitcnt vmcnt(6)
	s_barrier
	v_mfma_f32_16x16x32_bf16 v[54:57], v[202:205], v[170:173], v[54:57]
	v_mfma_f32_16x16x32_bf16 v[50:53], v[210:213], v[170:173], v[50:53]
	v_mfma_f32_16x16x32_bf16 v[38:41], v[202:205], v[178:181], v[38:41]
	v_mfma_f32_16x16x32_bf16 v[34:37], v[210:213], v[178:181], v[34:37]
	v_mfma_f32_16x16x32_bf16 v[22:25], v[202:205], v[186:189], v[22:25]
	v_mfma_f32_16x16x32_bf16 v[18:21], v[210:213], v[186:189], v[18:21]
	v_mfma_f32_16x16x32_bf16 v[6:9], v[202:205], v[194:197], v[6:9]
	v_mfma_f32_16x16x32_bf16 v[2:5], v[210:213], v[194:197], v[2:5]
	v_mfma_f32_16x16x32_bf16 v[54:57], v[206:209], v[174:177], v[54:57]
	v_mfma_f32_16x16x32_bf16 v[50:53], v[214:217], v[174:177], v[50:53]
	v_mfma_f32_16x16x32_bf16 v[38:41], v[206:209], v[182:185], v[38:41]
	v_mfma_f32_16x16x32_bf16 v[34:37], v[214:217], v[182:185], v[34:37]
	v_mfma_f32_16x16x32_bf16 v[22:25], v[206:209], v[190:193], v[22:25]
	v_mfma_f32_16x16x32_bf16 v[18:21], v[214:217], v[190:193], v[18:21]
	v_mfma_f32_16x16x32_bf16 v[6:9], v[206:209], v[198:201], v[6:9]
	v_mfma_f32_16x16x32_bf16 v[2:5], v[214:217], v[198:201], v[2:5]
	s_add_i32 s46, s46, 2
	s_add_u32 s18, s18, 0x100
	s_addc_u32 s19, s19, 0
	s_add_u32 s44, s44, 0x100
	s_addc_u32 s45, s45, 0
	s_cmp_gt_u32 s46, 29
	s_barrier
	s_cbranch_scc0 .LBB0_921
	v_lshl_add_u32 v148, s16, 8, v1
	v_ashrrev_i32_e32 v149, 31, v148
	v_lshl_add_u64 v[154:155], v[148:149], 2, s[4:5]
	s_nop 0
	s_lshl_b32 s18, s41, 8
	s_ashr_i32 s19, s18, 31
	v_lshlrev_b64 v[158:159], 14, v[148:149]
	s_lshl_b64 s[18:19], s[18:19], 1
	v_lshl_add_u64 v[158:159], s[6:7], 0, v[158:159]
	v_or_b32_e32 v156, 16, v148
	v_lshl_add_u64 v[158:159], v[158:159], 0, s[18:19]
	v_ashrrev_i32_e32 v157, 31, v156
	v_lshl_add_u64 v[158:159], v[158:159], 0, v[138:139]
	v_lshl_add_u64 v[160:161], v[156:157], 2, s[4:5]
	s_and_b64 vcc, exec, s[0:1]
	s_mov_b32 s41, s8
	s_mov_b32 s16, s10
	s_mov_b64 s[20:21], s[14:15]
	s_mov_b64 s[22:23], s[12:13]
	v_mov_b32_e32 v154, v247
	v_pk_mul_f32 v[128:129], v[128:129], v[154:155] op_sel_hi:[1,0]
	v_pk_mul_f32 v[126:127], v[126:127], v[154:155] op_sel_hi:[1,0]
	v_pk_mul_f32 v[124:125], v[124:125], v[154:155] op_sel_hi:[1,0]
	v_pk_mul_f32 v[122:123], v[122:123], v[154:155] op_sel_hi:[1,0]
	v_pk_mul_f32 v[120:121], v[120:121], v[154:155] op_sel_hi:[1,0]
	v_pk_mul_f32 v[118:119], v[118:119], v[154:155] op_sel_hi:[1,0]
	v_pk_mul_f32 v[116:117], v[116:117], v[154:155] op_sel_hi:[1,0]
	v_pk_mul_f32 v[114:115], v[114:115], v[154:155] op_sel_hi:[1,0]
	v_max_f32_e32 v126, 0, v126
	v_max_f32_e32 v122, 0, v122
	v_max_f32_e32 v127, 0, v127
	v_max_f32_e32 v123, 0, v123
	v_max_f32_e32 v128, 0, v128
	v_max_f32_e32 v124, 0, v124
	v_max_f32_e32 v129, 0, v129
	v_max_f32_e32 v125, 0, v125
	v_max_f32_e32 v118, 0, v118
	v_max_f32_e32 v114, 0, v114
	v_max_f32_e32 v119, 0, v119
	v_max_f32_e32 v115, 0, v115
	v_max_f32_e32 v120, 0, v120
	v_max_f32_e32 v116, 0, v116
	v_max_f32_e32 v121, 0, v121
	v_max_f32_e32 v117, 0, v117
	v_pk_mul_f32 v[126:127], v[126:127], v[126:127]
	v_pk_mul_f32 v[122:123], v[122:123], v[122:123]
	v_pk_mul_f32 v[128:129], v[128:129], v[128:129]
	v_pk_mul_f32 v[124:125], v[124:125], v[124:125]
	v_pk_mul_f32 v[118:119], v[118:119], v[118:119]
	v_pk_mul_f32 v[154:155], v[114:115], v[114:115]
	v_pk_mul_f32 v[120:121], v[120:121], v[120:121]
	v_pk_mul_f32 v[162:163], v[116:117], v[116:117]
	v_cvt_pk_bf16_f32 v114, v126, v127
	v_cvt_pk_bf16_f32 v115, v128, v129
	v_cvt_pk_bf16_f32 v116, v122, v123
	v_cvt_pk_bf16_f32 v117, v124, v125
	v_cvt_pk_bf16_f32 v118, v118, v119
	v_cvt_pk_bf16_f32 v119, v120, v121
	v_cvt_pk_bf16_f32 v120, v154, v155
	v_cvt_pk_bf16_f32 v121, v162, v163
	global_store_dwordx4 v[158:159], v[114:117], off
	global_store_dwordx4 v[158:159], v[118:121], off offset:256
	s_nop 0
	v_or_b32_e32 v116, 32, v148
	v_lshlrev_b64 v[118:119], 14, v[156:157]
	v_lshl_add_u64 v[118:119], s[6:7], 0, v[118:119]
	v_lshl_add_u64 v[118:119], v[118:119], 0, s[18:19]
	v_ashrrev_i32_e32 v117, 31, v116
	v_lshl_add_u64 v[118:119], v[118:119], 0, v[138:139]
	v_lshl_add_u64 v[120:121], v[116:117], 2, s[4:5]
	v_mov_b32_e32 v114, v240
	v_pk_mul_f32 v[112:113], v[112:113], v[114:115] op_sel_hi:[1,0]
;   DI void operator()(const f32x4 (&acc)[2][2][4][2], const pg8::Unit& u, int wr, int wc, int fr, int fq) const {
;     ...
;           f32x4 v0 = acc[ai][bj][m][0] * rs, v1 = acc[ai][bj][m][1] * rs;
;           if (MODE == EP_IN || MODE == EP_MIX || MODE == EP_DOWN) {
; #pragma unroll
;             for (int j = 0; j < 4; ++j) ssq += v0[j] * v0[j] + v1[j] * v1[j];
;           }
;           if (MODE == EP_UP) {
; #pragma unroll
;             for (int j = 0; j < 4; ++j) { float a = fmaxf(v0[j], 0.f), b = fmaxf(v1[j], 0.f); v0[j] = a * a; v1[j] = b * b; }
;           }
;           bf16_t* dst;
;           const int ct = bj * 128 + cl;
;           if (MODE == EP_IN) {
;             if (pn < 4) dst = (bf16_t*)(ws + OFF_PROJA) + (size_t)grow * 1024 + pn * 256 + ct;
;             else if (pn < 16) dst = (bf16_t*)(ws + OFF_PROJG) + (size_t)grow * 3072 + (pn - 4) * 256 + ct;
;             else dst = (bf16_t*)(ws + OFF_PROJS) + (size_t)grow * 256 + ct;
;           } else if (MODE == EP_Q) {
;             if (pn < 4) dst = (bf16_t*)(dout + DO_Q) + (size_t)grow * 1536 + (pn * 2 + bj) * 192 + cl;
;             else {
;               const int mm = (pn - 4) * 256 + ct, h = mm >> 6, r = mm & 63;
;               dst = (bf16_t*)(dout + DO_Q) + (size_t)grow * 1536 + h * 192 + 128 + r;
;               const int pos = grow < TP ? (grow & 4095) : grow - TP;
;               const f32x4* tb = (const f32x4*)((const f32x2*)(ws + OFF_ROPE) + pos * 32 + (r >> 1));
;               const f32x4 t0 = tb[0], t1 = tb[1];
;               f32x4 o0, o1;
;               o0[0] = v0[0] * t0[0] - v0[1] * t0[1]; o0[1] = v0[1] * t0[0] + v0[0] * t0[1];
;               o0[2] = v0[2] * t0[2] - v0[3] * t0[3]; o0[3] = v0[3] * t0[2] + v0[2] * t0[3];
;               o1[0] = v1[0] * t1[0] - v1[1] * t1[1]; o1[1] = v1[1] * t1[0] + v1[0] * t1[1];
;               o1[2] = v1[2] * t1[2] - v1[3] * t1[3]; o1[3] = v1[3] * t1[2] + v1[2] * t1[3];
;               v0 = o0; v1 = o1;
;             }
;           } else if (MODE == EP_KV) {
;             dst = (bf16_t*)(ws + OFF_XB) + (size_t)grow * 2048 + pn * 256 + ct;
;           } else if (MODE == EP_MIX) {
;             dst = (bf16_t*)(ws + OFF_MIX) + (size_t)grow * 2048 + pn * 256 + ct;
;           } else if (MODE == EP_UP) {
;             dst = (bf16_t*)(ws + OFF_U) + (size_t)row * 8192 + pn * 256 + ct;
;           } else {
	v_pk_mul_f32 v[110:111], v[110:111], v[114:115] op_sel_hi:[1,0]
	v_pk_mul_f32 v[108:109], v[108:109], v[114:115] op_sel_hi:[1,0]
	v_pk_mul_f32 v[106:107], v[106:107], v[114:115] op_sel_hi:[1,0]
	v_pk_mul_f32 v[104:105], v[104:105], v[114:115] op_sel_hi:[1,0]
	v_pk_mul_f32 v[102:103], v[102:103], v[114:115] op_sel_hi:[1,0]
	v_pk_mul_f32 v[100:101], v[100:101], v[114:115] op_sel_hi:[1,0]
	v_pk_mul_f32 v[98:99], v[98:99], v[114:115] op_sel_hi:[1,0]
	v_max_f32_e32 v110, 0, v110
	v_max_f32_e32 v106, 0, v106
	v_max_f32_e32 v111, 0, v111
	v_max_f32_e32 v107, 0, v107
	v_max_f32_e32 v112, 0, v112
	v_max_f32_e32 v108, 0, v108
	v_max_f32_e32 v113, 0, v113
	v_max_f32_e32 v109, 0, v109
	v_max_f32_e32 v102, 0, v102
	v_max_f32_e32 v98, 0, v98
	v_max_f32_e32 v103, 0, v103
	v_max_f32_e32 v99, 0, v99
	v_max_f32_e32 v104, 0, v104
	v_max_f32_e32 v100, 0, v100
	v_max_f32_e32 v105, 0, v105
	v_max_f32_e32 v101, 0, v101
	v_pk_mul_f32 v[110:111], v[110:111], v[110:111]
	v_pk_mul_f32 v[106:107], v[106:107], v[106:107]
	v_pk_mul_f32 v[112:113], v[112:113], v[112:113]
	v_pk_mul_f32 v[108:109], v[108:109], v[108:109]
	v_pk_mul_f32 v[102:103], v[102:103], v[102:103]
	v_pk_mul_f32 v[114:115], v[98:99], v[98:99]
	v_pk_mul_f32 v[104:105], v[104:105], v[104:105]
	v_pk_mul_f32 v[122:123], v[100:101], v[100:101]
	v_cvt_pk_bf16_f32 v98, v110, v111
	v_cvt_pk_bf16_f32 v99, v112, v113
	v_cvt_pk_bf16_f32 v100, v106, v107
	v_cvt_pk_bf16_f32 v101, v108, v109
	v_cvt_pk_bf16_f32 v102, v102, v103
	v_cvt_pk_bf16_f32 v103, v104, v105
	v_cvt_pk_bf16_f32 v104, v114, v115
	v_cvt_pk_bf16_f32 v105, v122, v123
	global_store_dwordx4 v[118:119], v[98:101], off
	global_store_dwordx4 v[118:119], v[102:105], off offset:256
	s_nop 0
	v_or_b32_e32 v100, 48, v148
	v_lshlrev_b64 v[102:103], 14, v[116:117]
	v_lshl_add_u64 v[102:103], s[6:7], 0, v[102:103]
	v_lshl_add_u64 v[102:103], v[102:103], 0, s[18:19]
	v_ashrrev_i32_e32 v101, 31, v100
	v_lshl_add_u64 v[102:103], v[102:103], 0, v[138:139]
	v_lshl_add_u64 v[104:105], v[100:101], 2, s[4:5]
	v_mov_b32_e32 v98, v241
	v_pk_mul_f32 v[96:97], v[96:97], v[98:99] op_sel_hi:[1,0]
	v_pk_mul_f32 v[94:95], v[94:95], v[98:99] op_sel_hi:[1,0]
	v_pk_mul_f32 v[92:93], v[92:93], v[98:99] op_sel_hi:[1,0]
	v_pk_mul_f32 v[90:91], v[90:91], v[98:99] op_sel_hi:[1,0]
	v_pk_mul_f32 v[88:89], v[88:89], v[98:99] op_sel_hi:[1,0]
	v_pk_mul_f32 v[86:87], v[86:87], v[98:99] op_sel_hi:[1,0]
	v_pk_mul_f32 v[84:85], v[84:85], v[98:99] op_sel_hi:[1,0]
	v_pk_mul_f32 v[82:83], v[82:83], v[98:99] op_sel_hi:[1,0]
	v_max_f32_e32 v94, 0, v94
	v_max_f32_e32 v90, 0, v90
	v_max_f32_e32 v95, 0, v95
	v_max_f32_e32 v91, 0, v91
	v_max_f32_e32 v96, 0, v96
	v_max_f32_e32 v92, 0, v92
	v_max_f32_e32 v97, 0, v97
	v_max_f32_e32 v93, 0, v93
	v_max_f32_e32 v86, 0, v86
	v_max_f32_e32 v82, 0, v82
	v_max_f32_e32 v87, 0, v87
	v_max_f32_e32 v83, 0, v83
	v_max_f32_e32 v88, 0, v88
	v_max_f32_e32 v84, 0, v84
	v_max_f32_e32 v89, 0, v89
	v_max_f32_e32 v85, 0, v85
	v_pk_mul_f32 v[94:95], v[94:95], v[94:95]
	v_pk_mul_f32 v[90:91], v[90:91], v[90:91]
	v_pk_mul_f32 v[96:97], v[96:97], v[96:97]
	v_pk_mul_f32 v[92:93], v[92:93], v[92:93]
	v_pk_mul_f32 v[86:87], v[86:87], v[86:87]
	v_pk_mul_f32 v[98:99], v[82:83], v[82:83]
	v_pk_mul_f32 v[88:89], v[88:89], v[88:89]
	v_pk_mul_f32 v[106:107], v[84:85], v[84:85]
	v_cvt_pk_bf16_f32 v82, v94, v95
	v_cvt_pk_bf16_f32 v83, v96, v97
	v_cvt_pk_bf16_f32 v84, v90, v91
	v_cvt_pk_bf16_f32 v85, v92, v93
	v_cvt_pk_bf16_f32 v86, v86, v87
	v_cvt_pk_bf16_f32 v87, v88, v89
	v_cvt_pk_bf16_f32 v88, v98, v99
	v_cvt_pk_bf16_f32 v89, v106, v107
	global_store_dwordx4 v[102:103], v[82:85], off
	global_store_dwordx4 v[102:103], v[86:89], off offset:256
	s_nop 0
	v_add_u32_e32 v84, 0x80, v148
	v_lshlrev_b64 v[86:87], 14, v[100:101]
	v_lshl_add_u64 v[86:87], s[6:7], 0, v[86:87]
	v_lshl_add_u64 v[86:87], v[86:87], 0, s[18:19]
	v_ashrrev_i32_e32 v85, 31, v84
	v_lshl_add_u64 v[86:87], v[86:87], 0, v[138:139]
	v_lshl_add_u64 v[88:89], v[84:85], 2, s[4:5]
	v_mov_b32_e32 v82, v242
	v_pk_mul_f32 v[80:81], v[80:81], v[82:83] op_sel_hi:[1,0]
	v_pk_mul_f32 v[78:79], v[78:79], v[82:83] op_sel_hi:[1,0]
	v_pk_mul_f32 v[76:77], v[76:77], v[82:83] op_sel_hi:[1,0]
	v_pk_mul_f32 v[74:75], v[74:75], v[82:83] op_sel_hi:[1,0]
	v_pk_mul_f32 v[72:73], v[72:73], v[82:83] op_sel_hi:[1,0]
	v_pk_mul_f32 v[70:71], v[70:71], v[82:83] op_sel_hi:[1,0]
	v_pk_mul_f32 v[68:69], v[68:69], v[82:83] op_sel_hi:[1,0]
	v_pk_mul_f32 v[66:67], v[66:67], v[82:83] op_sel_hi:[1,0]
	v_max_f32_e32 v78, 0, v78
	v_max_f32_e32 v74, 0, v74
	v_max_f32_e32 v79, 0, v79
	v_max_f32_e32 v75, 0, v75
	v_max_f32_e32 v80, 0, v80
	v_max_f32_e32 v76, 0, v76
	v_max_f32_e32 v81, 0, v81
	v_max_f32_e32 v77, 0, v77
	v_max_f32_e32 v70, 0, v70
	v_max_f32_e32 v66, 0, v66
	v_max_f32_e32 v71, 0, v71
	v_max_f32_e32 v67, 0, v67
	v_max_f32_e32 v72, 0, v72
	v_max_f32_e32 v68, 0, v68
	v_max_f32_e32 v73, 0, v73
	v_max_f32_e32 v69, 0, v69
	v_pk_mul_f32 v[78:79], v[78:79], v[78:79]
	v_pk_mul_f32 v[74:75], v[74:75], v[74:75]
	v_pk_mul_f32 v[80:81], v[80:81], v[80:81]
	v_pk_mul_f32 v[76:77], v[76:77], v[76:77]
	v_pk_mul_f32 v[70:71], v[70:71], v[70:71]
	v_pk_mul_f32 v[82:83], v[66:67], v[66:67]
	v_pk_mul_f32 v[72:73], v[72:73], v[72:73]
	v_pk_mul_f32 v[90:91], v[68:69], v[68:69]
	v_cvt_pk_bf16_f32 v66, v78, v79
	v_cvt_pk_bf16_f32 v67, v80, v81
	v_cvt_pk_bf16_f32 v68, v74, v75
	v_cvt_pk_bf16_f32 v69, v76, v77
	v_cvt_pk_bf16_f32 v70, v70, v71
	v_cvt_pk_bf16_f32 v71, v72, v73
	v_cvt_pk_bf16_f32 v72, v82, v83
	v_cvt_pk_bf16_f32 v73, v90, v91
	global_store_dwordx4 v[86:87], v[66:69], off
	global_store_dwordx4 v[86:87], v[70:73], off offset:256
	s_nop 0
	v_add_u32_e32 v68, 0x90, v148
;   DI void operator()(const f32x4 (&acc)[2][2][4][2], const pg8::Unit& u, int wr, int wc, int fr, int fq) const {
;     ...
;           f32x4 v0 = acc[ai][bj][m][0] * rs, v1 = acc[ai][bj][m][1] * rs;
;           if (MODE == EP_IN || MODE == EP_MIX || MODE == EP_DOWN) {
; #pragma unroll
;             for (int j = 0; j < 4; ++j) ssq += v0[j] * v0[j] + v1[j] * v1[j];
;           }
;           if (MODE == EP_UP) {
; #pragma unroll
;             for (int j = 0; j < 4; ++j) { float a = fmaxf(v0[j], 0.f), b = fmaxf(v1[j], 0.f); v0[j] = a * a; v1[j] = b * b; }
;           }
;           bf16_t* dst;
;           const int ct = bj * 128 + cl;
;           if (MODE == EP_IN) {
;             if (pn < 4) dst = (bf16_t*)(ws + OFF_PROJA) + (size_t)grow * 1024 + pn * 256 + ct;
;             else if (pn < 16) dst = (bf16_t*)(ws + OFF_PROJG) + (size_t)grow * 3072 + (pn - 4) * 256 + ct;
;             else dst = (bf16_t*)(ws + OFF_PROJS) + (size_t)grow * 256 + ct;
;           } else if (MODE == EP_Q) {
;             if (pn < 4) dst = (bf16_t*)(dout + DO_Q) + (size_t)grow * 1536 + (pn * 2 + bj) * 192 + cl;
;             else {
;               const int mm = (pn - 4) * 256 + ct, h = mm >> 6, r = mm & 63;
;               dst = (bf16_t*)(dout + DO_Q) + (size_t)grow * 1536 + h * 192 + 128 + r;
;               const int pos = grow < TP ? (grow & 4095) : grow - TP;
;               const f32x4* tb = (const f32x4*)((const f32x2*)(ws + OFF_ROPE) + pos * 32 + (r >> 1));
;               const f32x4 t0 = tb[0], t1 = tb[1];
;               f32x4 o0, o1;
;               o0[0] = v0[0] * t0[0] - v0[1] * t0[1]; o0[1] = v0[1] * t0[0] + v0[0] * t0[1];
;               o0[2] = v0[2] * t0[2] - v0[3] * t0[3]; o0[3] = v0[3] * t0[2] + v0[2] * t0[3];
;               o1[0] = v1[0] * t1[0] - v1[1] * t1[1]; o1[1] = v1[1] * t1[0] + v1[0] * t1[1];
;               o1[2] = v1[2] * t1[2] - v1[3] * t1[3]; o1[3] = v1[3] * t1[2] + v1[2] * t1[3];
;               v0 = o0; v1 = o1;
;             }
;           } else if (MODE == EP_KV) {
;             dst = (bf16_t*)(ws + OFF_XB) + (size_t)grow * 2048 + pn * 256 + ct;
;           } else if (MODE == EP_MIX) {
;             dst = (bf16_t*)(ws + OFF_MIX) + (size_t)grow * 2048 + pn * 256 + ct;
;           } else if (MODE == EP_UP) {
;             dst = (bf16_t*)(ws + OFF_U) + (size_t)row * 8192 + pn * 256 + ct;
;           } else {
	v_lshlrev_b64 v[70:71], 14, v[84:85]
	v_lshl_add_u64 v[70:71], s[6:7], 0, v[70:71]
	v_lshl_add_u64 v[70:71], v[70:71], 0, s[18:19]
	v_ashrrev_i32_e32 v69, 31, v68
	v_lshl_add_u64 v[70:71], v[70:71], 0, v[138:139]
	v_lshl_add_u64 v[72:73], v[68:69], 2, s[4:5]
	v_mov_b32_e32 v66, v243
	v_pk_mul_f32 v[64:65], v[64:65], v[66:67] op_sel_hi:[1,0]
	v_pk_mul_f32 v[62:63], v[62:63], v[66:67] op_sel_hi:[1,0]
	v_pk_mul_f32 v[60:61], v[60:61], v[66:67] op_sel_hi:[1,0]
	v_pk_mul_f32 v[58:59], v[58:59], v[66:67] op_sel_hi:[1,0]
	v_pk_mul_f32 v[56:57], v[56:57], v[66:67] op_sel_hi:[1,0]
	v_pk_mul_f32 v[54:55], v[54:55], v[66:67] op_sel_hi:[1,0]
	v_pk_mul_f32 v[52:53], v[52:53], v[66:67] op_sel_hi:[1,0]
	v_pk_mul_f32 v[50:51], v[50:51], v[66:67] op_sel_hi:[1,0]
	v_max_f32_e32 v62, 0, v62
	v_max_f32_e32 v58, 0, v58
	v_max_f32_e32 v63, 0, v63
	v_max_f32_e32 v59, 0, v59
	v_max_f32_e32 v64, 0, v64
	v_max_f32_e32 v60, 0, v60
	v_max_f32_e32 v65, 0, v65
	v_max_f32_e32 v61, 0, v61
	v_max_f32_e32 v54, 0, v54
	v_max_f32_e32 v50, 0, v50
	v_max_f32_e32 v55, 0, v55
	v_max_f32_e32 v51, 0, v51
	v_max_f32_e32 v56, 0, v56
	v_max_f32_e32 v52, 0, v52
	v_max_f32_e32 v57, 0, v57
	v_max_f32_e32 v53, 0, v53
	v_pk_mul_f32 v[62:63], v[62:63], v[62:63]
	v_pk_mul_f32 v[58:59], v[58:59], v[58:59]
	v_pk_mul_f32 v[64:65], v[64:65], v[64:65]
	v_pk_mul_f32 v[60:61], v[60:61], v[60:61]
	v_pk_mul_f32 v[54:55], v[54:55], v[54:55]
	v_pk_mul_f32 v[66:67], v[50:51], v[50:51]
	v_pk_mul_f32 v[56:57], v[56:57], v[56:57]
	v_pk_mul_f32 v[74:75], v[52:53], v[52:53]
	v_cvt_pk_bf16_f32 v50, v62, v63
	v_cvt_pk_bf16_f32 v51, v64, v65
	v_cvt_pk_bf16_f32 v52, v58, v59
	v_cvt_pk_bf16_f32 v53, v60, v61
	v_cvt_pk_bf16_f32 v54, v54, v55
	v_cvt_pk_bf16_f32 v55, v56, v57
	v_cvt_pk_bf16_f32 v56, v66, v67
	v_cvt_pk_bf16_f32 v57, v74, v75
	global_store_dwordx4 v[70:71], v[50:53], off
	global_store_dwordx4 v[70:71], v[54:57], off offset:256
	s_nop 0
	v_add_u32_e32 v52, 0xa0, v148
	v_lshlrev_b64 v[54:55], 14, v[68:69]
	v_lshl_add_u64 v[54:55], s[6:7], 0, v[54:55]
	v_lshl_add_u64 v[54:55], v[54:55], 0, s[18:19]
	v_ashrrev_i32_e32 v53, 31, v52
	v_lshl_add_u64 v[54:55], v[54:55], 0, v[138:139]
	v_lshl_add_u64 v[56:57], v[52:53], 2, s[4:5]
	v_mov_b32_e32 v50, v244
	v_pk_mul_f32 v[48:49], v[48:49], v[50:51] op_sel_hi:[1,0]
	v_pk_mul_f32 v[46:47], v[46:47], v[50:51] op_sel_hi:[1,0]
	v_pk_mul_f32 v[44:45], v[44:45], v[50:51] op_sel_hi:[1,0]
	v_pk_mul_f32 v[42:43], v[42:43], v[50:51] op_sel_hi:[1,0]
	v_pk_mul_f32 v[40:41], v[40:41], v[50:51] op_sel_hi:[1,0]
	v_pk_mul_f32 v[38:39], v[38:39], v[50:51] op_sel_hi:[1,0]
	v_pk_mul_f32 v[36:37], v[36:37], v[50:51] op_sel_hi:[1,0]
	v_pk_mul_f32 v[34:35], v[34:35], v[50:51] op_sel_hi:[1,0]
	v_max_f32_e32 v46, 0, v46
	v_max_f32_e32 v42, 0, v42
	v_max_f32_e32 v47, 0, v47
	v_max_f32_e32 v43, 0, v43
	v_max_f32_e32 v48, 0, v48
	v_max_f32_e32 v44, 0, v44
	v_max_f32_e32 v49, 0, v49
	v_max_f32_e32 v45, 0, v45
	v_max_f32_e32 v38, 0, v38
	v_max_f32_e32 v34, 0, v34
	v_max_f32_e32 v39, 0, v39
	v_max_f32_e32 v35, 0, v35
	v_max_f32_e32 v40, 0, v40
	v_max_f32_e32 v36, 0, v36
	v_max_f32_e32 v41, 0, v41
	v_max_f32_e32 v37, 0, v37
	v_pk_mul_f32 v[46:47], v[46:47], v[46:47]
	v_pk_mul_f32 v[42:43], v[42:43], v[42:43]
	v_pk_mul_f32 v[48:49], v[48:49], v[48:49]
	v_pk_mul_f32 v[44:45], v[44:45], v[44:45]
	v_pk_mul_f32 v[38:39], v[38:39], v[38:39]
	v_pk_mul_f32 v[50:51], v[34:35], v[34:35]
	v_pk_mul_f32 v[40:41], v[40:41], v[40:41]
	v_pk_mul_f32 v[58:59], v[36:37], v[36:37]
	v_cvt_pk_bf16_f32 v34, v46, v47
	v_cvt_pk_bf16_f32 v35, v48, v49
	v_cvt_pk_bf16_f32 v36, v42, v43
	v_cvt_pk_bf16_f32 v37, v44, v45
	v_cvt_pk_bf16_f32 v38, v38, v39
	v_cvt_pk_bf16_f32 v39, v40, v41
	v_cvt_pk_bf16_f32 v40, v50, v51
	v_cvt_pk_bf16_f32 v41, v58, v59
	global_store_dwordx4 v[54:55], v[34:37], off
	global_store_dwordx4 v[54:55], v[38:41], off offset:256
;   DI void operator()(const f32x4 (&acc)[2][2][4][2], const pg8::Unit& u, int wr, int wc, int fr, int fq) const {
;     ...
;           f32x4 v0 = acc[ai][bj][m][0] * rs, v1 = acc[ai][bj][m][1] * rs;
;           if (MODE == EP_IN || MODE == EP_MIX || MODE == EP_DOWN) {
; #pragma unroll
;             for (int j = 0; j < 4; ++j) ssq += v0[j] * v0[j] + v1[j] * v1[j];
;           }
;           if (MODE == EP_UP) {
; #pragma unroll
;             for (int j = 0; j < 4; ++j) { float a = fmaxf(v0[j], 0.f), b = fmaxf(v1[j], 0.f); v0[j] = a * a; v1[j] = b * b; }
;           }
;           bf16_t* dst;
;           const int ct = bj * 128 + cl;
;           if (MODE == EP_IN) {
;             if (pn < 4) dst = (bf16_t*)(ws + OFF_PROJA) + (size_t)grow * 1024 + pn * 256 + ct;
;             else if (pn < 16) dst = (bf16_t*)(ws + OFF_PROJG) + (size_t)grow * 3072 + (pn - 4) * 256 + ct;
;             else dst = (bf16_t*)(ws + OFF_PROJS) + (size_t)grow * 256 + ct;
;           } else if (MODE == EP_Q) {
;             if (pn < 4) dst = (bf16_t*)(dout + DO_Q) + (size_t)grow * 1536 + (pn * 2 + bj) * 192 + cl;
;             else {
;               const int mm = (pn - 4) * 256 + ct, h = mm >> 6, r = mm & 63;
;               dst = (bf16_t*)(dout + DO_Q) + (size_t)grow * 1536 + h * 192 + 128 + r;
;               const int pos = grow < TP ? (grow & 4095) : grow - TP;
;               const f32x4* tb = (const f32x4*)((const f32x2*)(ws + OFF_ROPE) + pos * 32 + (r >> 1));
;               const f32x4 t0 = tb[0], t1 = tb[1];
;               f32x4 o0, o1;
;               o0[0] = v0[0] * t0[0] - v0[1] * t0[1]; o0[1] = v0[1] * t0[0] + v0[0] * t0[1];
;               o0[2] = v0[2] * t0[2] - v0[3] * t0[3]; o0[3] = v0[3] * t0[2] + v0[2] * t0[3];
;               o1[0] = v1[0] * t1[0] - v1[1] * t1[1]; o1[1] = v1[1] * t1[0] + v1[0] * t1[1];
;               o1[2] = v1[2] * t1[2] - v1[3] * t1[3]; o1[3] = v1[3] * t1[2] + v1[2] * t1[3];
;               v0 = o0; v1 = o1;
;             }
;           } else if (MODE == EP_KV) {
;             dst = (bf16_t*)(ws + OFF_XB) + (size_t)grow * 2048 + pn * 256 + ct;
;           } else if (MODE == EP_MIX) {
;             dst = (bf16_t*)(ws + OFF_MIX) + (size_t)grow * 2048 + pn * 256 + ct;
;           } else if (MODE == EP_UP) {
;             dst = (bf16_t*)(ws + OFF_U) + (size_t)row * 8192 + pn * 256 + ct;
;           } else {
	s_nop 0
	v_add_u32_e32 v36, 0xb0, v148
	v_lshlrev_b64 v[38:39], 14, v[52:53]
	v_lshl_add_u64 v[38:39], s[6:7], 0, v[38:39]
	v_lshl_add_u64 v[38:39], v[38:39], 0, s[18:19]
	v_ashrrev_i32_e32 v37, 31, v36
	v_lshl_add_u64 v[38:39], v[38:39], 0, v[138:139]
	v_lshl_add_u64 v[40:41], v[36:37], 2, s[4:5]
	v_mov_b32_e32 v34, v245
	v_pk_mul_f32 v[32:33], v[32:33], v[34:35] op_sel_hi:[1,0]
	v_pk_mul_f32 v[30:31], v[30:31], v[34:35] op_sel_hi:[1,0]
	v_pk_mul_f32 v[28:29], v[28:29], v[34:35] op_sel_hi:[1,0]
	v_pk_mul_f32 v[26:27], v[26:27], v[34:35] op_sel_hi:[1,0]
	v_pk_mul_f32 v[24:25], v[24:25], v[34:35] op_sel_hi:[1,0]
	v_pk_mul_f32 v[22:23], v[22:23], v[34:35] op_sel_hi:[1,0]
	v_pk_mul_f32 v[20:21], v[20:21], v[34:35] op_sel_hi:[1,0]
	v_pk_mul_f32 v[18:19], v[18:19], v[34:35] op_sel_hi:[1,0]
	v_max_f32_e32 v30, 0, v30
	v_max_f32_e32 v26, 0, v26
	v_max_f32_e32 v31, 0, v31
	v_max_f32_e32 v27, 0, v27
	v_max_f32_e32 v32, 0, v32
	v_max_f32_e32 v28, 0, v28
	v_max_f32_e32 v33, 0, v33
	v_max_f32_e32 v29, 0, v29
	v_max_f32_e32 v22, 0, v22
	v_max_f32_e32 v18, 0, v18
	v_max_f32_e32 v23, 0, v23
	v_max_f32_e32 v19, 0, v19
	v_max_f32_e32 v24, 0, v24
	v_max_f32_e32 v20, 0, v20
	v_max_f32_e32 v25, 0, v25
	v_max_f32_e32 v21, 0, v21
	v_pk_mul_f32 v[30:31], v[30:31], v[30:31]
	v_pk_mul_f32 v[26:27], v[26:27], v[26:27]
	v_pk_mul_f32 v[32:33], v[32:33], v[32:33]
	v_pk_mul_f32 v[28:29], v[28:29], v[28:29]
	v_pk_mul_f32 v[22:23], v[22:23], v[22:23]
	v_pk_mul_f32 v[34:35], v[18:19], v[18:19]
	v_pk_mul_f32 v[24:25], v[24:25], v[24:25]
	v_pk_mul_f32 v[42:43], v[20:21], v[20:21]
	v_cvt_pk_bf16_f32 v18, v30, v31
	v_cvt_pk_bf16_f32 v19, v32, v33
	v_cvt_pk_bf16_f32 v20, v26, v27
	v_cvt_pk_bf16_f32 v21, v28, v29
	v_cvt_pk_bf16_f32 v22, v22, v23
	v_cvt_pk_bf16_f32 v23, v24, v25
	v_cvt_pk_bf16_f32 v24, v34, v35
	v_cvt_pk_bf16_f32 v25, v42, v43
	global_store_dwordx4 v[38:39], v[18:21], off
	global_store_dwordx4 v[38:39], v[22:25], off offset:256
	s_nop 0
	v_lshlrev_b64 v[20:21], 14, v[36:37]
	v_lshl_add_u64 v[20:21], s[6:7], 0, v[20:21]
	v_lshl_add_u64 v[20:21], v[20:21], 0, s[18:19]
	v_lshl_add_u64 v[20:21], v[20:21], 0, v[138:139]
	v_mov_b32_e32 v18, v246
	v_pk_mul_f32 v[16:17], v[16:17], v[18:19] op_sel_hi:[1,0]
	v_pk_mul_f32 v[14:15], v[14:15], v[18:19] op_sel_hi:[1,0]
	v_pk_mul_f32 v[12:13], v[12:13], v[18:19] op_sel_hi:[1,0]
	v_pk_mul_f32 v[10:11], v[10:11], v[18:19] op_sel_hi:[1,0]
	v_pk_mul_f32 v[8:9], v[8:9], v[18:19] op_sel_hi:[1,0]
	v_pk_mul_f32 v[6:7], v[6:7], v[18:19] op_sel_hi:[1,0]
	v_pk_mul_f32 v[4:5], v[4:5], v[18:19] op_sel_hi:[1,0]
	v_pk_mul_f32 v[2:3], v[2:3], v[18:19] op_sel_hi:[1,0]
	v_max_f32_e32 v14, 0, v14
	v_max_f32_e32 v10, 0, v10
	v_max_f32_e32 v15, 0, v15
	v_max_f32_e32 v11, 0, v11
	v_max_f32_e32 v16, 0, v16
	v_max_f32_e32 v12, 0, v12
	v_max_f32_e32 v17, 0, v17
	v_max_f32_e32 v13, 0, v13
	v_max_f32_e32 v6, 0, v6
	v_max_f32_e32 v2, 0, v2
	v_max_f32_e32 v7, 0, v7
	v_max_f32_e32 v3, 0, v3
	v_max_f32_e32 v8, 0, v8
	v_max_f32_e32 v4, 0, v4
	v_max_f32_e32 v9, 0, v9
	v_max_f32_e32 v5, 0, v5
	v_pk_mul_f32 v[14:15], v[14:15], v[14:15]
	v_pk_mul_f32 v[10:11], v[10:11], v[10:11]
	v_pk_mul_f32 v[16:17], v[16:17], v[16:17]
	v_pk_mul_f32 v[12:13], v[12:13], v[12:13]
	v_pk_mul_f32 v[6:7], v[6:7], v[6:7]
	v_pk_mul_f32 v[18:19], v[2:3], v[2:3]
	v_pk_mul_f32 v[8:9], v[8:9], v[8:9]
	v_pk_mul_f32 v[22:23], v[4:5], v[4:5]
	v_cvt_pk_bf16_f32 v2, v14, v15
	v_cvt_pk_bf16_f32 v3, v16, v17
	v_cvt_pk_bf16_f32 v4, v10, v11
	v_cvt_pk_bf16_f32 v5, v12, v13
	v_cvt_pk_bf16_f32 v6, v6, v7
	v_cvt_pk_bf16_f32 v7, v8, v9
	v_cvt_pk_bf16_f32 v8, v18, v19
	v_cvt_pk_bf16_f32 v9, v22, v23
	global_store_dwordx4 v[20:21], v[2:5], off
	global_store_dwordx4 v[20:21], v[6:9], off offset:256
	s_cbranch_vccz .LBB0_914
	s_waitcnt vmcnt(0)
	s_cmpk_gt_u32 s24, 0xff
	s_cbranch_scc1 .LBB0_925
	s_barrier

; #define PG8_STAGE(bufoff, gbase, voff) do { _Pragma("unroll") for (int _i = 0; _i < 2; ++_i) \
;     __builtin_amdgcn_global_load_lds((const unsigned*)((const char*)(gbase) + (voff)[_i]), (LAS unsigned*)(lds + (bufoff) + ldsw + _i * 8192), 16, 0, 0); } while (0)
; #define PG8_LDA(dst, b, h) do { _Pragma("unroll") for (int m = 0; m < 4; ++m) _Pragma("unroll") for (int k = 0; k < 2; ++k) dst[m][k] = *(const LAS bf16x8*)(lds + PG8_SA(b, h) + aoff + m * 2048 + k * 1024); } while (0)
; #define PG8_LDB(dst, b, h) do { _Pragma("unroll") for (int n = 0; n < 2; ++n) _Pragma("unroll") for (int k = 0; k < 2; ++k) dst[n][k] = *(const LAS bf16x8*)(lds + PG8_SB(b, h) + boff + n * 2048 + k * 1024); } while (0)
; #define PG8_MMA(ai, bj, At, Bt) do { __builtin_amdgcn_s_setprio(1); _Pragma("unroll") for (int m = 0; m < 4; ++m) _Pragma("unroll") for (int n = 0; n < 2; ++n) _Pragma("unroll") for (int k = 0; k < 2; ++k) \
;     acc[ai][bj][m][n] = __builtin_amdgcn_mfma_f32_16x16x32_bf16(Bt[n][k], At[m][k], acc[ai][bj][m][n], 0, 0, 0); __builtin_amdgcn_s_setprio(0); } while (0)
; #define PG8_WAIT_V(n) asm volatile("s_waitcnt vmcnt(" #n ")" ::: "memory")
; #define PG8_WAIT_L(n) asm volatile("s_waitcnt lgkmcnt(" #n ")" ::: "memory")
; #define PG8_BAR __builtin_amdgcn_s_barrier()
; #define PG8_SCHED __builtin_amdgcn_sched_barrier(0)
; template <class Epi>
; DI void gemm_phase(LAS unsigned char* lds, const Gemm g, const StaticOrder& S, const Epi& E) {
;     ...
;     for (int t = 0; t < nt; t += 2) {
;       const bool last = (t == nt - 2);
;       const char* a1 = cA + PG8_AK(t + 1);
;       const char* a2 = last ? nA : cA + PG8_AK(t + 2); const char* b2 = last ? nB : cB + (size_t)(t + 2) * kstep;
;       const char* a3 = a2 + kstep; const char* b3 = b2 + kstep;
;       PG8_LDB(B0, 0, 0); PG8_SCHED; PG8_LDA(At, 0, 0); PG8_STAGE(PG8_SA(1, 1), a1 + hstepA, voffA);
;       PG8_WAIT_L(8); PG8_BAR; PG8_WAIT_L(0); PG8_MMA(0, 0, At, B0); PG8_BAR; PG8_SCHED;
;       PG8_LDB(B1, 0, 1); PG8_STAGE(PG8_SB(0, 0), b2, voffB);
;       PG8_BAR; PG8_WAIT_L(0); PG8_MMA(0, 1, At, B1); PG8_BAR;
;       PG8_LDA(At, 0, 1); PG8_STAGE(PG8_SA(0, 0), a2, voffA);
;       PG8_BAR; PG8_WAIT_L(0); PG8_MMA(1, 0, At, B0); PG8_BAR; PG8_SCHED;
;       PG8_STAGE(PG8_SB(0, 1), b2 + hstepB, voffB);
;       PG8_WAIT_V(6); PG8_BAR; PG8_MMA(1, 1, At, B1); PG8_BAR;
.LBB0_962:
	ds_read_b128 v[156:159], v151
	ds_read_b128 v[160:163], v151 offset:1024
	ds_read_b128 v[164:167], v151 offset:2048
	ds_read_b128 v[168:171], v151 offset:3072
	s_add_u32 s22, s20, 0xffe00080
	s_addc_u32 s23, s21, -1
	s_cmpk_eq_i32 s48, 0x7c
	s_cselect_b32 s25, s13, s23
	s_cselect_b32 s24, s19, s22
	s_cselect_b32 s23, s11, s47
	s_cselect_b32 s22, s45, s46
	v_lshl_add_u64 v[148:149], s[20:21], 0, v[140:141]
	s_add_i32 m0, s33, 0xc000
	ds_read_b128 v[172:175], v152
	ds_read_b128 v[176:179], v152 offset:1024
	ds_read_b128 v[180:183], v152 offset:2048
	ds_read_b128 v[184:187], v152 offset:3072
	ds_read_b128 v[188:191], v152 offset:4096
	ds_read_b128 v[192:195], v152 offset:5120
	ds_read_b128 v[196:199], v152 offset:6144
	ds_read_b128 v[200:203], v152 offset:7168
	global_load_lds_dwordx4 v[148:149], off
	v_lshl_add_u64 v[148:149], s[20:21], 0, v[142:143]
	s_add_i32 m0, s33, 0xe000
	s_nop 0
	global_load_lds_dwordx4 v[148:149], off
	s_waitcnt lgkmcnt(8)
	s_barrier
	s_waitcnt lgkmcnt(0)
	v_mfma_f32_16x16x32_bf16 v[126:129], v[156:159], v[172:175], v[126:129]
	v_mfma_f32_16x16x32_bf16 v[122:125], v[164:167], v[172:175], v[122:125]
	v_mfma_f32_16x16x32_bf16 v[110:113], v[156:159], v[180:183], v[110:113]
	v_mfma_f32_16x16x32_bf16 v[106:109], v[164:167], v[180:183], v[106:109]
	v_mfma_f32_16x16x32_bf16 v[94:97], v[156:159], v[188:191], v[94:97]
	v_mfma_f32_16x16x32_bf16 v[90:93], v[164:167], v[188:191], v[90:93]
	v_mfma_f32_16x16x32_bf16 v[78:81], v[156:159], v[196:199], v[78:81]
	v_mfma_f32_16x16x32_bf16 v[74:77], v[164:167], v[196:199], v[74:77]
	v_mfma_f32_16x16x32_bf16 v[126:129], v[160:163], v[176:179], v[126:129]
	v_mfma_f32_16x16x32_bf16 v[122:125], v[168:171], v[176:179], v[122:125]
	v_mfma_f32_16x16x32_bf16 v[110:113], v[160:163], v[184:187], v[110:113]
	v_mfma_f32_16x16x32_bf16 v[106:109], v[168:171], v[184:187], v[106:109]
	v_mfma_f32_16x16x32_bf16 v[94:97], v[160:163], v[192:195], v[94:97]
	v_mfma_f32_16x16x32_bf16 v[90:93], v[168:171], v[192:195], v[90:93]
	v_mfma_f32_16x16x32_bf16 v[78:81], v[160:163], v[200:203], v[78:81]
	v_mfma_f32_16x16x32_bf16 v[74:77], v[168:171], v[200:203], v[74:77]
	s_barrier
	s_add_i32 s49, s42, s31
	v_lshl_add_u64 v[148:149], s[22:23], 0, v[132:133]
	s_mov_b32 m0, s49
	ds_read_b128 v[204:207], v153
	ds_read_b128 v[208:211], v153 offset:1024
	ds_read_b128 v[212:215], v153 offset:2048
	ds_read_b128 v[216:219], v153 offset:3072
	global_load_lds_dwordx4 v[148:149], off
	v_lshl_add_u64 v[220:221], s[22:23], 0, v[136:137]
	s_add_i32 m0, s49, 0x2000
	s_nop 0
	global_load_lds_dwordx4 v[220:221], off
	s_barrier
	s_waitcnt lgkmcnt(0)
	v_mfma_f32_16x16x32_bf16 v[118:121], v[204:207], v[172:175], v[118:121]
	v_mfma_f32_16x16x32_bf16 v[114:117], v[212:215], v[172:175], v[114:117]
	v_mfma_f32_16x16x32_bf16 v[102:105], v[204:207], v[180:183], v[102:105]
	v_mfma_f32_16x16x32_bf16 v[98:101], v[212:215], v[180:183], v[98:101]
	v_mfma_f32_16x16x32_bf16 v[86:89], v[204:207], v[188:191], v[86:89]
	v_mfma_f32_16x16x32_bf16 v[82:85], v[212:215], v[188:191], v[82:85]
	v_mfma_f32_16x16x32_bf16 v[70:73], v[204:207], v[196:199], v[70:73]
	v_mfma_f32_16x16x32_bf16 v[66:69], v[212:215], v[196:199], v[66:69]
	v_mfma_f32_16x16x32_bf16 v[118:121], v[208:211], v[176:179], v[118:121]
	v_mfma_f32_16x16x32_bf16 v[114:117], v[216:219], v[176:179], v[114:117]
	v_mfma_f32_16x16x32_bf16 v[102:105], v[208:211], v[184:187], v[102:105]
	v_mfma_f32_16x16x32_bf16 v[98:101], v[216:219], v[184:187], v[98:101]
	v_mfma_f32_16x16x32_bf16 v[86:89], v[208:211], v[192:195], v[86:89]
	v_mfma_f32_16x16x32_bf16 v[82:85], v[216:219], v[192:195], v[82:85]
	v_mfma_f32_16x16x32_bf16 v[70:73], v[208:211], v[200:203], v[70:73]
	v_mfma_f32_16x16x32_bf16 v[66:69], v[216:219], v[200:203], v[66:69]
	s_mov_b32 m0, s33
	v_lshl_add_u64 v[222:223], s[24:25], 0, v[130:131]
	s_barrier
	ds_read_b128 v[172:175], v152 offset:16384
	ds_read_b128 v[176:179], v152 offset:17408
	ds_read_b128 v[180:183], v152 offset:18432
	ds_read_b128 v[184:187], v152 offset:19456
	ds_read_b128 v[188:191], v152 offset:20480
	ds_read_b128 v[192:195], v152 offset:21504
	ds_read_b128 v[196:199], v152 offset:22528
	ds_read_b128 v[200:203], v152 offset:23552
	global_load_lds_dwordx4 v[222:223], off
	v_lshl_add_u64 v[224:225], s[24:25], 0, v[134:135]
	s_mov_b32 m0, s34
	s_nop 0
	global_load_lds_dwordx4 v[224:225], off
	s_barrier
	s_waitcnt lgkmcnt(0)
	v_mfma_f32_16x16x32_bf16 v[62:65], v[156:159], v[172:175], v[62:65]
	v_mfma_f32_16x16x32_bf16 v[58:61], v[164:167], v[172:175], v[58:61]
	v_mfma_f32_16x16x32_bf16 v[46:49], v[156:159], v[180:183], v[46:49]
	v_mfma_f32_16x16x32_bf16 v[42:45], v[164:167], v[180:183], v[42:45]
	v_mfma_f32_16x16x32_bf16 v[30:33], v[156:159], v[188:191], v[30:33]
	v_mfma_f32_16x16x32_bf16 v[26:29], v[164:167], v[188:191], v[26:29]
	v_mfma_f32_16x16x32_bf16 v[14:17], v[156:159], v[196:199], v[14:17]
	v_mfma_f32_16x16x32_bf16 v[10:13], v[164:167], v[196:199], v[10:13]
	v_mfma_f32_16x16x32_bf16 v[62:65], v[160:163], v[176:179], v[62:65]
	v_mfma_f32_16x16x32_bf16 v[58:61], v[168:171], v[176:179], v[58:61]
	v_mfma_f32_16x16x32_bf16 v[46:49], v[160:163], v[184:187], v[46:49]
	v_mfma_f32_16x16x32_bf16 v[42:45], v[168:171], v[184:187], v[42:45]
	v_mfma_f32_16x16x32_bf16 v[30:33], v[160:163], v[192:195], v[30:33]
	v_mfma_f32_16x16x32_bf16 v[26:29], v[168:171], v[192:195], v[26:29]
	v_mfma_f32_16x16x32_bf16 v[14:17], v[160:163], v[200:203], v[14:17]
	v_mfma_f32_16x16x32_bf16 v[10:13], v[168:171], v[200:203], v[10:13]
	s_barrier
; #define PG8_STAGE(bufoff, gbase, voff) do { _Pragma("unroll") for (int _i = 0; _i < 2; ++_i) \
;     __builtin_amdgcn_global_load_lds((const unsigned*)((const char*)(gbase) + (voff)[_i]), (LAS unsigned*)(lds + (bufoff) + ldsw + _i * 8192), 16, 0, 0); } while (0)
; #define PG8_LDA(dst, b, h) do { _Pragma("unroll") for (int m = 0; m < 4; ++m) _Pragma("unroll") for (int k = 0; k < 2; ++k) dst[m][k] = *(const LAS bf16x8*)(lds + PG8_SA(b, h) + aoff + m * 2048 + k * 1024); } while (0)
; #define PG8_LDB(dst, b, h) do { _Pragma("unroll") for (int n = 0; n < 2; ++n) _Pragma("unroll") for (int k = 0; k < 2; ++k) dst[n][k] = *(const LAS bf16x8*)(lds + PG8_SB(b, h) + boff + n * 2048 + k * 1024); } while (0)
; #define PG8_MMA(ai, bj, At, Bt) do { __builtin_amdgcn_s_setprio(1); _Pragma("unroll") for (int m = 0; m < 4; ++m) _Pragma("unroll") for (int n = 0; n < 2; ++n) _Pragma("unroll") for (int k = 0; k < 2; ++k) \
;     acc[ai][bj][m][n] = __builtin_amdgcn_mfma_f32_16x16x32_bf16(Bt[n][k], At[m][k], acc[ai][bj][m][n], 0, 0, 0); __builtin_amdgcn_s_setprio(0); } while (0)
; #define PG8_WAIT_V(n) asm volatile("s_waitcnt vmcnt(" #n ")" ::: "memory")
; #define PG8_WAIT_L(n) asm volatile("s_waitcnt lgkmcnt(" #n ")" ::: "memory")
; #define PG8_BAR __builtin_amdgcn_s_barrier()
; #define PG8_SCHED __builtin_amdgcn_sched_barrier(0)
; template <class Epi>
; DI void gemm_phase(LAS unsigned char* lds, const Gemm g, const StaticOrder& S, const Epi& E) {
;     ...
;       PG8_LDA(At, 0, 1); PG8_STAGE(PG8_SA(0, 0), a2, voffA);
;       PG8_BAR; PG8_WAIT_L(0); PG8_MMA(1, 0, At, B0); PG8_BAR; PG8_SCHED;
;       PG8_STAGE(PG8_SB(0, 1), b2 + hstepB, voffB);
;       PG8_WAIT_V(6); PG8_BAR; PG8_MMA(1, 1, At, B1); PG8_BAR;
;       PG8_LDB(B0, 1, 0); PG8_SCHED; PG8_LDA(At, 1, 0); PG8_STAGE(PG8_SA(0, 1), a2 + hstepA, voffA);
;       PG8_WAIT_L(8); PG8_BAR; PG8_WAIT_L(0); PG8_MMA(0, 0, At, B0); PG8_BAR; PG8_SCHED;
;       PG8_LDB(B1, 1, 1); PG8_STAGE(PG8_SB(1, 0), b3, voffB);
;       PG8_BAR; PG8_WAIT_L(0); PG8_MMA(0, 1, At, B1); PG8_BAR;
;       PG8_LDA(At, 1, 1); PG8_STAGE(PG8_SA(1, 0), a3, voffA);
;       PG8_BAR; PG8_WAIT_L(0); PG8_MMA(1, 0, At, B0); PG8_BAR; PG8_SCHED;
	s_add_u32 s50, s22, 0x200000
	s_addc_u32 s51, s23, 0
	s_add_i32 s49, s43, s31
	v_lshl_add_u64 v[156:157], s[50:51], 0, v[132:133]
	s_mov_b32 m0, s49
	s_nop 0
	global_load_lds_dwordx4 v[156:157], off
	v_lshl_add_u64 v[156:157], s[50:51], 0, v[136:137]
	s_add_i32 m0, s49, 0x2000
	s_nop 0
	global_load_lds_dwordx4 v[156:157], off
	s_waitcnt vmcnt(6)
	s_barrier
	v_mfma_f32_16x16x32_bf16 v[54:57], v[204:207], v[172:175], v[54:57]
	v_mfma_f32_16x16x32_bf16 v[50:53], v[212:215], v[172:175], v[50:53]
	v_mfma_f32_16x16x32_bf16 v[38:41], v[204:207], v[180:183], v[38:41]
	v_mfma_f32_16x16x32_bf16 v[34:37], v[212:215], v[180:183], v[34:37]
	v_mfma_f32_16x16x32_bf16 v[22:25], v[204:207], v[188:191], v[22:25]
	v_mfma_f32_16x16x32_bf16 v[18:21], v[212:215], v[188:191], v[18:21]
	v_mfma_f32_16x16x32_bf16 v[6:9], v[204:207], v[196:199], v[6:9]
	v_mfma_f32_16x16x32_bf16 v[2:5], v[212:215], v[196:199], v[2:5]
	v_mfma_f32_16x16x32_bf16 v[54:57], v[208:211], v[176:179], v[54:57]
	v_mfma_f32_16x16x32_bf16 v[50:53], v[216:219], v[176:179], v[50:53]
	v_mfma_f32_16x16x32_bf16 v[38:41], v[208:211], v[184:187], v[38:41]
	v_mfma_f32_16x16x32_bf16 v[34:37], v[216:219], v[184:187], v[34:37]
	v_mfma_f32_16x16x32_bf16 v[22:25], v[208:211], v[192:195], v[22:25]
	v_mfma_f32_16x16x32_bf16 v[18:21], v[216:219], v[192:195], v[18:21]
	v_mfma_f32_16x16x32_bf16 v[6:9], v[208:211], v[200:203], v[6:9]
	v_mfma_f32_16x16x32_bf16 v[2:5], v[216:219], v[200:203], v[2:5]
	s_add_i32 s49, 0, 0x18000
	v_add_u32_e32 v155, s49, v150
	s_barrier
	ds_read_b128 v[156:159], v155
	ds_read_b128 v[160:163], v155 offset:1024
	ds_read_b128 v[164:167], v155 offset:2048
	ds_read_b128 v[168:171], v155 offset:3072
	s_add_u32 s24, s24, 0x200000
	s_addc_u32 s25, s25, 0
	s_mov_b32 m0, s35
	v_lshl_add_u64 v[204:205], s[24:25], 0, v[130:131]
	ds_read_b128 v[172:175], v152 offset:32768
	ds_read_b128 v[176:179], v152 offset:33792
	ds_read_b128 v[180:183], v152 offset:34816
	ds_read_b128 v[184:187], v152 offset:35840
	ds_read_b128 v[188:191], v152 offset:36864
	ds_read_b128 v[192:195], v152 offset:37888
	ds_read_b128 v[196:199], v152 offset:38912
	ds_read_b128 v[200:203], v152 offset:39936
	global_load_lds_dwordx4 v[204:205], off
	v_lshl_add_u64 v[204:205], s[24:25], 0, v[134:135]
	s_mov_b32 m0, s36
	s_nop 0
	global_load_lds_dwordx4 v[204:205], off
	s_waitcnt lgkmcnt(8)
	s_barrier
	s_waitcnt lgkmcnt(0)
	v_mfma_f32_16x16x32_bf16 v[126:129], v[156:159], v[172:175], v[126:129]
	v_mfma_f32_16x16x32_bf16 v[122:125], v[164:167], v[172:175], v[122:125]
	v_mfma_f32_16x16x32_bf16 v[110:113], v[156:159], v[180:183], v[110:113]
	v_mfma_f32_16x16x32_bf16 v[106:109], v[164:167], v[180:183], v[106:109]
	v_mfma_f32_16x16x32_bf16 v[94:97], v[156:159], v[188:191], v[94:97]
	v_mfma_f32_16x16x32_bf16 v[90:93], v[164:167], v[188:191], v[90:93]
	v_mfma_f32_16x16x32_bf16 v[78:81], v[156:159], v[196:199], v[78:81]
	v_mfma_f32_16x16x32_bf16 v[74:77], v[164:167], v[196:199], v[74:77]
	v_mfma_f32_16x16x32_bf16 v[126:129], v[160:163], v[176:179], v[126:129]
	v_mfma_f32_16x16x32_bf16 v[122:125], v[168:171], v[176:179], v[122:125]
	v_mfma_f32_16x16x32_bf16 v[110:113], v[160:163], v[184:187], v[110:113]
	v_mfma_f32_16x16x32_bf16 v[106:109], v[168:171], v[184:187], v[106:109]
	v_mfma_f32_16x16x32_bf16 v[94:97], v[160:163], v[192:195], v[94:97]
	v_mfma_f32_16x16x32_bf16 v[90:93], v[168:171], v[192:195], v[90:93]
	v_mfma_f32_16x16x32_bf16 v[78:81], v[160:163], v[200:203], v[78:81]
	v_mfma_f32_16x16x32_bf16 v[74:77], v[168:171], v[200:203], v[74:77]
	s_barrier
	s_add_i32 s24, 0, 0x1c000
	s_add_i32 s25, s49, s31
	v_add_u32_e32 v155, s24, v150
	v_lshl_add_u64 v[148:149], v[148:149], 0, s[6:7]
	s_mov_b32 m0, s25
	ds_read_b128 v[204:207], v155
	ds_read_b128 v[208:211], v155 offset:1024
	ds_read_b128 v[212:215], v155 offset:2048
	ds_read_b128 v[216:219], v155 offset:3072
	global_load_lds_dwordx4 v[148:149], off
	v_lshl_add_u64 v[148:149], v[220:221], 0, s[6:7]
	s_add_i32 m0, s25, 0x2000
	s_nop 0
	global_load_lds_dwordx4 v[148:149], off
	s_barrier
	s_waitcnt lgkmcnt(0)
	v_mfma_f32_16x16x32_bf16 v[118:121], v[204:207], v[172:175], v[118:121]
	v_mfma_f32_16x16x32_bf16 v[114:117], v[212:215], v[172:175], v[114:117]
	v_mfma_f32_16x16x32_bf16 v[102:105], v[204:207], v[180:183], v[102:105]
	v_mfma_f32_16x16x32_bf16 v[98:101], v[212:215], v[180:183], v[98:101]
	v_mfma_f32_16x16x32_bf16 v[86:89], v[204:207], v[188:191], v[86:89]
	v_mfma_f32_16x16x32_bf16 v[82:85], v[212:215], v[188:191], v[82:85]
	v_mfma_f32_16x16x32_bf16 v[70:73], v[204:207], v[196:199], v[70:73]
	v_mfma_f32_16x16x32_bf16 v[66:69], v[212:215], v[196:199], v[66:69]
	v_mfma_f32_16x16x32_bf16 v[118:121], v[208:211], v[176:179], v[118:121]
	v_mfma_f32_16x16x32_bf16 v[114:117], v[216:219], v[176:179], v[114:117]
	v_mfma_f32_16x16x32_bf16 v[102:105], v[208:211], v[184:187], v[102:105]
	v_mfma_f32_16x16x32_bf16 v[98:101], v[216:219], v[184:187], v[98:101]
	v_mfma_f32_16x16x32_bf16 v[86:89], v[208:211], v[192:195], v[86:89]
	v_mfma_f32_16x16x32_bf16 v[82:85], v[216:219], v[192:195], v[82:85]
	v_mfma_f32_16x16x32_bf16 v[70:73], v[208:211], v[200:203], v[70:73]
	v_mfma_f32_16x16x32_bf16 v[66:69], v[216:219], v[200:203], v[66:69]
	s_mov_b32 m0, s38
	v_lshl_add_u64 v[148:149], v[222:223], 0, s[6:7]
	s_barrier
	ds_read_b128 v[172:175], v152 offset:49152
	ds_read_b128 v[176:179], v152 offset:50176
	ds_read_b128 v[180:183], v152 offset:51200
	ds_read_b128 v[184:187], v152 offset:52224
	ds_read_b128 v[188:191], v152 offset:53248
	ds_read_b128 v[192:195], v152 offset:54272
	ds_read_b128 v[196:199], v152 offset:55296
	ds_read_b128 v[200:203], v152 offset:56320
	global_load_lds_dwordx4 v[148:149], off
	v_lshl_add_u64 v[148:149], v[224:225], 0, s[6:7]
	s_mov_b32 m0, s39
	s_nop 0
	global_load_lds_dwordx4 v[148:149], off
	s_barrier
; template <class Epi>
; DI void gemm_phase(LAS unsigned char* lds, const Gemm g, const StaticOrder& S, const Epi& E) {
;     ...
;       PG8_BAR; PG8_WAIT_L(0); PG8_MMA(0, 1, At, B1); PG8_BAR;
;       PG8_LDA(At, 1, 1); PG8_STAGE(PG8_SA(1, 0), a3, voffA);
;       PG8_BAR; PG8_WAIT_L(0); PG8_MMA(1, 0, At, B0); PG8_BAR; PG8_SCHED;
;       PG8_STAGE(PG8_SB(1, 1), b3 + hstepB, voffB);
;       PG8_WAIT_V(6); PG8_BAR; PG8_MMA(1, 1, At, B1); PG8_BAR;
;     }
;     E(acc, cur, wr, wc, fr, fq);
;   DI void operator()(const f32x4 (&acc)[2][2][4][2], const pg8::Unit& u, int wr, int wc, int fr, int fq) const {
;     ...
;         float ssq = 0.f;
; #pragma unroll
;         for (int bj = 0; bj < 2; ++bj) {
;           f32x4 v0 = acc[ai][bj][m][0] * rs, v1 = acc[ai][bj][m][1] * rs;
;           if (MODE == EP_IN || MODE == EP_MIX || MODE == EP_DOWN) {
; #pragma unroll
;             for (int j = 0; j < 4; ++j) ssq += v0[j] * v0[j] + v1[j] * v1[j];
;           }
;           if (MODE == EP_UP) {
; #pragma unroll
;             for (int j = 0; j < 4; ++j) { float a = fmaxf(v0[j], 0.f), b = fmaxf(v1[j], 0.f); v0[j] = a * a; v1[j] = b * b; }
;           }
;           bf16_t* dst;
;           const int ct = bj * 128 + cl;
;           if (MODE == EP_IN) {
;             if (pn < 4) dst = (bf16_t*)(ws + OFF_PROJA) + (size_t)grow * 1024 + pn * 256 + ct;
;             else if (pn < 16) dst = (bf16_t*)(ws + OFF_PROJG) + (size_t)grow * 3072 + (pn - 4) * 256 + ct;
;             else dst = (bf16_t*)(ws + OFF_PROJS) + (size_t)grow * 256 + ct;
;           } else if (MODE == EP_Q) {
;             if (pn < 4) dst = (bf16_t*)(dout + DO_Q) + (size_t)grow * 1536 + (pn * 2 + bj) * 192 + cl;
;             else {
;               const int mm = (pn - 4) * 256 + ct, h = mm >> 6, r = mm & 63;
;               dst = (bf16_t*)(dout + DO_Q) + (size_t)grow * 1536 + h * 192 + 128 + r;
;               const int pos = grow < TP ? (grow & 4095) : grow - TP;
;               const f32x4* tb = (const f32x4*)((const f32x2*)(ws + OFF_ROPE) + pos * 32 + (r >> 1));
;               const f32x4 t0 = tb[0], t1 = tb[1];
;               f32x4 o0, o1;
;               o0[0] = v0[0] * t0[0] - v0[1] * t0[1]; o0[1] = v0[1] * t0[0] + v0[0] * t0[1];
;               o0[2] = v0[2] * t0[2] - v0[3] * t0[3]; o0[3] = v0[3] * t0[2] + v0[2] * t0[3];
;               o1[0] = v1[0] * t1[0] - v1[1] * t1[1]; o1[1] = v1[1] * t1[0] + v1[0] * t1[1];
	s_waitcnt lgkmcnt(0)
	v_mfma_f32_16x16x32_bf16 v[62:65], v[156:159], v[172:175], v[62:65]
	v_mfma_f32_16x16x32_bf16 v[58:61], v[164:167], v[172:175], v[58:61]
	v_mfma_f32_16x16x32_bf16 v[46:49], v[156:159], v[180:183], v[46:49]
	v_mfma_f32_16x16x32_bf16 v[42:45], v[164:167], v[180:183], v[42:45]
	v_mfma_f32_16x16x32_bf16 v[30:33], v[156:159], v[188:191], v[30:33]
	v_mfma_f32_16x16x32_bf16 v[26:29], v[164:167], v[188:191], v[26:29]
	v_mfma_f32_16x16x32_bf16 v[14:17], v[156:159], v[196:199], v[14:17]
	v_mfma_f32_16x16x32_bf16 v[10:13], v[164:167], v[196:199], v[10:13]
	v_mfma_f32_16x16x32_bf16 v[62:65], v[160:163], v[176:179], v[62:65]
	v_mfma_f32_16x16x32_bf16 v[58:61], v[168:171], v[176:179], v[58:61]
	v_mfma_f32_16x16x32_bf16 v[46:49], v[160:163], v[184:187], v[46:49]
	v_mfma_f32_16x16x32_bf16 v[42:45], v[168:171], v[184:187], v[42:45]
	v_mfma_f32_16x16x32_bf16 v[30:33], v[160:163], v[192:195], v[30:33]
	v_mfma_f32_16x16x32_bf16 v[26:29], v[168:171], v[192:195], v[26:29]
	v_mfma_f32_16x16x32_bf16 v[14:17], v[160:163], v[200:203], v[14:17]
	v_mfma_f32_16x16x32_bf16 v[10:13], v[168:171], v[200:203], v[10:13]
	s_barrier
	s_add_u32 s22, s22, 0x200080
	s_addc_u32 s23, s23, 0
	s_add_i32 s24, s24, s31
	v_lshl_add_u64 v[148:149], s[22:23], 0, v[132:133]
	s_mov_b32 m0, s24
	s_nop 0
	global_load_lds_dwordx4 v[148:149], off
	v_lshl_add_u64 v[148:149], s[22:23], 0, v[136:137]
	s_add_i32 m0, s24, 0x2000
	s_nop 0
	global_load_lds_dwordx4 v[148:149], off
	s_waitcnt vmcnt(6)
	s_barrier
	v_mfma_f32_16x16x32_bf16 v[54:57], v[204:207], v[172:175], v[54:57]
	v_mfma_f32_16x16x32_bf16 v[50:53], v[212:215], v[172:175], v[50:53]
	v_mfma_f32_16x16x32_bf16 v[38:41], v[204:207], v[180:183], v[38:41]
	v_mfma_f32_16x16x32_bf16 v[34:37], v[212:215], v[180:183], v[34:37]
	v_mfma_f32_16x16x32_bf16 v[22:25], v[204:207], v[188:191], v[22:25]
	v_mfma_f32_16x16x32_bf16 v[18:21], v[212:215], v[188:191], v[18:21]
	v_mfma_f32_16x16x32_bf16 v[6:9], v[204:207], v[196:199], v[6:9]
	v_mfma_f32_16x16x32_bf16 v[2:5], v[212:215], v[196:199], v[2:5]
	v_mfma_f32_16x16x32_bf16 v[54:57], v[208:211], v[176:179], v[54:57]
	v_mfma_f32_16x16x32_bf16 v[50:53], v[216:219], v[176:179], v[50:53]
	v_mfma_f32_16x16x32_bf16 v[38:41], v[208:211], v[184:187], v[38:41]
	v_mfma_f32_16x16x32_bf16 v[34:37], v[216:219], v[184:187], v[34:37]
	v_mfma_f32_16x16x32_bf16 v[22:25], v[208:211], v[192:195], v[22:25]
	v_mfma_f32_16x16x32_bf16 v[18:21], v[216:219], v[192:195], v[18:21]
	v_mfma_f32_16x16x32_bf16 v[6:9], v[208:211], v[200:203], v[6:9]
	v_mfma_f32_16x16x32_bf16 v[2:5], v[216:219], v[200:203], v[2:5]
	s_add_i32 s48, s48, 2
	s_add_u32 s20, s20, 0x100
	s_addc_u32 s21, s21, 0
	s_add_u32 s46, s46, 0x100
	s_addc_u32 s47, s47, 0
	s_cmpk_gt_u32 s48, 0x7d
	s_barrier
	s_cbranch_scc0 .LBB0_962
	v_mul_f32_e32 v157, v122, v122
	v_mul_f32_e32 v160, v123, v123
	v_fmac_f32_e32 v157, v126, v126
	v_fmac_f32_e32 v160, v127, v127
	v_add_f32_e32 v157, v157, v160
	v_mul_f32_e32 v160, v124, v124
	v_fmac_f32_e32 v160, v128, v128
	v_add_f32_e32 v157, v160, v157
	v_mul_f32_e32 v160, v125, v125
	v_fmac_f32_e32 v160, v129, v129
	v_cvt_pk_bf16_f32 v126, v126, v127
	v_cvt_pk_bf16_f32 v127, v128, v129
	v_mul_f32_e32 v128, v114, v114
	v_add_f32_e32 v157, v160, v157
	v_fmac_f32_e32 v128, v118, v118
	v_mul_f32_e32 v129, v115, v115
	v_add_f32_e32 v128, v157, v128
	v_fmac_f32_e32 v129, v119, v119
	v_and_b32_e32 v155, 64, v154
	v_add_f32_e32 v128, v129, v128
	v_mul_f32_e32 v129, v116, v116
	v_xor_b32_e32 v149, 16, v154
	v_add_u32_e32 v155, 64, v155
	v_fmac_f32_e32 v129, v120, v120
	v_cmp_lt_i32_e32 vcc, v149, v155
	v_add_f32_e32 v128, v129, v128
	v_mul_f32_e32 v129, v117, v117
	v_cndmask_b32_e32 v149, v154, v149, vcc
	v_fmac_f32_e32 v129, v121, v121
	v_lshlrev_b32_e32 v156, 2, v149
	v_add_f32_e32 v157, v129, v128
	ds_bpermute_b32 v160, v156, v157
	v_xor_b32_e32 v149, 32, v154
	v_cmp_lt_i32_e32 vcc, v149, v155
	v_lshl_add_u32 v148, s18, 8, v1
	v_cvt_pk_bf16_f32 v128, v122, v123
	v_cndmask_b32_e32 v149, v154, v149, vcc
	v_lshlrev_b32_e32 v155, 2, v149
	v_cvt_pk_bf16_f32 v122, v118, v119
	s_waitcnt lgkmcnt(0)
	v_add_f32_e32 v118, v157, v160
	v_ashrrev_i32_e32 v149, 31, v148
	v_readlane_b32 s48, v238, 32
	ds_bpermute_b32 v119, v155, v118
	s_lshl_b32 s20, s4, 8
	v_lshlrev_b64 v[158:159], 13, v[148:149]
	v_readlane_b32 s54, v238, 38
	v_readlane_b32 s55, v238, 39
	s_ashr_i32 s21, s20, 31
	s_lshl_b32 s18, s4, 2
	v_lshl_add_u64 v[158:159], s[54:55], 0, v[158:159]
	v_lshl_add_u64 v[158:159], s[20:21], 1, v[158:159]
	s_ashr_i32 s19, s18, 31
	v_lshl_add_u64 v[158:159], v[158:159], 0, v[138:139]
	v_cvt_pk_bf16_f32 v129, v124, v125
	v_cvt_pk_bf16_f32 v123, v120, v121
	v_cvt_pk_bf16_f32 v124, v114, v115
	v_cvt_pk_bf16_f32 v125, v116, v117
	v_readlane_b32 s49, v238, 33
	v_readlane_b32 s50, v238, 34
	v_readlane_b32 s51, v238, 35
	v_readlane_b32 s52, v238, 36
	v_readlane_b32 s53, v238, 37
	global_store_dwordx4 v[158:159], v[126:129], off
	global_store_dwordx4 v[158:159], v[122:125], off offset:256
	s_and_saveexec_b64 s[22:23], s[0:1]
	s_cbranch_execz .LBB0_965
	v_lshlrev_b64 v[114:115], 7, v[148:149]
	v_lshl_add_u64 v[114:115], s[8:9], 0, v[114:115]
	v_lshl_add_u64 v[114:115], s[18:19], 2, v[114:115]
	s_lshl_b32 s4, s37, 2
	s_waitcnt lgkmcnt(0)
	v_add_f32_e32 v116, v118, v119
	v_lshl_add_u64 v[114:115], v[114:115], 0, s[4:5]
	global_store_dword v[114:115], v116, off

; #define PG8_STAGE(bufoff, gbase, voff) do { _Pragma("unroll") for (int _i = 0; _i < 2; ++_i) \
;     __builtin_amdgcn_global_load_lds((const unsigned*)((const char*)(gbase) + (voff)[_i]), (LAS unsigned*)(lds + (bufoff) + ldsw + _i * 8192), 16, 0, 0); } while (0)
; #define PG8_LDA(dst, b, h) do { _Pragma("unroll") for (int m = 0; m < 4; ++m) _Pragma("unroll") for (int k = 0; k < 2; ++k) dst[m][k] = *(const LAS bf16x8*)(lds + PG8_SA(b, h) + aoff + m * 2048 + k * 1024); } while (0)
; #define PG8_LDB(dst, b, h) do { _Pragma("unroll") for (int n = 0; n < 2; ++n) _Pragma("unroll") for (int k = 0; k < 2; ++k) dst[n][k] = *(const LAS bf16x8*)(lds + PG8_SB(b, h) + boff + n * 2048 + k * 1024); } while (0)
; #define PG8_MMA(ai, bj, At, Bt) do { __builtin_amdgcn_s_setprio(1); _Pragma("unroll") for (int m = 0; m < 4; ++m) _Pragma("unroll") for (int n = 0; n < 2; ++n) _Pragma("unroll") for (int k = 0; k < 2; ++k) \
;     acc[ai][bj][m][n] = __builtin_amdgcn_mfma_f32_16x16x32_bf16(Bt[n][k], At[m][k], acc[ai][bj][m][n], 0, 0, 0); __builtin_amdgcn_s_setprio(0); } while (0)
; #define PG8_WAIT_V(n) asm volatile("s_waitcnt vmcnt(" #n ")" ::: "memory")
; #define PG8_WAIT_L(n) asm volatile("s_waitcnt lgkmcnt(" #n ")" ::: "memory")
; #define PG8_BAR __builtin_amdgcn_s_barrier()
; #define PG8_SCHED __builtin_amdgcn_sched_barrier(0)
; template <class Epi>
; DI void gemm_phase(LAS unsigned char* lds, const Gemm g, const StaticOrder& S, const Epi& E) {
;     ...
;     for (int t = 0; t < nt; t += 2) {
;       const bool last = (t == nt - 2);
;       const char* a1 = cA + PG8_AK(t + 1);
;       const char* a2 = last ? nA : cA + PG8_AK(t + 2); const char* b2 = last ? nB : cB + (size_t)(t + 2) * kstep;
;       const char* a3 = a2 + kstep; const char* b3 = b2 + kstep;
;       PG8_LDB(B0, 0, 0); PG8_SCHED; PG8_LDA(At, 0, 0); PG8_STAGE(PG8_SA(1, 1), a1 + hstepA, voffA);
;       PG8_WAIT_L(8); PG8_BAR; PG8_WAIT_L(0); PG8_MMA(0, 0, At, B0); PG8_BAR; PG8_SCHED;
;       PG8_LDB(B1, 0, 1); PG8_STAGE(PG8_SB(0, 0), b2, voffB);
;       PG8_BAR; PG8_WAIT_L(0); PG8_MMA(0, 1, At, B1); PG8_BAR;
;       PG8_LDA(At, 0, 1); PG8_STAGE(PG8_SA(0, 0), a2, voffA);
;       PG8_BAR; PG8_WAIT_L(0); PG8_MMA(1, 0, At, B0); PG8_BAR; PG8_SCHED;
;       PG8_STAGE(PG8_SB(0, 1), b2 + hstepB, voffB);
;       PG8_WAIT_V(6); PG8_BAR; PG8_MMA(1, 1, At, B1); PG8_BAR;
.LBB0_1015:
	ds_read_b128 v[148:151], v153
	ds_read_b128 v[156:159], v153 offset:1024
	ds_read_b128 v[160:163], v153 offset:2048
	ds_read_b128 v[164:167], v153 offset:3072
	s_add_u32 s20, s18, 0xfff80080
	s_addc_u32 s21, s19, -1
	s_cmp_eq_u32 s46, 28
	s_cselect_b32 s23, s11, s21
	s_cselect_b32 s22, s42, s20
	s_cselect_b32 s21, s9, s45
	s_cselect_b32 s20, s43, s44
	v_lshl_add_u64 v[200:201], s[18:19], 0, v[140:141]
	s_add_i32 m0, s17, 0xc000
	ds_read_b128 v[168:171], v154
	ds_read_b128 v[172:175], v154 offset:1024
	ds_read_b128 v[176:179], v154 offset:2048
	ds_read_b128 v[180:183], v154 offset:3072
	ds_read_b128 v[184:187], v154 offset:4096
	ds_read_b128 v[188:191], v154 offset:5120
	ds_read_b128 v[192:195], v154 offset:6144
	ds_read_b128 v[196:199], v154 offset:7168
	global_load_lds_dwordx4 v[200:201], off
	v_lshl_add_u64 v[200:201], s[18:19], 0, v[142:143]
	s_add_i32 m0, s17, 0xe000
	s_nop 0
	global_load_lds_dwordx4 v[200:201], off
	s_waitcnt lgkmcnt(8)
	s_barrier
	s_waitcnt lgkmcnt(0)
	v_mfma_f32_16x16x32_bf16 v[126:129], v[148:151], v[168:171], v[126:129]
	v_mfma_f32_16x16x32_bf16 v[122:125], v[160:163], v[168:171], v[122:125]
	v_mfma_f32_16x16x32_bf16 v[110:113], v[148:151], v[176:179], v[110:113]
	v_mfma_f32_16x16x32_bf16 v[106:109], v[160:163], v[176:179], v[106:109]
	v_mfma_f32_16x16x32_bf16 v[94:97], v[148:151], v[184:187], v[94:97]
	v_mfma_f32_16x16x32_bf16 v[90:93], v[160:163], v[184:187], v[90:93]
	v_mfma_f32_16x16x32_bf16 v[78:81], v[148:151], v[192:195], v[78:81]
	v_mfma_f32_16x16x32_bf16 v[74:77], v[160:163], v[192:195], v[74:77]
	v_mfma_f32_16x16x32_bf16 v[126:129], v[156:159], v[172:175], v[126:129]
	v_mfma_f32_16x16x32_bf16 v[122:125], v[164:167], v[172:175], v[122:125]
	v_mfma_f32_16x16x32_bf16 v[110:113], v[156:159], v[180:183], v[110:113]
	v_mfma_f32_16x16x32_bf16 v[106:109], v[164:167], v[180:183], v[106:109]
	v_mfma_f32_16x16x32_bf16 v[94:97], v[156:159], v[188:191], v[94:97]
	v_mfma_f32_16x16x32_bf16 v[90:93], v[164:167], v[188:191], v[90:93]
	v_mfma_f32_16x16x32_bf16 v[78:81], v[156:159], v[196:199], v[78:81]
	v_mfma_f32_16x16x32_bf16 v[74:77], v[164:167], v[196:199], v[74:77]
	s_barrier
	s_add_i32 s47, s39, s30
	v_lshl_add_u64 v[216:217], s[20:21], 0, v[132:133]
	s_mov_b32 m0, s47
	ds_read_b128 v[200:203], v155
	ds_read_b128 v[204:207], v155 offset:1024
	ds_read_b128 v[208:211], v155 offset:2048
	ds_read_b128 v[212:215], v155 offset:3072
	global_load_lds_dwordx4 v[216:217], off
	v_lshl_add_u64 v[218:219], s[20:21], 0, v[136:137]
	s_add_i32 m0, s47, 0x2000
	s_nop 0
	global_load_lds_dwordx4 v[218:219], off
	s_barrier
	s_waitcnt lgkmcnt(0)
	v_mfma_f32_16x16x32_bf16 v[118:121], v[200:203], v[168:171], v[118:121]
	v_mfma_f32_16x16x32_bf16 v[114:117], v[208:211], v[168:171], v[114:117]
	v_mfma_f32_16x16x32_bf16 v[102:105], v[200:203], v[176:179], v[102:105]
	v_mfma_f32_16x16x32_bf16 v[98:101], v[208:211], v[176:179], v[98:101]
	v_mfma_f32_16x16x32_bf16 v[86:89], v[200:203], v[184:187], v[86:89]
	v_mfma_f32_16x16x32_bf16 v[82:85], v[208:211], v[184:187], v[82:85]
	v_mfma_f32_16x16x32_bf16 v[70:73], v[200:203], v[192:195], v[70:73]
	v_mfma_f32_16x16x32_bf16 v[66:69], v[208:211], v[192:195], v[66:69]
	v_mfma_f32_16x16x32_bf16 v[118:121], v[204:207], v[172:175], v[118:121]
	v_mfma_f32_16x16x32_bf16 v[114:117], v[212:215], v[172:175], v[114:117]
	v_mfma_f32_16x16x32_bf16 v[102:105], v[204:207], v[180:183], v[102:105]
	v_mfma_f32_16x16x32_bf16 v[98:101], v[212:215], v[180:183], v[98:101]
	v_mfma_f32_16x16x32_bf16 v[86:89], v[204:207], v[188:191], v[86:89]
	v_mfma_f32_16x16x32_bf16 v[82:85], v[212:215], v[188:191], v[82:85]
	v_mfma_f32_16x16x32_bf16 v[70:73], v[204:207], v[196:199], v[70:73]
	v_mfma_f32_16x16x32_bf16 v[66:69], v[212:215], v[196:199], v[66:69]
	s_mov_b32 m0, s17
	v_lshl_add_u64 v[220:221], s[22:23], 0, v[130:131]
	s_barrier
	ds_read_b128 v[168:171], v154 offset:16384
	ds_read_b128 v[172:175], v154 offset:17408
	ds_read_b128 v[176:179], v154 offset:18432
	ds_read_b128 v[180:183], v154 offset:19456
	ds_read_b128 v[184:187], v154 offset:20480
	ds_read_b128 v[188:191], v154 offset:21504
	ds_read_b128 v[192:195], v154 offset:22528
	ds_read_b128 v[196:199], v154 offset:23552
	global_load_lds_dwordx4 v[220:221], off
	v_lshl_add_u64 v[222:223], s[22:23], 0, v[134:135]
	s_mov_b32 m0, s31
	s_nop 0
	global_load_lds_dwordx4 v[222:223], off
	s_barrier
	s_waitcnt lgkmcnt(0)
	v_mfma_f32_16x16x32_bf16 v[62:65], v[148:151], v[168:171], v[62:65]
	v_mfma_f32_16x16x32_bf16 v[58:61], v[160:163], v[168:171], v[58:61]
	v_mfma_f32_16x16x32_bf16 v[46:49], v[148:151], v[176:179], v[46:49]
	v_mfma_f32_16x16x32_bf16 v[42:45], v[160:163], v[176:179], v[42:45]
	v_mfma_f32_16x16x32_bf16 v[30:33], v[148:151], v[184:187], v[30:33]
	v_mfma_f32_16x16x32_bf16 v[26:29], v[160:163], v[184:187], v[26:29]
	v_mfma_f32_16x16x32_bf16 v[14:17], v[148:151], v[192:195], v[14:17]
	v_mfma_f32_16x16x32_bf16 v[10:13], v[160:163], v[192:195], v[10:13]
	v_mfma_f32_16x16x32_bf16 v[62:65], v[156:159], v[172:175], v[62:65]
	v_mfma_f32_16x16x32_bf16 v[58:61], v[164:167], v[172:175], v[58:61]
	v_mfma_f32_16x16x32_bf16 v[46:49], v[156:159], v[180:183], v[46:49]
	v_mfma_f32_16x16x32_bf16 v[42:45], v[164:167], v[180:183], v[42:45]
	v_mfma_f32_16x16x32_bf16 v[30:33], v[156:159], v[188:191], v[30:33]
	v_mfma_f32_16x16x32_bf16 v[26:29], v[164:167], v[188:191], v[26:29]
	v_mfma_f32_16x16x32_bf16 v[14:17], v[156:159], v[196:199], v[14:17]
	v_mfma_f32_16x16x32_bf16 v[10:13], v[164:167], v[196:199], v[10:13]
	s_barrier
; #define PG8_STAGE(bufoff, gbase, voff) do { _Pragma("unroll") for (int _i = 0; _i < 2; ++_i) \
;     __builtin_amdgcn_global_load_lds((const unsigned*)((const char*)(gbase) + (voff)[_i]), (LAS unsigned*)(lds + (bufoff) + ldsw + _i * 8192), 16, 0, 0); } while (0)
; #define PG8_LDA(dst, b, h) do { _Pragma("unroll") for (int m = 0; m < 4; ++m) _Pragma("unroll") for (int k = 0; k < 2; ++k) dst[m][k] = *(const LAS bf16x8*)(lds + PG8_SA(b, h) + aoff + m * 2048 + k * 1024); } while (0)
; #define PG8_LDB(dst, b, h) do { _Pragma("unroll") for (int n = 0; n < 2; ++n) _Pragma("unroll") for (int k = 0; k < 2; ++k) dst[n][k] = *(const LAS bf16x8*)(lds + PG8_SB(b, h) + boff + n * 2048 + k * 1024); } while (0)
; #define PG8_MMA(ai, bj, At, Bt) do { __builtin_amdgcn_s_setprio(1); _Pragma("unroll") for (int m = 0; m < 4; ++m) _Pragma("unroll") for (int n = 0; n < 2; ++n) _Pragma("unroll") for (int k = 0; k < 2; ++k) \
;     acc[ai][bj][m][n] = __builtin_amdgcn_mfma_f32_16x16x32_bf16(Bt[n][k], At[m][k], acc[ai][bj][m][n], 0, 0, 0); __builtin_amdgcn_s_setprio(0); } while (0)
; #define PG8_WAIT_V(n) asm volatile("s_waitcnt vmcnt(" #n ")" ::: "memory")
; #define PG8_WAIT_L(n) asm volatile("s_waitcnt lgkmcnt(" #n ")" ::: "memory")
; #define PG8_BAR __builtin_amdgcn_s_barrier()
; #define PG8_SCHED __builtin_amdgcn_sched_barrier(0)
; template <class Epi>
; DI void gemm_phase(LAS unsigned char* lds, const Gemm g, const StaticOrder& S, const Epi& E) {
;     ...
;       PG8_LDA(At, 0, 1); PG8_STAGE(PG8_SA(0, 0), a2, voffA);
;       PG8_BAR; PG8_WAIT_L(0); PG8_MMA(1, 0, At, B0); PG8_BAR; PG8_SCHED;
;       PG8_STAGE(PG8_SB(0, 1), b2 + hstepB, voffB);
;       PG8_WAIT_V(6); PG8_BAR; PG8_MMA(1, 1, At, B1); PG8_BAR;
;       PG8_LDB(B0, 1, 0); PG8_SCHED; PG8_LDA(At, 1, 0); PG8_STAGE(PG8_SA(0, 1), a2 + hstepA, voffA);
;       PG8_WAIT_L(8); PG8_BAR; PG8_WAIT_L(0); PG8_MMA(0, 0, At, B0); PG8_BAR; PG8_SCHED;
;       PG8_LDB(B1, 1, 1); PG8_STAGE(PG8_SB(1, 0), b3, voffB);
;       PG8_BAR; PG8_WAIT_L(0); PG8_MMA(0, 1, At, B1); PG8_BAR;
;       PG8_LDA(At, 1, 1); PG8_STAGE(PG8_SA(1, 0), a3, voffA);
;       PG8_BAR; PG8_WAIT_L(0); PG8_MMA(1, 0, At, B0); PG8_BAR; PG8_SCHED;
	s_add_u32 s48, s20, 0x80000
	s_addc_u32 s49, s21, 0
	s_add_i32 s47, s40, s30
	v_lshl_add_u64 v[148:149], s[48:49], 0, v[132:133]
	s_mov_b32 m0, s47
	s_nop 0
	global_load_lds_dwordx4 v[148:149], off
	v_lshl_add_u64 v[148:149], s[48:49], 0, v[136:137]
	s_add_i32 m0, s47, 0x2000
	s_nop 0
	global_load_lds_dwordx4 v[148:149], off
	s_waitcnt vmcnt(6)
	s_barrier
	v_mfma_f32_16x16x32_bf16 v[54:57], v[200:203], v[168:171], v[54:57]
	v_mfma_f32_16x16x32_bf16 v[50:53], v[208:211], v[168:171], v[50:53]
	v_mfma_f32_16x16x32_bf16 v[38:41], v[200:203], v[176:179], v[38:41]
	v_mfma_f32_16x16x32_bf16 v[34:37], v[208:211], v[176:179], v[34:37]
	v_mfma_f32_16x16x32_bf16 v[22:25], v[200:203], v[184:187], v[22:25]
	v_mfma_f32_16x16x32_bf16 v[18:21], v[208:211], v[184:187], v[18:21]
	v_mfma_f32_16x16x32_bf16 v[6:9], v[200:203], v[192:195], v[6:9]
	v_mfma_f32_16x16x32_bf16 v[2:5], v[208:211], v[192:195], v[2:5]
	v_mfma_f32_16x16x32_bf16 v[54:57], v[204:207], v[172:175], v[54:57]
	v_mfma_f32_16x16x32_bf16 v[50:53], v[212:215], v[172:175], v[50:53]
	v_mfma_f32_16x16x32_bf16 v[38:41], v[204:207], v[180:183], v[38:41]
	v_mfma_f32_16x16x32_bf16 v[34:37], v[212:215], v[180:183], v[34:37]
	v_mfma_f32_16x16x32_bf16 v[22:25], v[204:207], v[188:191], v[22:25]
	v_mfma_f32_16x16x32_bf16 v[18:21], v[212:215], v[188:191], v[18:21]
	v_mfma_f32_16x16x32_bf16 v[6:9], v[204:207], v[196:199], v[6:9]
	v_mfma_f32_16x16x32_bf16 v[2:5], v[212:215], v[196:199], v[2:5]
	s_add_i32 s47, 0, 0x18000
	v_add_u32_e32 v164, s47, v152
	s_barrier
	ds_read_b128 v[148:151], v164
	ds_read_b128 v[156:159], v164 offset:1024
	ds_read_b128 v[160:163], v164 offset:2048
	ds_read_b128 v[164:167], v164 offset:3072
	s_add_u32 s22, s22, 0x80000
	s_addc_u32 s23, s23, 0
	s_mov_b32 m0, s33
	v_lshl_add_u64 v[200:201], s[22:23], 0, v[130:131]
	ds_read_b128 v[168:171], v154 offset:32768
	ds_read_b128 v[172:175], v154 offset:33792
	ds_read_b128 v[176:179], v154 offset:34816
	ds_read_b128 v[180:183], v154 offset:35840
	ds_read_b128 v[184:187], v154 offset:36864
	ds_read_b128 v[188:191], v154 offset:37888
	ds_read_b128 v[192:195], v154 offset:38912
	ds_read_b128 v[196:199], v154 offset:39936
	global_load_lds_dwordx4 v[200:201], off
	v_lshl_add_u64 v[200:201], s[22:23], 0, v[134:135]
	s_mov_b32 m0, s34
	s_nop 0
	global_load_lds_dwordx4 v[200:201], off
	s_waitcnt lgkmcnt(8)
	s_barrier
	s_waitcnt lgkmcnt(0)
	v_mfma_f32_16x16x32_bf16 v[126:129], v[148:151], v[168:171], v[126:129]
	v_mfma_f32_16x16x32_bf16 v[122:125], v[160:163], v[168:171], v[122:125]
	v_mfma_f32_16x16x32_bf16 v[110:113], v[148:151], v[176:179], v[110:113]
	v_mfma_f32_16x16x32_bf16 v[106:109], v[160:163], v[176:179], v[106:109]
	v_mfma_f32_16x16x32_bf16 v[94:97], v[148:151], v[184:187], v[94:97]
	v_mfma_f32_16x16x32_bf16 v[90:93], v[160:163], v[184:187], v[90:93]
	v_mfma_f32_16x16x32_bf16 v[78:81], v[148:151], v[192:195], v[78:81]
	v_mfma_f32_16x16x32_bf16 v[74:77], v[160:163], v[192:195], v[74:77]
	v_mfma_f32_16x16x32_bf16 v[126:129], v[156:159], v[172:175], v[126:129]
	v_mfma_f32_16x16x32_bf16 v[122:125], v[164:167], v[172:175], v[122:125]
	v_mfma_f32_16x16x32_bf16 v[110:113], v[156:159], v[180:183], v[110:113]
	v_mfma_f32_16x16x32_bf16 v[106:109], v[164:167], v[180:183], v[106:109]
	v_mfma_f32_16x16x32_bf16 v[94:97], v[156:159], v[188:191], v[94:97]
	v_mfma_f32_16x16x32_bf16 v[90:93], v[164:167], v[188:191], v[90:93]
	v_mfma_f32_16x16x32_bf16 v[78:81], v[156:159], v[196:199], v[78:81]
	v_mfma_f32_16x16x32_bf16 v[74:77], v[164:167], v[196:199], v[74:77]
	s_barrier
	s_add_i32 s22, 0, 0x1c000
	s_add_i32 s23, s47, s30
	v_add_u32_e32 v212, s22, v152
	v_lshl_add_u64 v[216:217], v[216:217], 0, s[2:3]
	s_mov_b32 m0, s23
	ds_read_b128 v[200:203], v212
	ds_read_b128 v[204:207], v212 offset:1024
	ds_read_b128 v[208:211], v212 offset:2048
	ds_read_b128 v[212:215], v212 offset:3072
	global_load_lds_dwordx4 v[216:217], off
	v_lshl_add_u64 v[216:217], v[218:219], 0, s[2:3]
	s_add_i32 m0, s23, 0x2000
	s_nop 0
	global_load_lds_dwordx4 v[216:217], off
	s_barrier
	s_waitcnt lgkmcnt(0)
	v_mfma_f32_16x16x32_bf16 v[118:121], v[200:203], v[168:171], v[118:121]
	v_mfma_f32_16x16x32_bf16 v[114:117], v[208:211], v[168:171], v[114:117]
	v_mfma_f32_16x16x32_bf16 v[102:105], v[200:203], v[176:179], v[102:105]
	v_mfma_f32_16x16x32_bf16 v[98:101], v[208:211], v[176:179], v[98:101]
	v_mfma_f32_16x16x32_bf16 v[86:89], v[200:203], v[184:187], v[86:89]
	v_mfma_f32_16x16x32_bf16 v[82:85], v[208:211], v[184:187], v[82:85]
	v_mfma_f32_16x16x32_bf16 v[70:73], v[200:203], v[192:195], v[70:73]
	v_mfma_f32_16x16x32_bf16 v[66:69], v[208:211], v[192:195], v[66:69]
	v_mfma_f32_16x16x32_bf16 v[118:121], v[204:207], v[172:175], v[118:121]
	v_mfma_f32_16x16x32_bf16 v[114:117], v[212:215], v[172:175], v[114:117]
	v_mfma_f32_16x16x32_bf16 v[102:105], v[204:207], v[180:183], v[102:105]
	v_mfma_f32_16x16x32_bf16 v[98:101], v[212:215], v[180:183], v[98:101]
	v_mfma_f32_16x16x32_bf16 v[86:89], v[204:207], v[188:191], v[86:89]
	v_mfma_f32_16x16x32_bf16 v[82:85], v[212:215], v[188:191], v[82:85]
	v_mfma_f32_16x16x32_bf16 v[70:73], v[204:207], v[196:199], v[70:73]
	v_mfma_f32_16x16x32_bf16 v[66:69], v[212:215], v[196:199], v[66:69]
	s_mov_b32 m0, s36
	v_lshl_add_u64 v[216:217], v[220:221], 0, s[2:3]
	s_barrier
	ds_read_b128 v[168:171], v154 offset:49152
	ds_read_b128 v[172:175], v154 offset:50176
	ds_read_b128 v[176:179], v154 offset:51200
	ds_read_b128 v[180:183], v154 offset:52224
	ds_read_b128 v[184:187], v154 offset:53248
	ds_read_b128 v[188:191], v154 offset:54272
	ds_read_b128 v[192:195], v154 offset:55296
	ds_read_b128 v[196:199], v154 offset:56320
	global_load_lds_dwordx4 v[216:217], off
	v_lshl_add_u64 v[216:217], v[222:223], 0, s[2:3]
	s_mov_b32 m0, s37
	s_nop 0
	global_load_lds_dwordx4 v[216:217], off
	s_barrier
; template <class Epi>
; DI void gemm_phase(LAS unsigned char* lds, const Gemm g, const StaticOrder& S, const Epi& E) {
;     ...
;       PG8_BAR; PG8_WAIT_L(0); PG8_MMA(0, 1, At, B1); PG8_BAR;
;       PG8_LDA(At, 1, 1); PG8_STAGE(PG8_SA(1, 0), a3, voffA);
;       PG8_BAR; PG8_WAIT_L(0); PG8_MMA(1, 0, At, B0); PG8_BAR; PG8_SCHED;
;       PG8_STAGE(PG8_SB(1, 1), b3 + hstepB, voffB);
;       PG8_WAIT_V(6); PG8_BAR; PG8_MMA(1, 1, At, B1); PG8_BAR;
;     }
;     E(acc, cur, wr, wc, fr, fq);
;   DI void operator()(const f32x4 (&acc)[2][2][4][2], const pg8::Unit& u, int wr, int wc, int fr, int fq) const {
;     ...
;           f32x4 v0 = acc[ai][bj][m][0] * rs, v1 = acc[ai][bj][m][1] * rs;
;           if (MODE == EP_IN || MODE == EP_MIX || MODE == EP_DOWN) {
; #pragma unroll
;             for (int j = 0; j < 4; ++j) ssq += v0[j] * v0[j] + v1[j] * v1[j];
;           }
;           if (MODE == EP_UP) {
; #pragma unroll
;             for (int j = 0; j < 4; ++j) { float a = fmaxf(v0[j], 0.f), b = fmaxf(v1[j], 0.f); v0[j] = a * a; v1[j] = b * b; }
;           }
;           bf16_t* dst;
;           const int ct = bj * 128 + cl;
;           if (MODE == EP_IN) {
;             if (pn < 4) dst = (bf16_t*)(ws + OFF_PROJA) + (size_t)grow * 1024 + pn * 256 + ct;
;             else if (pn < 16) dst = (bf16_t*)(ws + OFF_PROJG) + (size_t)grow * 3072 + (pn - 4) * 256 + ct;
;             else dst = (bf16_t*)(ws + OFF_PROJS) + (size_t)grow * 256 + ct;
;           } else if (MODE == EP_Q) {
;             if (pn < 4) dst = (bf16_t*)(dout + DO_Q) + (size_t)grow * 1536 + (pn * 2 + bj) * 192 + cl;
;             else {
;               const int mm = (pn - 4) * 256 + ct, h = mm >> 6, r = mm & 63;
;               dst = (bf16_t*)(dout + DO_Q) + (size_t)grow * 1536 + h * 192 + 128 + r;
;               const int pos = grow < TP ? (grow & 4095) : grow - TP;
;               const f32x4* tb = (const f32x4*)((const f32x2*)(ws + OFF_ROPE) + pos * 32 + (r >> 1));
;               const f32x4 t0 = tb[0], t1 = tb[1];
;               f32x4 o0, o1;
;               o0[0] = v0[0] * t0[0] - v0[1] * t0[1]; o0[1] = v0[1] * t0[0] + v0[0] * t0[1];
;               o0[2] = v0[2] * t0[2] - v0[3] * t0[3]; o0[3] = v0[3] * t0[2] + v0[2] * t0[3];
;               o1[0] = v1[0] * t1[0] - v1[1] * t1[1]; o1[1] = v1[1] * t1[0] + v1[0] * t1[1];
;               o1[2] = v1[2] * t1[2] - v1[3] * t1[3]; o1[3] = v1[3] * t1[2] + v1[2] * t1[3];
	s_waitcnt lgkmcnt(0)
	v_mfma_f32_16x16x32_bf16 v[62:65], v[148:151], v[168:171], v[62:65]
	v_mfma_f32_16x16x32_bf16 v[58:61], v[160:163], v[168:171], v[58:61]
	v_mfma_f32_16x16x32_bf16 v[46:49], v[148:151], v[176:179], v[46:49]
	v_mfma_f32_16x16x32_bf16 v[42:45], v[160:163], v[176:179], v[42:45]
	v_mfma_f32_16x16x32_bf16 v[30:33], v[148:151], v[184:187], v[30:33]
	v_mfma_f32_16x16x32_bf16 v[26:29], v[160:163], v[184:187], v[26:29]
	v_mfma_f32_16x16x32_bf16 v[14:17], v[148:151], v[192:195], v[14:17]
	v_mfma_f32_16x16x32_bf16 v[10:13], v[160:163], v[192:195], v[10:13]
	v_mfma_f32_16x16x32_bf16 v[62:65], v[156:159], v[172:175], v[62:65]
	v_mfma_f32_16x16x32_bf16 v[58:61], v[164:167], v[172:175], v[58:61]
	v_mfma_f32_16x16x32_bf16 v[46:49], v[156:159], v[180:183], v[46:49]
	v_mfma_f32_16x16x32_bf16 v[42:45], v[164:167], v[180:183], v[42:45]
	v_mfma_f32_16x16x32_bf16 v[30:33], v[156:159], v[188:191], v[30:33]
	v_mfma_f32_16x16x32_bf16 v[26:29], v[164:167], v[188:191], v[26:29]
	v_mfma_f32_16x16x32_bf16 v[14:17], v[156:159], v[196:199], v[14:17]
	v_mfma_f32_16x16x32_bf16 v[10:13], v[164:167], v[196:199], v[10:13]
	s_barrier
	s_add_u32 s20, s20, 0x80080
	s_addc_u32 s21, s21, 0
	s_add_i32 s22, s22, s30
	v_lshl_add_u64 v[148:149], s[20:21], 0, v[132:133]
	s_mov_b32 m0, s22
	s_nop 0
	global_load_lds_dwordx4 v[148:149], off
	v_lshl_add_u64 v[148:149], s[20:21], 0, v[136:137]
	s_add_i32 m0, s22, 0x2000
	s_nop 0
	global_load_lds_dwordx4 v[148:149], off
	s_waitcnt vmcnt(6)
	s_barrier
	v_mfma_f32_16x16x32_bf16 v[54:57], v[200:203], v[168:171], v[54:57]
	v_mfma_f32_16x16x32_bf16 v[50:53], v[208:211], v[168:171], v[50:53]
	v_mfma_f32_16x16x32_bf16 v[38:41], v[200:203], v[176:179], v[38:41]
	v_mfma_f32_16x16x32_bf16 v[34:37], v[208:211], v[176:179], v[34:37]
	v_mfma_f32_16x16x32_bf16 v[22:25], v[200:203], v[184:187], v[22:25]
	v_mfma_f32_16x16x32_bf16 v[18:21], v[208:211], v[184:187], v[18:21]
	v_mfma_f32_16x16x32_bf16 v[6:9], v[200:203], v[192:195], v[6:9]
	v_mfma_f32_16x16x32_bf16 v[2:5], v[208:211], v[192:195], v[2:5]
	v_mfma_f32_16x16x32_bf16 v[54:57], v[204:207], v[172:175], v[54:57]
	v_mfma_f32_16x16x32_bf16 v[50:53], v[212:215], v[172:175], v[50:53]
	v_mfma_f32_16x16x32_bf16 v[38:41], v[204:207], v[180:183], v[38:41]
	v_mfma_f32_16x16x32_bf16 v[34:37], v[212:215], v[180:183], v[34:37]
	v_mfma_f32_16x16x32_bf16 v[22:25], v[204:207], v[188:191], v[22:25]
	v_mfma_f32_16x16x32_bf16 v[18:21], v[212:215], v[188:191], v[18:21]
	v_mfma_f32_16x16x32_bf16 v[6:9], v[204:207], v[196:199], v[6:9]
	v_mfma_f32_16x16x32_bf16 v[2:5], v[212:215], v[196:199], v[2:5]
	s_add_i32 s46, s46, 2
	s_add_u32 s18, s18, 0x100
	s_addc_u32 s19, s19, 0
	s_add_u32 s44, s44, 0x100
	s_addc_u32 s45, s45, 0
	s_cmp_gt_u32 s46, 29
	s_barrier
	s_cbranch_scc0 .LBB0_1015
	v_lshl_add_u32 v148, s16, 8, v1
	v_ashrrev_i32_e32 v149, 31, v148
	v_lshl_add_u64 v[150:151], v[148:149], 2, s[4:5]
	v_add_co_u32_e32 v150, vcc, 0x10000, v150
	s_lshl_b32 s18, s41, 8
	s_nop 0
	v_addc_co_u32_e32 v151, vcc, 0, v151, vcc
	s_nop 0
	s_ashr_i32 s19, s18, 31
	v_lshlrev_b64 v[158:159], 14, v[148:149]
	s_lshl_b64 s[18:19], s[18:19], 1
	v_lshl_add_u64 v[158:159], s[6:7], 0, v[158:159]
	v_lshl_add_u64 v[158:159], v[158:159], 0, s[18:19]
	v_lshl_add_u64 v[158:159], v[158:159], 0, v[138:139]
	s_and_b64 vcc, exec, s[0:1]
	s_mov_b32 s41, s8
	s_mov_b32 s16, s10
	s_mov_b64 s[20:21], s[14:15]
	s_mov_b64 s[22:23], s[12:13]
	v_mov_b32_e32 v156, v247
	v_pk_mul_f32 v[128:129], v[128:129], v[156:157] op_sel_hi:[1,0]
	v_pk_mul_f32 v[126:127], v[126:127], v[156:157] op_sel_hi:[1,0]
	v_pk_mul_f32 v[124:125], v[124:125], v[156:157] op_sel_hi:[1,0]
	v_pk_mul_f32 v[122:123], v[122:123], v[156:157] op_sel_hi:[1,0]
	v_pk_mul_f32 v[120:121], v[120:121], v[156:157] op_sel_hi:[1,0]
	v_pk_mul_f32 v[118:119], v[118:119], v[156:157] op_sel_hi:[1,0]
	v_pk_mul_f32 v[116:117], v[116:117], v[156:157] op_sel_hi:[1,0]
	v_pk_mul_f32 v[114:115], v[114:115], v[156:157] op_sel_hi:[1,0]
	v_max_f32_e32 v126, 0, v126
	v_max_f32_e32 v122, 0, v122
	v_max_f32_e32 v127, 0, v127
	v_max_f32_e32 v123, 0, v123
	v_max_f32_e32 v128, 0, v128
	v_max_f32_e32 v124, 0, v124
	v_max_f32_e32 v129, 0, v129
	v_max_f32_e32 v125, 0, v125
	v_max_f32_e32 v118, 0, v118
	v_max_f32_e32 v114, 0, v114
	v_max_f32_e32 v119, 0, v119
	v_max_f32_e32 v115, 0, v115
	v_max_f32_e32 v120, 0, v120
	v_max_f32_e32 v116, 0, v116
	v_max_f32_e32 v121, 0, v121
	v_max_f32_e32 v117, 0, v117
	v_pk_mul_f32 v[126:127], v[126:127], v[126:127]
	v_pk_mul_f32 v[122:123], v[122:123], v[122:123]
	v_pk_mul_f32 v[128:129], v[128:129], v[128:129]
	v_pk_mul_f32 v[124:125], v[124:125], v[124:125]
	v_pk_mul_f32 v[118:119], v[118:119], v[118:119]
	v_pk_mul_f32 v[156:157], v[114:115], v[114:115]
	v_pk_mul_f32 v[120:121], v[120:121], v[120:121]
	v_pk_mul_f32 v[160:161], v[116:117], v[116:117]
	v_cvt_pk_bf16_f32 v114, v126, v127
	v_cvt_pk_bf16_f32 v115, v128, v129
	v_cvt_pk_bf16_f32 v116, v122, v123
	v_cvt_pk_bf16_f32 v117, v124, v125
	v_cvt_pk_bf16_f32 v118, v118, v119
	v_cvt_pk_bf16_f32 v119, v120, v121
	v_cvt_pk_bf16_f32 v120, v156, v157
	v_cvt_pk_bf16_f32 v121, v160, v161
	global_store_dwordx4 v[158:159], v[114:117], off
	global_store_dwordx4 v[158:159], v[118:121], off offset:256
	s_nop 0
	v_or_b32_e32 v116, 16, v148
	v_ashrrev_i32_e32 v117, 31, v116
	v_lshlrev_b64 v[116:117], 14, v[116:117]
	v_lshl_add_u64 v[116:117], s[6:7], 0, v[116:117]
	v_lshl_add_u64 v[116:117], v[116:117], 0, s[18:19]
	v_lshl_add_u64 v[116:117], v[116:117], 0, v[138:139]
	v_mov_b32_e32 v114, v240
	v_pk_mul_f32 v[112:113], v[112:113], v[114:115] op_sel_hi:[1,0]
	v_pk_mul_f32 v[110:111], v[110:111], v[114:115] op_sel_hi:[1,0]
;   DI void operator()(const f32x4 (&acc)[2][2][4][2], const pg8::Unit& u, int wr, int wc, int fr, int fq) const {
;     ...
;           f32x4 v0 = acc[ai][bj][m][0] * rs, v1 = acc[ai][bj][m][1] * rs;
;           if (MODE == EP_IN || MODE == EP_MIX || MODE == EP_DOWN) {
; #pragma unroll
;             for (int j = 0; j < 4; ++j) ssq += v0[j] * v0[j] + v1[j] * v1[j];
;           }
;           if (MODE == EP_UP) {
; #pragma unroll
;             for (int j = 0; j < 4; ++j) { float a = fmaxf(v0[j], 0.f), b = fmaxf(v1[j], 0.f); v0[j] = a * a; v1[j] = b * b; }
;           }
;           bf16_t* dst;
;           const int ct = bj * 128 + cl;
;           if (MODE == EP_IN) {
;             if (pn < 4) dst = (bf16_t*)(ws + OFF_PROJA) + (size_t)grow * 1024 + pn * 256 + ct;
;             else if (pn < 16) dst = (bf16_t*)(ws + OFF_PROJG) + (size_t)grow * 3072 + (pn - 4) * 256 + ct;
;             else dst = (bf16_t*)(ws + OFF_PROJS) + (size_t)grow * 256 + ct;
;           } else if (MODE == EP_Q) {
;             if (pn < 4) dst = (bf16_t*)(dout + DO_Q) + (size_t)grow * 1536 + (pn * 2 + bj) * 192 + cl;
;             else {
;               const int mm = (pn - 4) * 256 + ct, h = mm >> 6, r = mm & 63;
;               dst = (bf16_t*)(dout + DO_Q) + (size_t)grow * 1536 + h * 192 + 128 + r;
;               const int pos = grow < TP ? (grow & 4095) : grow - TP;
;               const f32x4* tb = (const f32x4*)((const f32x2*)(ws + OFF_ROPE) + pos * 32 + (r >> 1));
;               const f32x4 t0 = tb[0], t1 = tb[1];
;               f32x4 o0, o1;
;               o0[0] = v0[0] * t0[0] - v0[1] * t0[1]; o0[1] = v0[1] * t0[0] + v0[0] * t0[1];
;               o0[2] = v0[2] * t0[2] - v0[3] * t0[3]; o0[3] = v0[3] * t0[2] + v0[2] * t0[3];
;               o1[0] = v1[0] * t1[0] - v1[1] * t1[1]; o1[1] = v1[1] * t1[0] + v1[0] * t1[1];
;               o1[2] = v1[2] * t1[2] - v1[3] * t1[3]; o1[3] = v1[3] * t1[2] + v1[2] * t1[3];
;               v0 = o0; v1 = o1;
;             }
;           } else if (MODE == EP_KV) {
;             dst = (bf16_t*)(ws + OFF_XB) + (size_t)grow * 2048 + pn * 256 + ct;
;           } else if (MODE == EP_MIX) {
;             dst = (bf16_t*)(ws + OFF_MIX) + (size_t)grow * 2048 + pn * 256 + ct;
;           } else if (MODE == EP_UP) {
;             dst = (bf16_t*)(ws + OFF_U) + (size_t)row * 8192 + pn * 256 + ct;
;           } else {
	v_pk_mul_f32 v[108:109], v[108:109], v[114:115] op_sel_hi:[1,0]
	v_pk_mul_f32 v[106:107], v[106:107], v[114:115] op_sel_hi:[1,0]
	v_pk_mul_f32 v[104:105], v[104:105], v[114:115] op_sel_hi:[1,0]
	v_pk_mul_f32 v[102:103], v[102:103], v[114:115] op_sel_hi:[1,0]
	v_pk_mul_f32 v[100:101], v[100:101], v[114:115] op_sel_hi:[1,0]
	v_pk_mul_f32 v[98:99], v[98:99], v[114:115] op_sel_hi:[1,0]
	v_max_f32_e32 v110, 0, v110
	v_max_f32_e32 v106, 0, v106
	v_max_f32_e32 v111, 0, v111
	v_max_f32_e32 v107, 0, v107
	v_max_f32_e32 v112, 0, v112
	v_max_f32_e32 v108, 0, v108
	v_max_f32_e32 v113, 0, v113
	v_max_f32_e32 v109, 0, v109
	v_max_f32_e32 v102, 0, v102
	v_max_f32_e32 v98, 0, v98
	v_max_f32_e32 v103, 0, v103
	v_max_f32_e32 v99, 0, v99
	v_max_f32_e32 v104, 0, v104
	v_max_f32_e32 v100, 0, v100
	v_max_f32_e32 v105, 0, v105
	v_max_f32_e32 v101, 0, v101
	v_pk_mul_f32 v[110:111], v[110:111], v[110:111]
	v_pk_mul_f32 v[106:107], v[106:107], v[106:107]
	v_pk_mul_f32 v[112:113], v[112:113], v[112:113]
	v_pk_mul_f32 v[108:109], v[108:109], v[108:109]
	v_pk_mul_f32 v[102:103], v[102:103], v[102:103]
	v_pk_mul_f32 v[114:115], v[98:99], v[98:99]
	v_pk_mul_f32 v[104:105], v[104:105], v[104:105]
	v_pk_mul_f32 v[118:119], v[100:101], v[100:101]
	v_cvt_pk_bf16_f32 v98, v110, v111
	v_cvt_pk_bf16_f32 v99, v112, v113
	v_cvt_pk_bf16_f32 v100, v106, v107
	v_cvt_pk_bf16_f32 v101, v108, v109
	v_cvt_pk_bf16_f32 v102, v102, v103
	v_cvt_pk_bf16_f32 v103, v104, v105
	v_cvt_pk_bf16_f32 v104, v114, v115
	v_cvt_pk_bf16_f32 v105, v118, v119
	global_store_dwordx4 v[116:117], v[98:101], off
	global_store_dwordx4 v[116:117], v[102:105], off offset:256
	s_nop 0
	v_or_b32_e32 v100, 32, v148
	v_ashrrev_i32_e32 v101, 31, v100
	v_lshlrev_b64 v[100:101], 14, v[100:101]
	v_lshl_add_u64 v[100:101], s[6:7], 0, v[100:101]
	v_lshl_add_u64 v[100:101], v[100:101], 0, s[18:19]
	v_lshl_add_u64 v[100:101], v[100:101], 0, v[138:139]
	v_mov_b32_e32 v98, v241
	v_pk_mul_f32 v[96:97], v[96:97], v[98:99] op_sel_hi:[1,0]
	v_pk_mul_f32 v[94:95], v[94:95], v[98:99] op_sel_hi:[1,0]
	v_pk_mul_f32 v[92:93], v[92:93], v[98:99] op_sel_hi:[1,0]
	v_pk_mul_f32 v[90:91], v[90:91], v[98:99] op_sel_hi:[1,0]
	v_pk_mul_f32 v[88:89], v[88:89], v[98:99] op_sel_hi:[1,0]
	v_pk_mul_f32 v[86:87], v[86:87], v[98:99] op_sel_hi:[1,0]
	v_pk_mul_f32 v[84:85], v[84:85], v[98:99] op_sel_hi:[1,0]
	v_pk_mul_f32 v[82:83], v[82:83], v[98:99] op_sel_hi:[1,0]
	v_max_f32_e32 v94, 0, v94
	v_max_f32_e32 v90, 0, v90
	v_max_f32_e32 v95, 0, v95
	v_max_f32_e32 v91, 0, v91
	v_max_f32_e32 v96, 0, v96
	v_max_f32_e32 v92, 0, v92
	v_max_f32_e32 v97, 0, v97
	v_max_f32_e32 v93, 0, v93
	v_max_f32_e32 v86, 0, v86
	v_max_f32_e32 v82, 0, v82
	v_max_f32_e32 v87, 0, v87
	v_max_f32_e32 v83, 0, v83
	v_max_f32_e32 v88, 0, v88
	v_max_f32_e32 v84, 0, v84
	v_max_f32_e32 v89, 0, v89
	v_max_f32_e32 v85, 0, v85
	v_pk_mul_f32 v[94:95], v[94:95], v[94:95]
	v_pk_mul_f32 v[90:91], v[90:91], v[90:91]
	v_pk_mul_f32 v[96:97], v[96:97], v[96:97]
	v_pk_mul_f32 v[92:93], v[92:93], v[92:93]
	v_pk_mul_f32 v[86:87], v[86:87], v[86:87]
	v_pk_mul_f32 v[98:99], v[82:83], v[82:83]
	v_pk_mul_f32 v[88:89], v[88:89], v[88:89]
	v_pk_mul_f32 v[102:103], v[84:85], v[84:85]
	v_cvt_pk_bf16_f32 v82, v94, v95
	v_cvt_pk_bf16_f32 v83, v96, v97
	v_cvt_pk_bf16_f32 v84, v90, v91
	v_cvt_pk_bf16_f32 v85, v92, v93
	v_cvt_pk_bf16_f32 v86, v86, v87
	v_cvt_pk_bf16_f32 v87, v88, v89
	v_cvt_pk_bf16_f32 v88, v98, v99
	v_cvt_pk_bf16_f32 v89, v102, v103
	global_store_dwordx4 v[100:101], v[82:85], off
	global_store_dwordx4 v[100:101], v[86:89], off offset:256
	s_nop 0
	v_or_b32_e32 v84, 48, v148
	v_ashrrev_i32_e32 v85, 31, v84
	v_lshlrev_b64 v[84:85], 14, v[84:85]
	v_lshl_add_u64 v[84:85], s[6:7], 0, v[84:85]
	v_add_u32_e32 v86, 0x4080, v148
	v_lshl_add_u64 v[84:85], v[84:85], 0, s[18:19]
	v_ashrrev_i32_e32 v87, 31, v86
	v_lshl_add_u64 v[84:85], v[84:85], 0, v[138:139]
	v_lshl_add_u64 v[86:87], v[86:87], 2, s[4:5]
	v_mov_b32_e32 v82, v242
	v_pk_mul_f32 v[80:81], v[80:81], v[82:83] op_sel_hi:[1,0]
	v_pk_mul_f32 v[78:79], v[78:79], v[82:83] op_sel_hi:[1,0]
	v_pk_mul_f32 v[76:77], v[76:77], v[82:83] op_sel_hi:[1,0]
	v_pk_mul_f32 v[74:75], v[74:75], v[82:83] op_sel_hi:[1,0]
	v_pk_mul_f32 v[72:73], v[72:73], v[82:83] op_sel_hi:[1,0]
	v_pk_mul_f32 v[70:71], v[70:71], v[82:83] op_sel_hi:[1,0]
	v_pk_mul_f32 v[68:69], v[68:69], v[82:83] op_sel_hi:[1,0]
	v_pk_mul_f32 v[66:67], v[66:67], v[82:83] op_sel_hi:[1,0]
	v_max_f32_e32 v78, 0, v78
	v_max_f32_e32 v74, 0, v74
	v_max_f32_e32 v79, 0, v79
	v_max_f32_e32 v75, 0, v75
	v_max_f32_e32 v80, 0, v80
	v_max_f32_e32 v76, 0, v76
	v_max_f32_e32 v81, 0, v81
	v_max_f32_e32 v77, 0, v77
	v_max_f32_e32 v70, 0, v70
	v_max_f32_e32 v66, 0, v66
	v_max_f32_e32 v71, 0, v71
	v_max_f32_e32 v67, 0, v67
	v_max_f32_e32 v72, 0, v72
	v_max_f32_e32 v68, 0, v68
	v_max_f32_e32 v73, 0, v73
	v_max_f32_e32 v69, 0, v69
	v_pk_mul_f32 v[78:79], v[78:79], v[78:79]
	v_pk_mul_f32 v[74:75], v[74:75], v[74:75]
	v_pk_mul_f32 v[80:81], v[80:81], v[80:81]
	v_pk_mul_f32 v[76:77], v[76:77], v[76:77]
	v_pk_mul_f32 v[70:71], v[70:71], v[70:71]
	v_pk_mul_f32 v[82:83], v[66:67], v[66:67]
	v_pk_mul_f32 v[72:73], v[72:73], v[72:73]
	v_pk_mul_f32 v[88:89], v[68:69], v[68:69]
	v_cvt_pk_bf16_f32 v66, v78, v79
	v_cvt_pk_bf16_f32 v67, v80, v81
	v_cvt_pk_bf16_f32 v68, v74, v75
	v_cvt_pk_bf16_f32 v69, v76, v77
	v_cvt_pk_bf16_f32 v70, v70, v71
	v_cvt_pk_bf16_f32 v71, v72, v73
	v_cvt_pk_bf16_f32 v72, v82, v83
	v_cvt_pk_bf16_f32 v73, v88, v89
	global_store_dwordx4 v[84:85], v[66:69], off
	global_store_dwordx4 v[84:85], v[70:73], off offset:256
	s_nop 0
	v_add_u32_e32 v68, 0x80, v148
	v_ashrrev_i32_e32 v69, 31, v68
;   DI void operator()(const f32x4 (&acc)[2][2][4][2], const pg8::Unit& u, int wr, int wc, int fr, int fq) const {
;     ...
;           f32x4 v0 = acc[ai][bj][m][0] * rs, v1 = acc[ai][bj][m][1] * rs;
;           if (MODE == EP_IN || MODE == EP_MIX || MODE == EP_DOWN) {
; #pragma unroll
;             for (int j = 0; j < 4; ++j) ssq += v0[j] * v0[j] + v1[j] * v1[j];
;           }
;           if (MODE == EP_UP) {
; #pragma unroll
;             for (int j = 0; j < 4; ++j) { float a = fmaxf(v0[j], 0.f), b = fmaxf(v1[j], 0.f); v0[j] = a * a; v1[j] = b * b; }
;           }
;           bf16_t* dst;
;           const int ct = bj * 128 + cl;
;           if (MODE == EP_IN) {
;             if (pn < 4) dst = (bf16_t*)(ws + OFF_PROJA) + (size_t)grow * 1024 + pn * 256 + ct;
;             else if (pn < 16) dst = (bf16_t*)(ws + OFF_PROJG) + (size_t)grow * 3072 + (pn - 4) * 256 + ct;
;             else dst = (bf16_t*)(ws + OFF_PROJS) + (size_t)grow * 256 + ct;
;           } else if (MODE == EP_Q) {
;             if (pn < 4) dst = (bf16_t*)(dout + DO_Q) + (size_t)grow * 1536 + (pn * 2 + bj) * 192 + cl;
;             else {
;               const int mm = (pn - 4) * 256 + ct, h = mm >> 6, r = mm & 63;
;               dst = (bf16_t*)(dout + DO_Q) + (size_t)grow * 1536 + h * 192 + 128 + r;
;               const int pos = grow < TP ? (grow & 4095) : grow - TP;
;               const f32x4* tb = (const f32x4*)((const f32x2*)(ws + OFF_ROPE) + pos * 32 + (r >> 1));
;               const f32x4 t0 = tb[0], t1 = tb[1];
;               f32x4 o0, o1;
;               o0[0] = v0[0] * t0[0] - v0[1] * t0[1]; o0[1] = v0[1] * t0[0] + v0[0] * t0[1];
;               o0[2] = v0[2] * t0[2] - v0[3] * t0[3]; o0[3] = v0[3] * t0[2] + v0[2] * t0[3];
;               o1[0] = v1[0] * t1[0] - v1[1] * t1[1]; o1[1] = v1[1] * t1[0] + v1[0] * t1[1];
;               o1[2] = v1[2] * t1[2] - v1[3] * t1[3]; o1[3] = v1[3] * t1[2] + v1[2] * t1[3];
;               v0 = o0; v1 = o1;
;             }
;           } else if (MODE == EP_KV) {
;             dst = (bf16_t*)(ws + OFF_XB) + (size_t)grow * 2048 + pn * 256 + ct;
;           } else if (MODE == EP_MIX) {
;             dst = (bf16_t*)(ws + OFF_MIX) + (size_t)grow * 2048 + pn * 256 + ct;
;           } else if (MODE == EP_UP) {
;             dst = (bf16_t*)(ws + OFF_U) + (size_t)row * 8192 + pn * 256 + ct;
;           } else {
	v_lshlrev_b64 v[68:69], 14, v[68:69]
	v_lshl_add_u64 v[68:69], s[6:7], 0, v[68:69]
	v_add_u32_e32 v70, 0x4090, v148
	v_lshl_add_u64 v[68:69], v[68:69], 0, s[18:19]
	v_ashrrev_i32_e32 v71, 31, v70
	v_lshl_add_u64 v[68:69], v[68:69], 0, v[138:139]
	v_lshl_add_u64 v[70:71], v[70:71], 2, s[4:5]
	v_mov_b32_e32 v66, v243
	v_pk_mul_f32 v[64:65], v[64:65], v[66:67] op_sel_hi:[1,0]
	v_pk_mul_f32 v[62:63], v[62:63], v[66:67] op_sel_hi:[1,0]
	v_pk_mul_f32 v[60:61], v[60:61], v[66:67] op_sel_hi:[1,0]
	v_pk_mul_f32 v[58:59], v[58:59], v[66:67] op_sel_hi:[1,0]
	v_pk_mul_f32 v[56:57], v[56:57], v[66:67] op_sel_hi:[1,0]
	v_pk_mul_f32 v[54:55], v[54:55], v[66:67] op_sel_hi:[1,0]
	v_pk_mul_f32 v[52:53], v[52:53], v[66:67] op_sel_hi:[1,0]
	v_pk_mul_f32 v[50:51], v[50:51], v[66:67] op_sel_hi:[1,0]
	v_max_f32_e32 v62, 0, v62
	v_max_f32_e32 v58, 0, v58
	v_max_f32_e32 v63, 0, v63
	v_max_f32_e32 v59, 0, v59
	v_max_f32_e32 v64, 0, v64
	v_max_f32_e32 v60, 0, v60
	v_max_f32_e32 v65, 0, v65
	v_max_f32_e32 v61, 0, v61
	v_max_f32_e32 v54, 0, v54
	v_max_f32_e32 v50, 0, v50
	v_max_f32_e32 v55, 0, v55
	v_max_f32_e32 v51, 0, v51
	v_max_f32_e32 v56, 0, v56
	v_max_f32_e32 v52, 0, v52
	v_max_f32_e32 v57, 0, v57
	v_max_f32_e32 v53, 0, v53
	v_pk_mul_f32 v[62:63], v[62:63], v[62:63]
	v_pk_mul_f32 v[58:59], v[58:59], v[58:59]
	v_pk_mul_f32 v[64:65], v[64:65], v[64:65]
	v_pk_mul_f32 v[60:61], v[60:61], v[60:61]
	v_pk_mul_f32 v[54:55], v[54:55], v[54:55]
	v_pk_mul_f32 v[66:67], v[50:51], v[50:51]
	v_pk_mul_f32 v[56:57], v[56:57], v[56:57]
	v_pk_mul_f32 v[72:73], v[52:53], v[52:53]
	v_cvt_pk_bf16_f32 v50, v62, v63
	v_cvt_pk_bf16_f32 v51, v64, v65
	v_cvt_pk_bf16_f32 v52, v58, v59
	v_cvt_pk_bf16_f32 v53, v60, v61
	v_cvt_pk_bf16_f32 v54, v54, v55
	v_cvt_pk_bf16_f32 v55, v56, v57
	v_cvt_pk_bf16_f32 v56, v66, v67
	v_cvt_pk_bf16_f32 v57, v72, v73
	global_store_dwordx4 v[68:69], v[50:53], off
	global_store_dwordx4 v[68:69], v[54:57], off offset:256
	s_nop 0
	v_add_u32_e32 v52, 0x90, v148
	v_ashrrev_i32_e32 v53, 31, v52
	v_lshlrev_b64 v[52:53], 14, v[52:53]
	v_lshl_add_u64 v[52:53], s[6:7], 0, v[52:53]
	v_add_u32_e32 v54, 0x40a0, v148
	v_lshl_add_u64 v[52:53], v[52:53], 0, s[18:19]
	v_ashrrev_i32_e32 v55, 31, v54
	v_lshl_add_u64 v[52:53], v[52:53], 0, v[138:139]
	v_lshl_add_u64 v[54:55], v[54:55], 2, s[4:5]
	v_mov_b32_e32 v50, v244
	v_pk_mul_f32 v[48:49], v[48:49], v[50:51] op_sel_hi:[1,0]
	v_pk_mul_f32 v[46:47], v[46:47], v[50:51] op_sel_hi:[1,0]
	v_pk_mul_f32 v[44:45], v[44:45], v[50:51] op_sel_hi:[1,0]
	v_pk_mul_f32 v[42:43], v[42:43], v[50:51] op_sel_hi:[1,0]
	v_pk_mul_f32 v[40:41], v[40:41], v[50:51] op_sel_hi:[1,0]
	v_pk_mul_f32 v[38:39], v[38:39], v[50:51] op_sel_hi:[1,0]
	v_pk_mul_f32 v[36:37], v[36:37], v[50:51] op_sel_hi:[1,0]
	v_pk_mul_f32 v[34:35], v[34:35], v[50:51] op_sel_hi:[1,0]
	v_max_f32_e32 v46, 0, v46
	v_max_f32_e32 v42, 0, v42
	v_max_f32_e32 v47, 0, v47
	v_max_f32_e32 v43, 0, v43
	v_max_f32_e32 v48, 0, v48
	v_max_f32_e32 v44, 0, v44
	v_max_f32_e32 v49, 0, v49
	v_max_f32_e32 v45, 0, v45
	v_max_f32_e32 v38, 0, v38
	v_max_f32_e32 v34, 0, v34
	v_max_f32_e32 v39, 0, v39
	v_max_f32_e32 v35, 0, v35
	v_max_f32_e32 v40, 0, v40
	v_max_f32_e32 v36, 0, v36
	v_max_f32_e32 v41, 0, v41
	v_max_f32_e32 v37, 0, v37
	v_pk_mul_f32 v[46:47], v[46:47], v[46:47]
	v_pk_mul_f32 v[42:43], v[42:43], v[42:43]
	v_pk_mul_f32 v[48:49], v[48:49], v[48:49]
	v_pk_mul_f32 v[44:45], v[44:45], v[44:45]
	v_pk_mul_f32 v[38:39], v[38:39], v[38:39]
	v_pk_mul_f32 v[50:51], v[34:35], v[34:35]
	v_pk_mul_f32 v[40:41], v[40:41], v[40:41]
	v_pk_mul_f32 v[56:57], v[36:37], v[36:37]
	v_cvt_pk_bf16_f32 v34, v46, v47
	v_cvt_pk_bf16_f32 v35, v48, v49
	v_cvt_pk_bf16_f32 v36, v42, v43
	v_cvt_pk_bf16_f32 v37, v44, v45
	v_cvt_pk_bf16_f32 v38, v38, v39
	v_cvt_pk_bf16_f32 v39, v40, v41
	v_cvt_pk_bf16_f32 v40, v50, v51
	v_cvt_pk_bf16_f32 v41, v56, v57
	global_store_dwordx4 v[52:53], v[34:37], off
	global_store_dwordx4 v[52:53], v[38:41], off offset:256
;   DI void operator()(const f32x4 (&acc)[2][2][4][2], const pg8::Unit& u, int wr, int wc, int fr, int fq) const {
;     ...
;           f32x4 v0 = acc[ai][bj][m][0] * rs, v1 = acc[ai][bj][m][1] * rs;
;           if (MODE == EP_IN || MODE == EP_MIX || MODE == EP_DOWN) {
; #pragma unroll
;             for (int j = 0; j < 4; ++j) ssq += v0[j] * v0[j] + v1[j] * v1[j];
;           }
;           if (MODE == EP_UP) {
; #pragma unroll
;             for (int j = 0; j < 4; ++j) { float a = fmaxf(v0[j], 0.f), b = fmaxf(v1[j], 0.f); v0[j] = a * a; v1[j] = b * b; }
;           }
;           bf16_t* dst;
;           const int ct = bj * 128 + cl;
;           if (MODE == EP_IN) {
;             if (pn < 4) dst = (bf16_t*)(ws + OFF_PROJA) + (size_t)grow * 1024 + pn * 256 + ct;
;             else if (pn < 16) dst = (bf16_t*)(ws + OFF_PROJG) + (size_t)grow * 3072 + (pn - 4) * 256 + ct;
;             else dst = (bf16_t*)(ws + OFF_PROJS) + (size_t)grow * 256 + ct;
;           } else if (MODE == EP_Q) {
;             if (pn < 4) dst = (bf16_t*)(dout + DO_Q) + (size_t)grow * 1536 + (pn * 2 + bj) * 192 + cl;
;             else {
;               const int mm = (pn - 4) * 256 + ct, h = mm >> 6, r = mm & 63;
;               dst = (bf16_t*)(dout + DO_Q) + (size_t)grow * 1536 + h * 192 + 128 + r;
;               const int pos = grow < TP ? (grow & 4095) : grow - TP;
;               const f32x4* tb = (const f32x4*)((const f32x2*)(ws + OFF_ROPE) + pos * 32 + (r >> 1));
;               const f32x4 t0 = tb[0], t1 = tb[1];
;               f32x4 o0, o1;
;               o0[0] = v0[0] * t0[0] - v0[1] * t0[1]; o0[1] = v0[1] * t0[0] + v0[0] * t0[1];
;               o0[2] = v0[2] * t0[2] - v0[3] * t0[3]; o0[3] = v0[3] * t0[2] + v0[2] * t0[3];
;               o1[0] = v1[0] * t1[0] - v1[1] * t1[1]; o1[1] = v1[1] * t1[0] + v1[0] * t1[1];
;               o1[2] = v1[2] * t1[2] - v1[3] * t1[3]; o1[3] = v1[3] * t1[2] + v1[2] * t1[3];
;               v0 = o0; v1 = o1;
;             }
;           } else if (MODE == EP_KV) {
;             dst = (bf16_t*)(ws + OFF_XB) + (size_t)grow * 2048 + pn * 256 + ct;
;           } else if (MODE == EP_MIX) {
;             dst = (bf16_t*)(ws + OFF_MIX) + (size_t)grow * 2048 + pn * 256 + ct;
;           } else if (MODE == EP_UP) {
;             dst = (bf16_t*)(ws + OFF_U) + (size_t)row * 8192 + pn * 256 + ct;
;           } else {
	s_nop 0
	v_add_u32_e32 v36, 0xa0, v148
	v_ashrrev_i32_e32 v37, 31, v36
	v_lshlrev_b64 v[36:37], 14, v[36:37]
	v_lshl_add_u64 v[36:37], s[6:7], 0, v[36:37]
	v_add_u32_e32 v38, 0x40b0, v148
	v_lshl_add_u64 v[36:37], v[36:37], 0, s[18:19]
	v_ashrrev_i32_e32 v39, 31, v38
	v_lshl_add_u64 v[36:37], v[36:37], 0, v[138:139]
	v_lshl_add_u64 v[38:39], v[38:39], 2, s[4:5]
	v_mov_b32_e32 v34, v245
	v_pk_mul_f32 v[32:33], v[32:33], v[34:35] op_sel_hi:[1,0]
	v_pk_mul_f32 v[30:31], v[30:31], v[34:35] op_sel_hi:[1,0]
	v_pk_mul_f32 v[28:29], v[28:29], v[34:35] op_sel_hi:[1,0]
	v_pk_mul_f32 v[26:27], v[26:27], v[34:35] op_sel_hi:[1,0]
	v_pk_mul_f32 v[24:25], v[24:25], v[34:35] op_sel_hi:[1,0]
	v_pk_mul_f32 v[22:23], v[22:23], v[34:35] op_sel_hi:[1,0]
	v_pk_mul_f32 v[20:21], v[20:21], v[34:35] op_sel_hi:[1,0]
	v_pk_mul_f32 v[18:19], v[18:19], v[34:35] op_sel_hi:[1,0]
	v_max_f32_e32 v30, 0, v30
	v_max_f32_e32 v26, 0, v26
	v_max_f32_e32 v31, 0, v31
	v_max_f32_e32 v27, 0, v27
	v_max_f32_e32 v32, 0, v32
	v_max_f32_e32 v28, 0, v28
	v_max_f32_e32 v33, 0, v33
	v_max_f32_e32 v29, 0, v29
	v_max_f32_e32 v22, 0, v22
	v_max_f32_e32 v18, 0, v18
	v_max_f32_e32 v23, 0, v23
	v_max_f32_e32 v19, 0, v19
	v_max_f32_e32 v24, 0, v24
	v_max_f32_e32 v20, 0, v20
	v_max_f32_e32 v25, 0, v25
	v_max_f32_e32 v21, 0, v21
	v_pk_mul_f32 v[30:31], v[30:31], v[30:31]
	v_pk_mul_f32 v[26:27], v[26:27], v[26:27]
	v_pk_mul_f32 v[32:33], v[32:33], v[32:33]
	v_pk_mul_f32 v[28:29], v[28:29], v[28:29]
	v_pk_mul_f32 v[22:23], v[22:23], v[22:23]
	v_pk_mul_f32 v[34:35], v[18:19], v[18:19]
	v_pk_mul_f32 v[24:25], v[24:25], v[24:25]
	v_pk_mul_f32 v[40:41], v[20:21], v[20:21]
	v_cvt_pk_bf16_f32 v18, v30, v31
	v_cvt_pk_bf16_f32 v19, v32, v33
	v_cvt_pk_bf16_f32 v20, v26, v27
	v_cvt_pk_bf16_f32 v21, v28, v29
	v_cvt_pk_bf16_f32 v22, v22, v23
	v_cvt_pk_bf16_f32 v23, v24, v25
	v_cvt_pk_bf16_f32 v24, v34, v35
	v_cvt_pk_bf16_f32 v25, v40, v41
	global_store_dwordx4 v[36:37], v[18:21], off
	global_store_dwordx4 v[36:37], v[22:25], off offset:256
	s_nop 0
	v_add_u32_e32 v20, 0xb0, v148
	v_ashrrev_i32_e32 v21, 31, v20
	v_lshlrev_b64 v[20:21], 14, v[20:21]
	v_lshl_add_u64 v[20:21], s[6:7], 0, v[20:21]
	v_lshl_add_u64 v[20:21], v[20:21], 0, s[18:19]
	v_lshl_add_u64 v[20:21], v[20:21], 0, v[138:139]
	v_mov_b32_e32 v18, v246
	v_pk_mul_f32 v[16:17], v[16:17], v[18:19] op_sel_hi:[1,0]
	v_pk_mul_f32 v[14:15], v[14:15], v[18:19] op_sel_hi:[1,0]
	v_pk_mul_f32 v[12:13], v[12:13], v[18:19] op_sel_hi:[1,0]
	v_pk_mul_f32 v[10:11], v[10:11], v[18:19] op_sel_hi:[1,0]
	v_pk_mul_f32 v[8:9], v[8:9], v[18:19] op_sel_hi:[1,0]
	v_pk_mul_f32 v[6:7], v[6:7], v[18:19] op_sel_hi:[1,0]
	v_pk_mul_f32 v[4:5], v[4:5], v[18:19] op_sel_hi:[1,0]
	v_pk_mul_f32 v[2:3], v[2:3], v[18:19] op_sel_hi:[1,0]
	v_max_f32_e32 v14, 0, v14
	v_max_f32_e32 v10, 0, v10
	v_max_f32_e32 v15, 0, v15
	v_max_f32_e32 v11, 0, v11
	v_max_f32_e32 v16, 0, v16
	v_max_f32_e32 v12, 0, v12
	v_max_f32_e32 v17, 0, v17
	v_max_f32_e32 v13, 0, v13
	v_max_f32_e32 v6, 0, v6
	v_max_f32_e32 v2, 0, v2
	v_max_f32_e32 v7, 0, v7
	v_max_f32_e32 v3, 0, v3
	v_max_f32_e32 v8, 0, v8
	v_max_f32_e32 v4, 0, v4
	v_max_f32_e32 v9, 0, v9
	v_max_f32_e32 v5, 0, v5
	v_pk_mul_f32 v[14:15], v[14:15], v[14:15]
	v_pk_mul_f32 v[10:11], v[10:11], v[10:11]
	v_pk_mul_f32 v[16:17], v[16:17], v[16:17]
	v_pk_mul_f32 v[12:13], v[12:13], v[12:13]
	v_pk_mul_f32 v[6:7], v[6:7], v[6:7]
	v_pk_mul_f32 v[18:19], v[2:3], v[2:3]
	v_pk_mul_f32 v[8:9], v[8:9], v[8:9]
	v_pk_mul_f32 v[22:23], v[4:5], v[4:5]
	v_cvt_pk_bf16_f32 v2, v14, v15
	v_cvt_pk_bf16_f32 v3, v16, v17
	v_cvt_pk_bf16_f32 v4, v10, v11
	v_cvt_pk_bf16_f32 v5, v12, v13
	v_cvt_pk_bf16_f32 v6, v6, v7
	v_cvt_pk_bf16_f32 v7, v8, v9
	v_cvt_pk_bf16_f32 v8, v18, v19
	v_cvt_pk_bf16_f32 v9, v22, v23
	global_store_dwordx4 v[20:21], v[2:5], off
	global_store_dwordx4 v[20:21], v[6:9], off offset:256
	s_cbranch_vccz .LBB0_1008
	s_waitcnt vmcnt(0)
	s_cmpk_gt_u32 s24, 0xff
	s_cbranch_scc1 .LBB0_1019
	s_barrier

; #define PG8_STAGE(bufoff, gbase, voff) do { _Pragma("unroll") for (int _i = 0; _i < 2; ++_i) \
;     __builtin_amdgcn_global_load_lds((const unsigned*)((const char*)(gbase) + (voff)[_i]), (LAS unsigned*)(lds + (bufoff) + ldsw + _i * 8192), 16, 0, 0); } while (0)
; #define PG8_LDA(dst, b, h) do { _Pragma("unroll") for (int m = 0; m < 4; ++m) _Pragma("unroll") for (int k = 0; k < 2; ++k) dst[m][k] = *(const LAS bf16x8*)(lds + PG8_SA(b, h) + aoff + m * 2048 + k * 1024); } while (0)
; #define PG8_LDB(dst, b, h) do { _Pragma("unroll") for (int n = 0; n < 2; ++n) _Pragma("unroll") for (int k = 0; k < 2; ++k) dst[n][k] = *(const LAS bf16x8*)(lds + PG8_SB(b, h) + boff + n * 2048 + k * 1024); } while (0)
; #define PG8_MMA(ai, bj, At, Bt) do { __builtin_amdgcn_s_setprio(1); _Pragma("unroll") for (int m = 0; m < 4; ++m) _Pragma("unroll") for (int n = 0; n < 2; ++n) _Pragma("unroll") for (int k = 0; k < 2; ++k) \
;     acc[ai][bj][m][n] = __builtin_amdgcn_mfma_f32_16x16x32_bf16(Bt[n][k], At[m][k], acc[ai][bj][m][n], 0, 0, 0); __builtin_amdgcn_s_setprio(0); } while (0)
; #define PG8_WAIT_V(n) asm volatile("s_waitcnt vmcnt(" #n ")" ::: "memory")
; #define PG8_WAIT_L(n) asm volatile("s_waitcnt lgkmcnt(" #n ")" ::: "memory")
; #define PG8_BAR __builtin_amdgcn_s_barrier()
; #define PG8_SCHED __builtin_amdgcn_sched_barrier(0)
; template <class Epi>
; DI void gemm_phase(LAS unsigned char* lds, const Gemm g, const StaticOrder& S, const Epi& E) {
;     ...
;     for (int t = 0; t < nt; t += 2) {
;       const bool last = (t == nt - 2);
;       const char* a1 = cA + PG8_AK(t + 1);
;       const char* a2 = last ? nA : cA + PG8_AK(t + 2); const char* b2 = last ? nB : cB + (size_t)(t + 2) * kstep;
;       const char* a3 = a2 + kstep; const char* b3 = b2 + kstep;
;       PG8_LDB(B0, 0, 0); PG8_SCHED; PG8_LDA(At, 0, 0); PG8_STAGE(PG8_SA(1, 1), a1 + hstepA, voffA);
;       PG8_WAIT_L(8); PG8_BAR; PG8_WAIT_L(0); PG8_MMA(0, 0, At, B0); PG8_BAR; PG8_SCHED;
;       PG8_LDB(B1, 0, 1); PG8_STAGE(PG8_SB(0, 0), b2, voffB);
;       PG8_BAR; PG8_WAIT_L(0); PG8_MMA(0, 1, At, B1); PG8_BAR;
;       PG8_LDA(At, 0, 1); PG8_STAGE(PG8_SA(0, 0), a2, voffA);
;       PG8_BAR; PG8_WAIT_L(0); PG8_MMA(1, 0, At, B0); PG8_BAR; PG8_SCHED;
;       PG8_STAGE(PG8_SB(0, 1), b2 + hstepB, voffB);
;       PG8_WAIT_V(6); PG8_BAR; PG8_MMA(1, 1, At, B1); PG8_BAR;
.LBB0_1056:
	ds_read_b128 v[156:159], v151
	ds_read_b128 v[160:163], v151 offset:1024
	ds_read_b128 v[164:167], v151 offset:2048
	ds_read_b128 v[168:171], v151 offset:3072
	s_add_u32 s22, s20, 0xffe00080
	s_addc_u32 s23, s21, -1
	s_cmpk_eq_i32 s48, 0x7c
	s_cselect_b32 s25, s13, s23
	s_cselect_b32 s24, s19, s22
	s_cselect_b32 s23, s11, s47
	s_cselect_b32 s22, s45, s46
	v_lshl_add_u64 v[148:149], s[20:21], 0, v[140:141]
	s_add_i32 m0, s33, 0xc000
	ds_read_b128 v[172:175], v152
	ds_read_b128 v[176:179], v152 offset:1024
	ds_read_b128 v[180:183], v152 offset:2048
	ds_read_b128 v[184:187], v152 offset:3072
	ds_read_b128 v[188:191], v152 offset:4096
	ds_read_b128 v[192:195], v152 offset:5120
	ds_read_b128 v[196:199], v152 offset:6144
	ds_read_b128 v[200:203], v152 offset:7168
	global_load_lds_dwordx4 v[148:149], off
	v_lshl_add_u64 v[148:149], s[20:21], 0, v[142:143]
	s_add_i32 m0, s33, 0xe000
	s_nop 0
	global_load_lds_dwordx4 v[148:149], off
	s_waitcnt lgkmcnt(8)
	s_barrier
	s_waitcnt lgkmcnt(0)
	v_mfma_f32_16x16x32_bf16 v[126:129], v[156:159], v[172:175], v[126:129]
	v_mfma_f32_16x16x32_bf16 v[122:125], v[164:167], v[172:175], v[122:125]
	v_mfma_f32_16x16x32_bf16 v[110:113], v[156:159], v[180:183], v[110:113]
	v_mfma_f32_16x16x32_bf16 v[106:109], v[164:167], v[180:183], v[106:109]
	v_mfma_f32_16x16x32_bf16 v[94:97], v[156:159], v[188:191], v[94:97]
	v_mfma_f32_16x16x32_bf16 v[90:93], v[164:167], v[188:191], v[90:93]
	v_mfma_f32_16x16x32_bf16 v[78:81], v[156:159], v[196:199], v[78:81]
	v_mfma_f32_16x16x32_bf16 v[74:77], v[164:167], v[196:199], v[74:77]
	v_mfma_f32_16x16x32_bf16 v[126:129], v[160:163], v[176:179], v[126:129]
	v_mfma_f32_16x16x32_bf16 v[122:125], v[168:171], v[176:179], v[122:125]
	v_mfma_f32_16x16x32_bf16 v[110:113], v[160:163], v[184:187], v[110:113]
	v_mfma_f32_16x16x32_bf16 v[106:109], v[168:171], v[184:187], v[106:109]
	v_mfma_f32_16x16x32_bf16 v[94:97], v[160:163], v[192:195], v[94:97]
	v_mfma_f32_16x16x32_bf16 v[90:93], v[168:171], v[192:195], v[90:93]
	v_mfma_f32_16x16x32_bf16 v[78:81], v[160:163], v[200:203], v[78:81]
	v_mfma_f32_16x16x32_bf16 v[74:77], v[168:171], v[200:203], v[74:77]
	s_barrier
	s_add_i32 s49, s42, s31
	v_lshl_add_u64 v[148:149], s[22:23], 0, v[132:133]
	s_mov_b32 m0, s49
	ds_read_b128 v[204:207], v153
	ds_read_b128 v[208:211], v153 offset:1024
	ds_read_b128 v[212:215], v153 offset:2048
	ds_read_b128 v[216:219], v153 offset:3072
	global_load_lds_dwordx4 v[148:149], off
	v_lshl_add_u64 v[220:221], s[22:23], 0, v[136:137]
	s_add_i32 m0, s49, 0x2000
	s_nop 0
	global_load_lds_dwordx4 v[220:221], off
	s_barrier
	s_waitcnt lgkmcnt(0)
	v_mfma_f32_16x16x32_bf16 v[118:121], v[204:207], v[172:175], v[118:121]
	v_mfma_f32_16x16x32_bf16 v[114:117], v[212:215], v[172:175], v[114:117]
	v_mfma_f32_16x16x32_bf16 v[102:105], v[204:207], v[180:183], v[102:105]
	v_mfma_f32_16x16x32_bf16 v[98:101], v[212:215], v[180:183], v[98:101]
	v_mfma_f32_16x16x32_bf16 v[86:89], v[204:207], v[188:191], v[86:89]
	v_mfma_f32_16x16x32_bf16 v[82:85], v[212:215], v[188:191], v[82:85]
	v_mfma_f32_16x16x32_bf16 v[70:73], v[204:207], v[196:199], v[70:73]
	v_mfma_f32_16x16x32_bf16 v[66:69], v[212:215], v[196:199], v[66:69]
	v_mfma_f32_16x16x32_bf16 v[118:121], v[208:211], v[176:179], v[118:121]
	v_mfma_f32_16x16x32_bf16 v[114:117], v[216:219], v[176:179], v[114:117]
	v_mfma_f32_16x16x32_bf16 v[102:105], v[208:211], v[184:187], v[102:105]
	v_mfma_f32_16x16x32_bf16 v[98:101], v[216:219], v[184:187], v[98:101]
	v_mfma_f32_16x16x32_bf16 v[86:89], v[208:211], v[192:195], v[86:89]
	v_mfma_f32_16x16x32_bf16 v[82:85], v[216:219], v[192:195], v[82:85]
	v_mfma_f32_16x16x32_bf16 v[70:73], v[208:211], v[200:203], v[70:73]
	v_mfma_f32_16x16x32_bf16 v[66:69], v[216:219], v[200:203], v[66:69]
	s_mov_b32 m0, s33
	v_lshl_add_u64 v[222:223], s[24:25], 0, v[130:131]
	s_barrier
	ds_read_b128 v[172:175], v152 offset:16384
	ds_read_b128 v[176:179], v152 offset:17408
	ds_read_b128 v[180:183], v152 offset:18432
	ds_read_b128 v[184:187], v152 offset:19456
	ds_read_b128 v[188:191], v152 offset:20480
	ds_read_b128 v[192:195], v152 offset:21504
	ds_read_b128 v[196:199], v152 offset:22528
	ds_read_b128 v[200:203], v152 offset:23552
	global_load_lds_dwordx4 v[222:223], off
	v_lshl_add_u64 v[224:225], s[24:25], 0, v[134:135]
	s_mov_b32 m0, s34
	s_nop 0
	global_load_lds_dwordx4 v[224:225], off
	s_barrier
	s_waitcnt lgkmcnt(0)
	v_mfma_f32_16x16x32_bf16 v[62:65], v[156:159], v[172:175], v[62:65]
	v_mfma_f32_16x16x32_bf16 v[58:61], v[164:167], v[172:175], v[58:61]
	v_mfma_f32_16x16x32_bf16 v[46:49], v[156:159], v[180:183], v[46:49]
	v_mfma_f32_16x16x32_bf16 v[42:45], v[164:167], v[180:183], v[42:45]
	v_mfma_f32_16x16x32_bf16 v[30:33], v[156:159], v[188:191], v[30:33]
	v_mfma_f32_16x16x32_bf16 v[26:29], v[164:167], v[188:191], v[26:29]
	v_mfma_f32_16x16x32_bf16 v[14:17], v[156:159], v[196:199], v[14:17]
	v_mfma_f32_16x16x32_bf16 v[10:13], v[164:167], v[196:199], v[10:13]
	v_mfma_f32_16x16x32_bf16 v[62:65], v[160:163], v[176:179], v[62:65]
	v_mfma_f32_16x16x32_bf16 v[58:61], v[168:171], v[176:179], v[58:61]
	v_mfma_f32_16x16x32_bf16 v[46:49], v[160:163], v[184:187], v[46:49]
	v_mfma_f32_16x16x32_bf16 v[42:45], v[168:171], v[184:187], v[42:45]
	v_mfma_f32_16x16x32_bf16 v[30:33], v[160:163], v[192:195], v[30:33]
	v_mfma_f32_16x16x32_bf16 v[26:29], v[168:171], v[192:195], v[26:29]
	v_mfma_f32_16x16x32_bf16 v[14:17], v[160:163], v[200:203], v[14:17]
	v_mfma_f32_16x16x32_bf16 v[10:13], v[168:171], v[200:203], v[10:13]
	s_barrier
; #define PG8_STAGE(bufoff, gbase, voff) do { _Pragma("unroll") for (int _i = 0; _i < 2; ++_i) \
;     __builtin_amdgcn_global_load_lds((const unsigned*)((const char*)(gbase) + (voff)[_i]), (LAS unsigned*)(lds + (bufoff) + ldsw + _i * 8192), 16, 0, 0); } while (0)
; #define PG8_LDA(dst, b, h) do { _Pragma("unroll") for (int m = 0; m < 4; ++m) _Pragma("unroll") for (int k = 0; k < 2; ++k) dst[m][k] = *(const LAS bf16x8*)(lds + PG8_SA(b, h) + aoff + m * 2048 + k * 1024); } while (0)
; #define PG8_LDB(dst, b, h) do { _Pragma("unroll") for (int n = 0; n < 2; ++n) _Pragma("unroll") for (int k = 0; k < 2; ++k) dst[n][k] = *(const LAS bf16x8*)(lds + PG8_SB(b, h) + boff + n * 2048 + k * 1024); } while (0)
; #define PG8_MMA(ai, bj, At, Bt) do { __builtin_amdgcn_s_setprio(1); _Pragma("unroll") for (int m = 0; m < 4; ++m) _Pragma("unroll") for (int n = 0; n < 2; ++n) _Pragma("unroll") for (int k = 0; k < 2; ++k) \
;     acc[ai][bj][m][n] = __builtin_amdgcn_mfma_f32_16x16x32_bf16(Bt[n][k], At[m][k], acc[ai][bj][m][n], 0, 0, 0); __builtin_amdgcn_s_setprio(0); } while (0)
; #define PG8_WAIT_V(n) asm volatile("s_waitcnt vmcnt(" #n ")" ::: "memory")
; #define PG8_WAIT_L(n) asm volatile("s_waitcnt lgkmcnt(" #n ")" ::: "memory")
; #define PG8_BAR __builtin_amdgcn_s_barrier()
; #define PG8_SCHED __builtin_amdgcn_sched_barrier(0)
; template <class Epi>
; DI void gemm_phase(LAS unsigned char* lds, const Gemm g, const StaticOrder& S, const Epi& E) {
;     ...
;       PG8_LDA(At, 0, 1); PG8_STAGE(PG8_SA(0, 0), a2, voffA);
;       PG8_BAR; PG8_WAIT_L(0); PG8_MMA(1, 0, At, B0); PG8_BAR; PG8_SCHED;
;       PG8_STAGE(PG8_SB(0, 1), b2 + hstepB, voffB);
;       PG8_WAIT_V(6); PG8_BAR; PG8_MMA(1, 1, At, B1); PG8_BAR;
;       PG8_LDB(B0, 1, 0); PG8_SCHED; PG8_LDA(At, 1, 0); PG8_STAGE(PG8_SA(0, 1), a2 + hstepA, voffA);
;       PG8_WAIT_L(8); PG8_BAR; PG8_WAIT_L(0); PG8_MMA(0, 0, At, B0); PG8_BAR; PG8_SCHED;
;       PG8_LDB(B1, 1, 1); PG8_STAGE(PG8_SB(1, 0), b3, voffB);
;       PG8_BAR; PG8_WAIT_L(0); PG8_MMA(0, 1, At, B1); PG8_BAR;
;       PG8_LDA(At, 1, 1); PG8_STAGE(PG8_SA(1, 0), a3, voffA);
;       PG8_BAR; PG8_WAIT_L(0); PG8_MMA(1, 0, At, B0); PG8_BAR; PG8_SCHED;
	s_add_u32 s50, s22, 0x200000
	s_addc_u32 s51, s23, 0
	s_add_i32 s49, s43, s31
	v_lshl_add_u64 v[156:157], s[50:51], 0, v[132:133]
	s_mov_b32 m0, s49
	s_nop 0
	global_load_lds_dwordx4 v[156:157], off
	v_lshl_add_u64 v[156:157], s[50:51], 0, v[136:137]
	s_add_i32 m0, s49, 0x2000
	s_nop 0
	global_load_lds_dwordx4 v[156:157], off
	s_waitcnt vmcnt(6)
	s_barrier
	v_mfma_f32_16x16x32_bf16 v[54:57], v[204:207], v[172:175], v[54:57]
	v_mfma_f32_16x16x32_bf16 v[50:53], v[212:215], v[172:175], v[50:53]
	v_mfma_f32_16x16x32_bf16 v[38:41], v[204:207], v[180:183], v[38:41]
	v_mfma_f32_16x16x32_bf16 v[34:37], v[212:215], v[180:183], v[34:37]
	v_mfma_f32_16x16x32_bf16 v[22:25], v[204:207], v[188:191], v[22:25]
	v_mfma_f32_16x16x32_bf16 v[18:21], v[212:215], v[188:191], v[18:21]
	v_mfma_f32_16x16x32_bf16 v[6:9], v[204:207], v[196:199], v[6:9]
	v_mfma_f32_16x16x32_bf16 v[2:5], v[212:215], v[196:199], v[2:5]
	v_mfma_f32_16x16x32_bf16 v[54:57], v[208:211], v[176:179], v[54:57]
	v_mfma_f32_16x16x32_bf16 v[50:53], v[216:219], v[176:179], v[50:53]
	v_mfma_f32_16x16x32_bf16 v[38:41], v[208:211], v[184:187], v[38:41]
	v_mfma_f32_16x16x32_bf16 v[34:37], v[216:219], v[184:187], v[34:37]
	v_mfma_f32_16x16x32_bf16 v[22:25], v[208:211], v[192:195], v[22:25]
	v_mfma_f32_16x16x32_bf16 v[18:21], v[216:219], v[192:195], v[18:21]
	v_mfma_f32_16x16x32_bf16 v[6:9], v[208:211], v[200:203], v[6:9]
	v_mfma_f32_16x16x32_bf16 v[2:5], v[216:219], v[200:203], v[2:5]
	s_add_i32 s49, 0, 0x18000
	v_add_u32_e32 v155, s49, v150
	s_barrier
	ds_read_b128 v[156:159], v155
	ds_read_b128 v[160:163], v155 offset:1024
	ds_read_b128 v[164:167], v155 offset:2048
	ds_read_b128 v[168:171], v155 offset:3072
	s_add_u32 s24, s24, 0x200000
	s_addc_u32 s25, s25, 0
	s_mov_b32 m0, s35
	v_lshl_add_u64 v[204:205], s[24:25], 0, v[130:131]
	ds_read_b128 v[172:175], v152 offset:32768
	ds_read_b128 v[176:179], v152 offset:33792
	ds_read_b128 v[180:183], v152 offset:34816
	ds_read_b128 v[184:187], v152 offset:35840
	ds_read_b128 v[188:191], v152 offset:36864
	ds_read_b128 v[192:195], v152 offset:37888
	ds_read_b128 v[196:199], v152 offset:38912
	ds_read_b128 v[200:203], v152 offset:39936
	global_load_lds_dwordx4 v[204:205], off
	v_lshl_add_u64 v[204:205], s[24:25], 0, v[134:135]
	s_mov_b32 m0, s36
	s_nop 0
	global_load_lds_dwordx4 v[204:205], off
	s_waitcnt lgkmcnt(8)
	s_barrier
	s_waitcnt lgkmcnt(0)
	v_mfma_f32_16x16x32_bf16 v[126:129], v[156:159], v[172:175], v[126:129]
	v_mfma_f32_16x16x32_bf16 v[122:125], v[164:167], v[172:175], v[122:125]
	v_mfma_f32_16x16x32_bf16 v[110:113], v[156:159], v[180:183], v[110:113]
	v_mfma_f32_16x16x32_bf16 v[106:109], v[164:167], v[180:183], v[106:109]
	v_mfma_f32_16x16x32_bf16 v[94:97], v[156:159], v[188:191], v[94:97]
	v_mfma_f32_16x16x32_bf16 v[90:93], v[164:167], v[188:191], v[90:93]
	v_mfma_f32_16x16x32_bf16 v[78:81], v[156:159], v[196:199], v[78:81]
	v_mfma_f32_16x16x32_bf16 v[74:77], v[164:167], v[196:199], v[74:77]
	v_mfma_f32_16x16x32_bf16 v[126:129], v[160:163], v[176:179], v[126:129]
	v_mfma_f32_16x16x32_bf16 v[122:125], v[168:171], v[176:179], v[122:125]
	v_mfma_f32_16x16x32_bf16 v[110:113], v[160:163], v[184:187], v[110:113]
	v_mfma_f32_16x16x32_bf16 v[106:109], v[168:171], v[184:187], v[106:109]
	v_mfma_f32_16x16x32_bf16 v[94:97], v[160:163], v[192:195], v[94:97]
	v_mfma_f32_16x16x32_bf16 v[90:93], v[168:171], v[192:195], v[90:93]
	v_mfma_f32_16x16x32_bf16 v[78:81], v[160:163], v[200:203], v[78:81]
	v_mfma_f32_16x16x32_bf16 v[74:77], v[168:171], v[200:203], v[74:77]
	s_barrier
	s_add_i32 s24, 0, 0x1c000
	s_add_i32 s25, s49, s31
	v_add_u32_e32 v155, s24, v150
	v_lshl_add_u64 v[148:149], v[148:149], 0, s[6:7]
	s_mov_b32 m0, s25
	ds_read_b128 v[204:207], v155
	ds_read_b128 v[208:211], v155 offset:1024
	ds_read_b128 v[212:215], v155 offset:2048
	ds_read_b128 v[216:219], v155 offset:3072
	global_load_lds_dwordx4 v[148:149], off
	v_lshl_add_u64 v[148:149], v[220:221], 0, s[6:7]
	s_add_i32 m0, s25, 0x2000
	s_nop 0
	global_load_lds_dwordx4 v[148:149], off
	s_barrier
	s_waitcnt lgkmcnt(0)
	v_mfma_f32_16x16x32_bf16 v[118:121], v[204:207], v[172:175], v[118:121]
	v_mfma_f32_16x16x32_bf16 v[114:117], v[212:215], v[172:175], v[114:117]
	v_mfma_f32_16x16x32_bf16 v[102:105], v[204:207], v[180:183], v[102:105]
	v_mfma_f32_16x16x32_bf16 v[98:101], v[212:215], v[180:183], v[98:101]
	v_mfma_f32_16x16x32_bf16 v[86:89], v[204:207], v[188:191], v[86:89]
	v_mfma_f32_16x16x32_bf16 v[82:85], v[212:215], v[188:191], v[82:85]
	v_mfma_f32_16x16x32_bf16 v[70:73], v[204:207], v[196:199], v[70:73]
	v_mfma_f32_16x16x32_bf16 v[66:69], v[212:215], v[196:199], v[66:69]
	v_mfma_f32_16x16x32_bf16 v[118:121], v[208:211], v[176:179], v[118:121]
	v_mfma_f32_16x16x32_bf16 v[114:117], v[216:219], v[176:179], v[114:117]
	v_mfma_f32_16x16x32_bf16 v[102:105], v[208:211], v[184:187], v[102:105]
	v_mfma_f32_16x16x32_bf16 v[98:101], v[216:219], v[184:187], v[98:101]
	v_mfma_f32_16x16x32_bf16 v[86:89], v[208:211], v[192:195], v[86:89]
	v_mfma_f32_16x16x32_bf16 v[82:85], v[216:219], v[192:195], v[82:85]
	v_mfma_f32_16x16x32_bf16 v[70:73], v[208:211], v[200:203], v[70:73]
	v_mfma_f32_16x16x32_bf16 v[66:69], v[216:219], v[200:203], v[66:69]
	s_mov_b32 m0, s38
	v_lshl_add_u64 v[148:149], v[222:223], 0, s[6:7]
	s_barrier
	ds_read_b128 v[172:175], v152 offset:49152
	ds_read_b128 v[176:179], v152 offset:50176
	ds_read_b128 v[180:183], v152 offset:51200
	ds_read_b128 v[184:187], v152 offset:52224
	ds_read_b128 v[188:191], v152 offset:53248
	ds_read_b128 v[192:195], v152 offset:54272
	ds_read_b128 v[196:199], v152 offset:55296
	ds_read_b128 v[200:203], v152 offset:56320
	global_load_lds_dwordx4 v[148:149], off
	v_lshl_add_u64 v[148:149], v[224:225], 0, s[6:7]
	s_mov_b32 m0, s39
	s_nop 0
	global_load_lds_dwordx4 v[148:149], off
	s_barrier
; template <class Epi>
; DI void gemm_phase(LAS unsigned char* lds, const Gemm g, const StaticOrder& S, const Epi& E) {
;     ...
;       PG8_BAR; PG8_WAIT_L(0); PG8_MMA(0, 1, At, B1); PG8_BAR;
;       PG8_LDA(At, 1, 1); PG8_STAGE(PG8_SA(1, 0), a3, voffA);
;       PG8_BAR; PG8_WAIT_L(0); PG8_MMA(1, 0, At, B0); PG8_BAR; PG8_SCHED;
;       PG8_STAGE(PG8_SB(1, 1), b3 + hstepB, voffB);
;       PG8_WAIT_V(6); PG8_BAR; PG8_MMA(1, 1, At, B1); PG8_BAR;
;     }
;     E(acc, cur, wr, wc, fr, fq);
;   DI void operator()(const f32x4 (&acc)[2][2][4][2], const pg8::Unit& u, int wr, int wc, int fr, int fq) const {
;     ...
;         float ssq = 0.f;
; #pragma unroll
;         for (int bj = 0; bj < 2; ++bj) {
;           f32x4 v0 = acc[ai][bj][m][0] * rs, v1 = acc[ai][bj][m][1] * rs;
;           if (MODE == EP_IN || MODE == EP_MIX || MODE == EP_DOWN) {
; #pragma unroll
;             for (int j = 0; j < 4; ++j) ssq += v0[j] * v0[j] + v1[j] * v1[j];
;           }
;           if (MODE == EP_UP) {
; #pragma unroll
;             for (int j = 0; j < 4; ++j) { float a = fmaxf(v0[j], 0.f), b = fmaxf(v1[j], 0.f); v0[j] = a * a; v1[j] = b * b; }
;           }
;           bf16_t* dst;
;           const int ct = bj * 128 + cl;
;           if (MODE == EP_IN) {
;             if (pn < 4) dst = (bf16_t*)(ws + OFF_PROJA) + (size_t)grow * 1024 + pn * 256 + ct;
;             else if (pn < 16) dst = (bf16_t*)(ws + OFF_PROJG) + (size_t)grow * 3072 + (pn - 4) * 256 + ct;
;             else dst = (bf16_t*)(ws + OFF_PROJS) + (size_t)grow * 256 + ct;
;           } else if (MODE == EP_Q) {
;             if (pn < 4) dst = (bf16_t*)(dout + DO_Q) + (size_t)grow * 1536 + (pn * 2 + bj) * 192 + cl;
;             else {
;               const int mm = (pn - 4) * 256 + ct, h = mm >> 6, r = mm & 63;
;               dst = (bf16_t*)(dout + DO_Q) + (size_t)grow * 1536 + h * 192 + 128 + r;
;               const int pos = grow < TP ? (grow & 4095) : grow - TP;
;               const f32x4* tb = (const f32x4*)((const f32x2*)(ws + OFF_ROPE) + pos * 32 + (r >> 1));
;               const f32x4 t0 = tb[0], t1 = tb[1];
;               f32x4 o0, o1;
;               o0[0] = v0[0] * t0[0] - v0[1] * t0[1]; o0[1] = v0[1] * t0[0] + v0[0] * t0[1];
;               o0[2] = v0[2] * t0[2] - v0[3] * t0[3]; o0[3] = v0[3] * t0[2] + v0[2] * t0[3];
;               o1[0] = v1[0] * t1[0] - v1[1] * t1[1]; o1[1] = v1[1] * t1[0] + v1[0] * t1[1];
	s_waitcnt lgkmcnt(0)
	v_mfma_f32_16x16x32_bf16 v[62:65], v[156:159], v[172:175], v[62:65]
	v_mfma_f32_16x16x32_bf16 v[58:61], v[164:167], v[172:175], v[58:61]
	v_mfma_f32_16x16x32_bf16 v[46:49], v[156:159], v[180:183], v[46:49]
	v_mfma_f32_16x16x32_bf16 v[42:45], v[164:167], v[180:183], v[42:45]
	v_mfma_f32_16x16x32_bf16 v[30:33], v[156:159], v[188:191], v[30:33]
	v_mfma_f32_16x16x32_bf16 v[26:29], v[164:167], v[188:191], v[26:29]
	v_mfma_f32_16x16x32_bf16 v[14:17], v[156:159], v[196:199], v[14:17]
	v_mfma_f32_16x16x32_bf16 v[10:13], v[164:167], v[196:199], v[10:13]
	v_mfma_f32_16x16x32_bf16 v[62:65], v[160:163], v[176:179], v[62:65]
	v_mfma_f32_16x16x32_bf16 v[58:61], v[168:171], v[176:179], v[58:61]
	v_mfma_f32_16x16x32_bf16 v[46:49], v[160:163], v[184:187], v[46:49]
	v_mfma_f32_16x16x32_bf16 v[42:45], v[168:171], v[184:187], v[42:45]
	v_mfma_f32_16x16x32_bf16 v[30:33], v[160:163], v[192:195], v[30:33]
	v_mfma_f32_16x16x32_bf16 v[26:29], v[168:171], v[192:195], v[26:29]
	v_mfma_f32_16x16x32_bf16 v[14:17], v[160:163], v[200:203], v[14:17]
	v_mfma_f32_16x16x32_bf16 v[10:13], v[168:171], v[200:203], v[10:13]
	s_barrier
	s_add_u32 s22, s22, 0x200080
	s_addc_u32 s23, s23, 0
	s_add_i32 s24, s24, s31
	v_lshl_add_u64 v[148:149], s[22:23], 0, v[132:133]
	s_mov_b32 m0, s24
	s_nop 0
	global_load_lds_dwordx4 v[148:149], off
	v_lshl_add_u64 v[148:149], s[22:23], 0, v[136:137]
	s_add_i32 m0, s24, 0x2000
	s_nop 0
	global_load_lds_dwordx4 v[148:149], off
	s_waitcnt vmcnt(6)
	s_barrier
	v_mfma_f32_16x16x32_bf16 v[54:57], v[204:207], v[172:175], v[54:57]
	v_mfma_f32_16x16x32_bf16 v[50:53], v[212:215], v[172:175], v[50:53]
	v_mfma_f32_16x16x32_bf16 v[38:41], v[204:207], v[180:183], v[38:41]
	v_mfma_f32_16x16x32_bf16 v[34:37], v[212:215], v[180:183], v[34:37]
	v_mfma_f32_16x16x32_bf16 v[22:25], v[204:207], v[188:191], v[22:25]
	v_mfma_f32_16x16x32_bf16 v[18:21], v[212:215], v[188:191], v[18:21]
	v_mfma_f32_16x16x32_bf16 v[6:9], v[204:207], v[196:199], v[6:9]
	v_mfma_f32_16x16x32_bf16 v[2:5], v[212:215], v[196:199], v[2:5]
	v_mfma_f32_16x16x32_bf16 v[54:57], v[208:211], v[176:179], v[54:57]
	v_mfma_f32_16x16x32_bf16 v[50:53], v[216:219], v[176:179], v[50:53]
	v_mfma_f32_16x16x32_bf16 v[38:41], v[208:211], v[184:187], v[38:41]
	v_mfma_f32_16x16x32_bf16 v[34:37], v[216:219], v[184:187], v[34:37]
	v_mfma_f32_16x16x32_bf16 v[22:25], v[208:211], v[192:195], v[22:25]
	v_mfma_f32_16x16x32_bf16 v[18:21], v[216:219], v[192:195], v[18:21]
	v_mfma_f32_16x16x32_bf16 v[6:9], v[208:211], v[200:203], v[6:9]
	v_mfma_f32_16x16x32_bf16 v[2:5], v[216:219], v[200:203], v[2:5]
	s_add_i32 s48, s48, 2
	s_add_u32 s20, s20, 0x100
	s_addc_u32 s21, s21, 0
	s_add_u32 s46, s46, 0x100
	s_addc_u32 s47, s47, 0
	s_cmpk_gt_u32 s48, 0x7d
	s_barrier
	s_cbranch_scc0 .LBB0_1056
	v_mul_f32_e32 v160, v122, v122
	v_mul_f32_e32 v161, v123, v123
	v_fmac_f32_e32 v160, v126, v126
	v_fmac_f32_e32 v161, v127, v127
	v_add_f32_e32 v160, v160, v161
	v_mul_f32_e32 v161, v124, v124
	v_fmac_f32_e32 v161, v128, v128
	v_add_f32_e32 v160, v161, v160
	v_mul_f32_e32 v161, v125, v125
	v_fmac_f32_e32 v161, v129, v129
	v_cvt_pk_bf16_f32 v126, v126, v127
	v_cvt_pk_bf16_f32 v127, v128, v129
	v_mul_f32_e32 v128, v114, v114
	v_add_f32_e32 v160, v161, v160
	v_fmac_f32_e32 v128, v118, v118
	v_mul_f32_e32 v129, v115, v115
	v_add_f32_e32 v128, v160, v128
	v_fmac_f32_e32 v129, v119, v119
	v_and_b32_e32 v149, 64, v154
	v_add_f32_e32 v128, v129, v128
	v_mul_f32_e32 v129, v116, v116
	v_xor_b32_e32 v148, 16, v154
	v_add_u32_e32 v149, 64, v149
	v_fmac_f32_e32 v129, v120, v120
	v_cmp_lt_i32_e32 vcc, v148, v149
	v_add_f32_e32 v128, v129, v128
	v_mul_f32_e32 v129, v117, v117
	v_cndmask_b32_e32 v148, v154, v148, vcc
	v_fmac_f32_e32 v129, v121, v121
	v_lshlrev_b32_e32 v156, 2, v148
	v_add_f32_e32 v160, v129, v128
	ds_bpermute_b32 v161, v156, v160
	v_xor_b32_e32 v148, 32, v154
	v_cmp_lt_i32_e32 vcc, v148, v149
	v_lshl_add_u32 v157, s18, 8, v1
	v_cvt_pk_bf16_f32 v128, v122, v123
	v_cndmask_b32_e32 v148, v154, v148, vcc
	v_lshlrev_b32_e32 v155, 2, v148
	v_add_u32_e32 v148, 0x4000, v157
	v_cvt_pk_bf16_f32 v122, v118, v119
	s_waitcnt lgkmcnt(0)
	v_add_f32_e32 v118, v160, v161
	v_ashrrev_i32_e32 v149, 31, v148
	v_readlane_b32 s48, v238, 32
	ds_bpermute_b32 v119, v155, v118
	s_lshl_b32 s20, s4, 8
	v_lshlrev_b64 v[158:159], 13, v[148:149]
	v_readlane_b32 s54, v238, 38
	v_readlane_b32 s55, v238, 39
	s_ashr_i32 s21, s20, 31
	s_lshl_b32 s18, s4, 2
	v_lshl_add_u64 v[158:159], s[54:55], 0, v[158:159]
	v_lshl_add_u64 v[158:159], s[20:21], 1, v[158:159]
	s_ashr_i32 s19, s18, 31
	v_lshl_add_u64 v[158:159], v[158:159], 0, v[138:139]
	v_cvt_pk_bf16_f32 v129, v124, v125
	v_cvt_pk_bf16_f32 v123, v120, v121
	v_cvt_pk_bf16_f32 v124, v114, v115
	v_cvt_pk_bf16_f32 v125, v116, v117
	v_readlane_b32 s49, v238, 33
	v_readlane_b32 s50, v238, 34
	v_readlane_b32 s51, v238, 35
	v_readlane_b32 s52, v238, 36
	v_readlane_b32 s53, v238, 37
	global_store_dwordx4 v[158:159], v[126:129], off
	global_store_dwordx4 v[158:159], v[122:125], off offset:256
	s_and_saveexec_b64 s[22:23], s[0:1]
	s_cbranch_execz .LBB0_1059
	v_lshlrev_b64 v[114:115], 7, v[148:149]
	v_lshl_add_u64 v[114:115], s[8:9], 0, v[114:115]
	v_lshl_add_u64 v[114:115], s[18:19], 2, v[114:115]
	s_lshl_b32 s4, s37, 2
	s_waitcnt lgkmcnt(0)
	v_add_f32_e32 v116, v118, v119
	v_lshl_add_u64 v[114:115], v[114:115], 0, s[4:5]
	global_store_dword v[114:115], v116, off
